# o54: o50 + loop-edge edit: K-loop back-edge SALU (counter/pointer update, compare) hoisted above the trip-end barrier into the MFMA shadow, 8 GEMM loops
# speedup vs baseline: 1.0102x; 1.0075x over previous
;     __device__ float mid(int row) const { return rg(row) / ra(row); }
; #define PG8_STAGE(bufoff, gbase, voff) do { const char* gb_ = (const char*)(gbase); asm volatile("" : "+s"(gb_));     \
;         _Pragma("unroll") for (int _i = 0; _i < 2; ++_i) \
;         __builtin_amdgcn_global_load_lds((const unsigned*)(gb_ + (voff)[_i]), (PG8_LAS unsigned*)(lds + (bufoff) + ldsw + _i * 8192), 16, 0, 0); } while (0)
; #define PG8_BAR __builtin_amdgcn_s_barrier()
; template <class Epi, class Sched, bool ALIGN_EPI = false, bool SP2 = false>
; __device__ __forceinline__ void gemm_phase(PG8_LAS unsigned char* lds, const Gemm g, const Sched& S, const Epi& E, int wid0) {
;     ...
;         for (int t = 0; t < nt; t += 2) {
;             const bool last = (t == nt - 2);
;             const char* a1 = cA + (size_t)(t + 1) * kstep;
;             const char* a2 = last ? nA : cA + (size_t)(t + 2) * kstep; const char* b2 = last ? nB : cB + (size_t)(t + 2) * kstep;
;             const char* a3 = a2 + kstep; const char* b3 = b2 + kstep;
;             if (last && has_next) S.a_ready(nxt);
;             if constexpr (Epi::HAS_MID) { if (t == Epi::MID_T) E.mid(acc, cur, wr, fr); }
;             unsigned vA_[2] = {voffA[0], voffA[1]}, vB_[2] = {voffB[0], voffB[1]};
;             asm volatile("" : "+v"(vA_[0]), "+v"(vA_[1]), "+v"(vB_[0]), "+v"(vB_[1]));
;             if constexpr (SP2) {
;             PG8_LDB(B0, 0, 0); PG8_LDB(B1, 0, 1); PG8_SCHED; PG8_LDA(At, 0, 0); PG8_STAGE(PG8_SA(1, 1), a1 + hstepA, vA_);
;             PG8_WAIT_V(8); PG8_WAIT_L(0); PG8_BAR; PG8_MMA(0, 0, At, B0); PG8_MMA(0, 1, At, B1); PG8_BAR; PG8_SCHED;
;             PG8_LDA(At, 0, 1); PG8_STAGE(PG8_SB(0, 0), b2, vB_); PG8_STAGE(PG8_SB(0, 1), b2 + hstep, vB_); PG8_STAGE(PG8_SA(0, 0), a2, vA_);
;             PG8_WAIT_V(8); PG8_WAIT_L(0); PG8_BAR; PG8_MMA(1, 0, At, B0); PG8_MMA(1, 1, At, B1); PG8_BAR; PG8_SCHED;
;             PG8_LDB(B0, 1, 0); PG8_LDB(B1, 1, 1); PG8_SCHED; PG8_LDA(At, 1, 0); PG8_STAGE(PG8_SA(0, 1), a2 + hstepA, vA_);
;             PG8_WAIT_V(8); PG8_WAIT_L(0); PG8_BAR; PG8_MMA(0, 0, At, B0); PG8_MMA(0, 1, At, B1); PG8_BAR; PG8_SCHED;
;             PG8_LDA(At, 1, 1); PG8_STAGE(PG8_SB(1, 0), b3, vB_); PG8_STAGE(PG8_SB(1, 1), b3 + hstep, vB_); PG8_STAGE(PG8_SA(1, 0), a3, vA_);
;             PG8_WAIT_V(8); PG8_WAIT_L(0); PG8_BAR; PG8_MMA(1, 0, At, B0); PG8_MMA(1, 1, At, B1); PG8_BAR; PG8_SCHED;
.LBB13_358:
	v_mov_b32_e32 v8, v174
	v_mov_b32_e32 v220, v200
	v_mov_b32_e32 v221, v176
	v_mov_b32_e32 v222, v178
	ds_read_b128 v[82:85], v201
	ds_read_b128 v[90:93], v201 offset:1024
	ds_read_b128 v[94:97], v201 offset:2048
	ds_read_b128 v[102:105], v201 offset:3072
	ds_read_b128 v[158:161], v202
	ds_read_b128 v[162:165], v202 offset:1024
	ds_read_b128 v[166:169], v202 offset:2048
	ds_read_b128 v[170:173], v202 offset:3072
	s_add_u32 s8, s2, 0x100
	s_addc_u32 s9, s3, 0
	s_cmp_eq_u32 s82, 12
	s_cselect_b32 s58, s78, s8
	s_cselect_b32 s59, s47, s9
	s_cselect_b32 s12, s79, s80
	s_cselect_b32 s13, s49, s81
	s_add_u32 s10, s58, 0x80
	s_addc_u32 s11, s59, 0
	s_add_u32 s2, s2, 0x40080
	s_addc_u32 s3, s3, 0
	s_add_i32 m0, s57, 0xc000
	ds_read_b128 v[180:183], v203
	ds_read_b128 v[184:187], v203 offset:1024
	ds_read_b128 v[188:191], v203 offset:2048
	ds_read_b128 v[192:195], v203 offset:3072
	ds_read_b128 v[204:207], v203 offset:4096
	ds_read_b128 v[208:211], v203 offset:5120
	ds_read_b128 v[212:215], v203 offset:6144
	ds_read_b128 v[216:219], v203 offset:7168
	s_nop 0
	global_load_lds_dwordx4 v8, s[2:3]
	s_add_i32 m0, s57, 0xe000
	s_nop 0
	global_load_lds_dwordx4 v221, s[2:3]
	s_waitcnt vmcnt(8)
	s_waitcnt lgkmcnt(0)
	s_barrier
	s_setprio 1
	s_waitcnt lgkmcnt(0)
	v_mfma_f32_16x16x32_bf16 v[154:157], v[82:85], v[180:183], v[154:157]
	v_mfma_f32_16x16x32_bf16 v[150:153], v[94:97], v[180:183], v[150:153]
	v_mfma_f32_16x16x32_bf16 v[138:141], v[82:85], v[188:191], v[138:141]
	v_mfma_f32_16x16x32_bf16 v[134:137], v[94:97], v[188:191], v[134:137]
	v_mfma_f32_16x16x32_bf16 v[122:125], v[82:85], v[204:207], v[122:125]
	v_mfma_f32_16x16x32_bf16 v[118:121], v[94:97], v[204:207], v[118:121]
	v_mfma_f32_16x16x32_bf16 v[106:109], v[82:85], v[212:215], v[106:109]
	v_mfma_f32_16x16x32_bf16 v[98:101], v[94:97], v[212:215], v[98:101]
	v_mfma_f32_16x16x32_bf16 v[154:157], v[90:93], v[184:187], v[154:157]
	v_mfma_f32_16x16x32_bf16 v[150:153], v[102:105], v[184:187], v[150:153]
	v_mfma_f32_16x16x32_bf16 v[138:141], v[90:93], v[192:195], v[138:141]
	v_mfma_f32_16x16x32_bf16 v[134:137], v[102:105], v[192:195], v[134:137]
	v_mfma_f32_16x16x32_bf16 v[122:125], v[90:93], v[208:211], v[122:125]
	v_mfma_f32_16x16x32_bf16 v[118:121], v[102:105], v[208:211], v[118:121]
	v_mfma_f32_16x16x32_bf16 v[106:109], v[90:93], v[216:219], v[106:109]
	v_mfma_f32_16x16x32_bf16 v[98:101], v[102:105], v[216:219], v[98:101]
	s_setprio 0
	s_setprio 1
	v_mfma_f32_16x16x32_bf16 v[146:149], v[158:161], v[180:183], v[146:149]
	v_mfma_f32_16x16x32_bf16 v[142:145], v[166:169], v[180:183], v[142:145]
	v_mfma_f32_16x16x32_bf16 v[130:133], v[158:161], v[188:191], v[130:133]
	v_mfma_f32_16x16x32_bf16 v[126:129], v[166:169], v[188:191], v[126:129]
	v_mfma_f32_16x16x32_bf16 v[114:117], v[158:161], v[204:207], v[114:117]
	v_mfma_f32_16x16x32_bf16 v[110:113], v[166:169], v[204:207], v[110:113]
	v_mfma_f32_16x16x32_bf16 v[86:89], v[158:161], v[212:215], v[86:89]
	v_mfma_f32_16x16x32_bf16 v[78:81], v[166:169], v[212:215], v[78:81]
	v_mfma_f32_16x16x32_bf16 v[146:149], v[162:165], v[184:187], v[146:149]
	v_mfma_f32_16x16x32_bf16 v[142:145], v[170:173], v[184:187], v[142:145]
	v_mfma_f32_16x16x32_bf16 v[130:133], v[162:165], v[192:195], v[130:133]
	v_mfma_f32_16x16x32_bf16 v[126:129], v[170:173], v[192:195], v[126:129]
	v_mfma_f32_16x16x32_bf16 v[114:117], v[162:165], v[208:211], v[114:117]
	v_mfma_f32_16x16x32_bf16 v[110:113], v[170:173], v[208:211], v[110:113]
	v_mfma_f32_16x16x32_bf16 v[86:89], v[162:165], v[216:219], v[86:89]
	v_mfma_f32_16x16x32_bf16 v[78:81], v[170:173], v[216:219], v[78:81]
	s_setprio 0
	s_barrier
	s_add_i32 s83, s74, s55
	s_mov_b64 s[2:3], s[12:13]
	s_mov_b32 m0, s83
	ds_read_b128 v[180:183], v203 offset:16384
	ds_read_b128 v[184:187], v203 offset:17408
	ds_read_b128 v[188:191], v203 offset:18432
	ds_read_b128 v[192:195], v203 offset:19456
	ds_read_b128 v[204:207], v203 offset:20480
	ds_read_b128 v[208:211], v203 offset:21504
	ds_read_b128 v[212:215], v203 offset:22528
	ds_read_b128 v[216:219], v203 offset:23552
	s_nop 0
	global_load_lds_dwordx4 v220, s[2:3]
	s_add_i32 m0, s83, 0x2000
	s_nop 0
	global_load_lds_dwordx4 v222, s[2:3]
	s_add_u32 s2, s12, 0x40000
	s_addc_u32 s3, s13, 0
	s_add_i32 s83, s75, s55
	s_mov_b32 m0, s83
	s_nop 0
	global_load_lds_dwordx4 v220, s[2:3]
	s_add_i32 m0, s83, 0x2000
	s_nop 0
	global_load_lds_dwordx4 v222, s[2:3]
	s_mov_b64 s[2:3], s[58:59]
	s_mov_b32 m0, s57
	s_nop 0
	global_load_lds_dwordx4 v8, s[2:3]
	s_mov_b32 m0, s63
	s_nop 0
	global_load_lds_dwordx4 v221, s[2:3]
	s_waitcnt vmcnt(8)
	s_waitcnt lgkmcnt(0)
	s_barrier
; #define PG8_STAGE(bufoff, gbase, voff) do { const char* gb_ = (const char*)(gbase); asm volatile("" : "+s"(gb_));     \
;         _Pragma("unroll") for (int _i = 0; _i < 2; ++_i) \
;         __builtin_amdgcn_global_load_lds((const unsigned*)(gb_ + (voff)[_i]), (PG8_LAS unsigned*)(lds + (bufoff) + ldsw + _i * 8192), 16, 0, 0); } while (0)
; #define PG8_LDA(dst, b, h) do { _Pragma("unroll") for (int m = 0; m < 4; ++m) _Pragma("unroll") for (int k = 0; k < 2; ++k) dst[m][k] = *(const PG8_LAS bf16x8*)(lds + PG8_SA(b, h) + aoff + m * 2048 + k * 1024); } while (0)
; #define PG8_LDB(dst, b, h) do { _Pragma("unroll") for (int n = 0; n < 2; ++n) _Pragma("unroll") for (int k = 0; k < 2; ++k) dst[n][k] = *(const PG8_LAS bf16x8*)(lds + PG8_SB(b, h) + boff + n * 2048 + k * 1024); } while (0)
; #define PG8_MMA(ai, bj, At, Bt) do { __builtin_amdgcn_s_setprio(1); _Pragma("unroll") for (int m = 0; m < 4; ++m) _Pragma("unroll") for (int n = 0; n < 2; ++n) _Pragma("unroll") for (int k = 0; k < 2; ++k) \
;         acc[ai][bj][m][n] = __builtin_amdgcn_mfma_f32_16x16x32_bf16(Bt[n][k], At[m][k], acc[ai][bj][m][n], 0, 0, 0); __builtin_amdgcn_s_setprio(0); } while (0)
; #define PG8_WAIT_V(n) asm volatile("s_waitcnt vmcnt(" #n ")" ::: "memory")
; #define PG8_WAIT_L(n) asm volatile("s_waitcnt lgkmcnt(" #n ")" ::: "memory")
; #define PG8_BAR __builtin_amdgcn_s_barrier()
; #define PG8_SCHED __builtin_amdgcn_sched_barrier(0)
; template <class Epi, class Sched, bool ALIGN_EPI = false, bool SP2 = false>
; __device__ __forceinline__ void gemm_phase(PG8_LAS unsigned char* lds, const Gemm g, const Sched& S, const Epi& E, int wid0) {
;     ...
;             PG8_WAIT_V(8); PG8_WAIT_L(0); PG8_BAR; PG8_MMA(0, 0, At, B0); PG8_MMA(0, 1, At, B1); PG8_BAR; PG8_SCHED;
;             PG8_LDA(At, 0, 1); PG8_STAGE(PG8_SB(0, 0), b2, vB_); PG8_STAGE(PG8_SB(0, 1), b2 + hstep, vB_); PG8_STAGE(PG8_SA(0, 0), a2, vA_);
;             PG8_WAIT_V(8); PG8_WAIT_L(0); PG8_BAR; PG8_MMA(1, 0, At, B0); PG8_MMA(1, 1, At, B1); PG8_BAR; PG8_SCHED;
;             PG8_LDB(B0, 1, 0); PG8_LDB(B1, 1, 1); PG8_SCHED; PG8_LDA(At, 1, 0); PG8_STAGE(PG8_SA(0, 1), a2 + hstepA, vA_);
;             PG8_WAIT_V(8); PG8_WAIT_L(0); PG8_BAR; PG8_MMA(0, 0, At, B0); PG8_MMA(0, 1, At, B1); PG8_BAR; PG8_SCHED;
	s_setprio 1
	s_waitcnt lgkmcnt(0)
	v_mfma_f32_16x16x32_bf16 v[74:77], v[82:85], v[180:183], v[74:77]
	v_mfma_f32_16x16x32_bf16 v[70:73], v[94:97], v[180:183], v[70:73]
	v_mfma_f32_16x16x32_bf16 v[58:61], v[82:85], v[188:191], v[58:61]
	v_mfma_f32_16x16x32_bf16 v[54:57], v[94:97], v[188:191], v[54:57]
	v_mfma_f32_16x16x32_bf16 v[42:45], v[82:85], v[204:207], v[42:45]
	v_mfma_f32_16x16x32_bf16 v[38:41], v[94:97], v[204:207], v[38:41]
	v_mfma_f32_16x16x32_bf16 v[26:29], v[82:85], v[212:215], v[26:29]
	v_mfma_f32_16x16x32_bf16 v[22:25], v[94:97], v[212:215], v[22:25]
	v_mfma_f32_16x16x32_bf16 v[74:77], v[90:93], v[184:187], v[74:77]
	v_mfma_f32_16x16x32_bf16 v[70:73], v[102:105], v[184:187], v[70:73]
	v_mfma_f32_16x16x32_bf16 v[58:61], v[90:93], v[192:195], v[58:61]
	v_mfma_f32_16x16x32_bf16 v[54:57], v[102:105], v[192:195], v[54:57]
	v_mfma_f32_16x16x32_bf16 v[42:45], v[90:93], v[208:211], v[42:45]
	v_mfma_f32_16x16x32_bf16 v[38:41], v[102:105], v[208:211], v[38:41]
	v_mfma_f32_16x16x32_bf16 v[26:29], v[90:93], v[216:219], v[26:29]
	v_mfma_f32_16x16x32_bf16 v[22:25], v[102:105], v[216:219], v[22:25]
	s_setprio 0
	s_setprio 1
	v_mfma_f32_16x16x32_bf16 v[66:69], v[158:161], v[180:183], v[66:69]
	v_mfma_f32_16x16x32_bf16 v[62:65], v[166:169], v[180:183], v[62:65]
	v_mfma_f32_16x16x32_bf16 v[50:53], v[158:161], v[188:191], v[50:53]
	v_mfma_f32_16x16x32_bf16 v[46:49], v[166:169], v[188:191], v[46:49]
	v_mfma_f32_16x16x32_bf16 v[34:37], v[158:161], v[204:207], v[34:37]
	v_mfma_f32_16x16x32_bf16 v[30:33], v[166:169], v[204:207], v[30:33]
	v_mfma_f32_16x16x32_bf16 v[18:21], v[158:161], v[212:215], v[18:21]
	v_mfma_f32_16x16x32_bf16 v[14:17], v[166:169], v[212:215], v[14:17]
	v_mfma_f32_16x16x32_bf16 v[66:69], v[162:165], v[184:187], v[66:69]
	v_mfma_f32_16x16x32_bf16 v[62:65], v[170:173], v[184:187], v[62:65]
	v_mfma_f32_16x16x32_bf16 v[50:53], v[162:165], v[192:195], v[50:53]
	v_mfma_f32_16x16x32_bf16 v[46:49], v[170:173], v[192:195], v[46:49]
	v_mfma_f32_16x16x32_bf16 v[34:37], v[162:165], v[208:211], v[34:37]
	v_mfma_f32_16x16x32_bf16 v[30:33], v[170:173], v[208:211], v[30:33]
	v_mfma_f32_16x16x32_bf16 v[18:21], v[162:165], v[216:219], v[18:21]
	v_mfma_f32_16x16x32_bf16 v[14:17], v[170:173], v[216:219], v[14:17]
	s_setprio 0
	s_barrier
	s_add_i32 s83, 0, 0x18000
	s_add_i32 s84, 0, 0x1c000
	v_add_u32_e32 v102, s83, v175
	v_add_u32_e32 v170, s84, v175
	ds_read_b128 v[82:85], v102
	ds_read_b128 v[90:93], v102 offset:1024
	ds_read_b128 v[94:97], v102 offset:2048
	ds_read_b128 v[102:105], v102 offset:3072
	ds_read_b128 v[158:161], v170
	ds_read_b128 v[162:165], v170 offset:1024
	ds_read_b128 v[166:169], v170 offset:2048
	ds_read_b128 v[170:173], v170 offset:3072
	s_add_u32 s2, s58, 0x40000
	s_addc_u32 s3, s59, 0
	s_mov_b32 m0, s64
	ds_read_b128 v[180:183], v203 offset:32768
	ds_read_b128 v[184:187], v203 offset:33792
	ds_read_b128 v[188:191], v203 offset:34816
	ds_read_b128 v[192:195], v203 offset:35840
	ds_read_b128 v[204:207], v203 offset:36864
	ds_read_b128 v[208:211], v203 offset:37888
	ds_read_b128 v[212:215], v203 offset:38912
	ds_read_b128 v[216:219], v203 offset:39936
	s_nop 0
	global_load_lds_dwordx4 v8, s[2:3]
	s_mov_b32 m0, s65
	s_nop 0
	global_load_lds_dwordx4 v221, s[2:3]
	s_waitcnt vmcnt(8)
	s_waitcnt lgkmcnt(0)
	s_barrier
	s_setprio 1
	s_waitcnt lgkmcnt(0)
	v_mfma_f32_16x16x32_bf16 v[154:157], v[82:85], v[180:183], v[154:157]
	v_mfma_f32_16x16x32_bf16 v[150:153], v[94:97], v[180:183], v[150:153]
	v_mfma_f32_16x16x32_bf16 v[138:141], v[82:85], v[188:191], v[138:141]
	v_mfma_f32_16x16x32_bf16 v[134:137], v[94:97], v[188:191], v[134:137]
	v_mfma_f32_16x16x32_bf16 v[122:125], v[82:85], v[204:207], v[122:125]
	v_mfma_f32_16x16x32_bf16 v[118:121], v[94:97], v[204:207], v[118:121]
	v_mfma_f32_16x16x32_bf16 v[106:109], v[82:85], v[212:215], v[106:109]
	v_mfma_f32_16x16x32_bf16 v[98:101], v[94:97], v[212:215], v[98:101]
	v_mfma_f32_16x16x32_bf16 v[154:157], v[90:93], v[184:187], v[154:157]
	v_mfma_f32_16x16x32_bf16 v[150:153], v[102:105], v[184:187], v[150:153]
	v_mfma_f32_16x16x32_bf16 v[138:141], v[90:93], v[192:195], v[138:141]
	v_mfma_f32_16x16x32_bf16 v[134:137], v[102:105], v[192:195], v[134:137]
	v_mfma_f32_16x16x32_bf16 v[122:125], v[90:93], v[208:211], v[122:125]
	v_mfma_f32_16x16x32_bf16 v[118:121], v[102:105], v[208:211], v[118:121]
	v_mfma_f32_16x16x32_bf16 v[106:109], v[90:93], v[216:219], v[106:109]
	v_mfma_f32_16x16x32_bf16 v[98:101], v[102:105], v[216:219], v[98:101]
	s_setprio 0
	s_setprio 1
	v_mfma_f32_16x16x32_bf16 v[146:149], v[158:161], v[180:183], v[146:149]
	v_mfma_f32_16x16x32_bf16 v[142:145], v[166:169], v[180:183], v[142:145]
	v_mfma_f32_16x16x32_bf16 v[130:133], v[158:161], v[188:191], v[130:133]
	v_mfma_f32_16x16x32_bf16 v[126:129], v[166:169], v[188:191], v[126:129]
	v_mfma_f32_16x16x32_bf16 v[114:117], v[158:161], v[204:207], v[114:117]
	v_mfma_f32_16x16x32_bf16 v[110:113], v[166:169], v[204:207], v[110:113]
	v_mfma_f32_16x16x32_bf16 v[86:89], v[158:161], v[212:215], v[86:89]
	v_mfma_f32_16x16x32_bf16 v[78:81], v[166:169], v[212:215], v[78:81]
	v_mfma_f32_16x16x32_bf16 v[146:149], v[162:165], v[184:187], v[146:149]
	v_mfma_f32_16x16x32_bf16 v[142:145], v[170:173], v[184:187], v[142:145]
	v_mfma_f32_16x16x32_bf16 v[130:133], v[162:165], v[192:195], v[130:133]
	v_mfma_f32_16x16x32_bf16 v[126:129], v[170:173], v[192:195], v[126:129]
	v_mfma_f32_16x16x32_bf16 v[114:117], v[162:165], v[208:211], v[114:117]
	v_mfma_f32_16x16x32_bf16 v[110:113], v[170:173], v[208:211], v[110:113]
	v_mfma_f32_16x16x32_bf16 v[86:89], v[162:165], v[216:219], v[86:89]
	v_mfma_f32_16x16x32_bf16 v[78:81], v[170:173], v[216:219], v[78:81]
	s_setprio 0
	s_barrier
;     __device__ float mid(int row) const { return rg(row) / ra(row); }
; #define PG8_STAGE(bufoff, gbase, voff) do { const char* gb_ = (const char*)(gbase); asm volatile("" : "+s"(gb_));     \
;         _Pragma("unroll") for (int _i = 0; _i < 2; ++_i) \
;         __builtin_amdgcn_global_load_lds((const unsigned*)(gb_ + (voff)[_i]), (PG8_LAS unsigned*)(lds + (bufoff) + ldsw + _i * 8192), 16, 0, 0); } while (0)
; #define PG8_BAR __builtin_amdgcn_s_barrier()
; template <class Epi, class Sched, bool ALIGN_EPI = false, bool SP2 = false>
; __device__ __forceinline__ void gemm_phase(PG8_LAS unsigned char* lds, const Gemm g, const Sched& S, const Epi& E, int wid0) {
;     ...
;         for (int t = 0; t < nt; t += 2) {
;             const bool last = (t == nt - 2);
;             const char* a1 = cA + (size_t)(t + 1) * kstep;
;             const char* a2 = last ? nA : cA + (size_t)(t + 2) * kstep; const char* b2 = last ? nB : cB + (size_t)(t + 2) * kstep;
;             const char* a3 = a2 + kstep; const char* b3 = b2 + kstep;
;             if (last && has_next) S.a_ready(nxt);
;             if constexpr (Epi::HAS_MID) { if (t == Epi::MID_T) E.mid(acc, cur, wr, fr); }
;             unsigned vA_[2] = {voffA[0], voffA[1]}, vB_[2] = {voffB[0], voffB[1]};
;             asm volatile("" : "+v"(vA_[0]), "+v"(vA_[1]), "+v"(vB_[0]), "+v"(vB_[1]));
;             if constexpr (SP2) {
;             PG8_LDB(B0, 0, 0); PG8_LDB(B1, 0, 1); PG8_SCHED; PG8_LDA(At, 0, 0); PG8_STAGE(PG8_SA(1, 1), a1 + hstepA, vA_);
;             PG8_WAIT_V(8); PG8_WAIT_L(0); PG8_BAR; PG8_MMA(0, 0, At, B0); PG8_MMA(0, 1, At, B1); PG8_BAR; PG8_SCHED;
;             PG8_LDA(At, 0, 1); PG8_STAGE(PG8_SB(0, 0), b2, vB_); PG8_STAGE(PG8_SB(0, 1), b2 + hstep, vB_); PG8_STAGE(PG8_SA(0, 0), a2, vA_);
;             PG8_WAIT_V(8); PG8_WAIT_L(0); PG8_BAR; PG8_MMA(1, 0, At, B0); PG8_MMA(1, 1, At, B1); PG8_BAR; PG8_SCHED;
;             PG8_LDB(B0, 1, 0); PG8_LDB(B1, 1, 1); PG8_SCHED; PG8_LDA(At, 1, 0); PG8_STAGE(PG8_SA(0, 1), a2 + hstepA, vA_);
;             PG8_WAIT_V(8); PG8_WAIT_L(0); PG8_BAR; PG8_MMA(0, 0, At, B0); PG8_MMA(0, 1, At, B1); PG8_BAR; PG8_SCHED;
;             PG8_LDA(At, 1, 1); PG8_STAGE(PG8_SB(1, 0), b3, vB_); PG8_STAGE(PG8_SB(1, 1), b3 + hstep, vB_); PG8_STAGE(PG8_SA(1, 0), a3, vA_);
;             PG8_WAIT_V(8); PG8_WAIT_L(0); PG8_BAR; PG8_MMA(1, 0, At, B0); PG8_MMA(1, 1, At, B1); PG8_BAR; PG8_SCHED;
	s_add_u32 s2, s12, 0x80
	s_addc_u32 s3, s13, 0
	s_add_i32 s58, s83, s55
	s_mov_b32 m0, s58
	ds_read_b128 v[180:183], v203 offset:49152
	ds_read_b128 v[184:187], v203 offset:50176
	ds_read_b128 v[188:191], v203 offset:51200
	ds_read_b128 v[192:195], v203 offset:52224
	ds_read_b128 v[204:207], v203 offset:53248
	ds_read_b128 v[208:211], v203 offset:54272
	ds_read_b128 v[212:215], v203 offset:55296
	ds_read_b128 v[216:219], v203 offset:56320
	s_nop 0
	global_load_lds_dwordx4 v220, s[2:3]
	s_add_i32 m0, s58, 0x2000
	s_nop 0
	global_load_lds_dwordx4 v222, s[2:3]
	s_add_u32 s2, s12, 0x40080
	s_addc_u32 s3, s13, 0
	s_add_i32 s12, s84, s55
	s_mov_b32 m0, s12
	s_nop 0
	global_load_lds_dwordx4 v220, s[2:3]
	s_add_i32 m0, s12, 0x2000
	s_nop 0
	global_load_lds_dwordx4 v222, s[2:3]
	s_mov_b32 m0, s68
	s_nop 0
	global_load_lds_dwordx4 v8, s[10:11]
	s_mov_b32 m0, s69
	s_nop 0
	global_load_lds_dwordx4 v221, s[10:11]
	s_waitcnt vmcnt(8)
	s_waitcnt lgkmcnt(0)
	s_barrier
	s_setprio 1
	s_waitcnt lgkmcnt(0)
	v_mfma_f32_16x16x32_bf16 v[74:77], v[82:85], v[180:183], v[74:77]
	v_mfma_f32_16x16x32_bf16 v[70:73], v[94:97], v[180:183], v[70:73]
	v_mfma_f32_16x16x32_bf16 v[58:61], v[82:85], v[188:191], v[58:61]
	v_mfma_f32_16x16x32_bf16 v[54:57], v[94:97], v[188:191], v[54:57]
	v_mfma_f32_16x16x32_bf16 v[42:45], v[82:85], v[204:207], v[42:45]
	v_mfma_f32_16x16x32_bf16 v[38:41], v[94:97], v[204:207], v[38:41]
	v_mfma_f32_16x16x32_bf16 v[26:29], v[82:85], v[212:215], v[26:29]
	v_mfma_f32_16x16x32_bf16 v[22:25], v[94:97], v[212:215], v[22:25]
	v_mfma_f32_16x16x32_bf16 v[74:77], v[90:93], v[184:187], v[74:77]
	v_mfma_f32_16x16x32_bf16 v[70:73], v[102:105], v[184:187], v[70:73]
	v_mfma_f32_16x16x32_bf16 v[58:61], v[90:93], v[192:195], v[58:61]
	v_mfma_f32_16x16x32_bf16 v[54:57], v[102:105], v[192:195], v[54:57]
	v_mfma_f32_16x16x32_bf16 v[42:45], v[90:93], v[208:211], v[42:45]
	v_mfma_f32_16x16x32_bf16 v[38:41], v[102:105], v[208:211], v[38:41]
	v_mfma_f32_16x16x32_bf16 v[26:29], v[90:93], v[216:219], v[26:29]
	v_mfma_f32_16x16x32_bf16 v[22:25], v[102:105], v[216:219], v[22:25]
	s_setprio 0
	s_setprio 1
	v_mfma_f32_16x16x32_bf16 v[66:69], v[158:161], v[180:183], v[66:69]
	v_mfma_f32_16x16x32_bf16 v[62:65], v[166:169], v[180:183], v[62:65]
	v_mfma_f32_16x16x32_bf16 v[50:53], v[158:161], v[188:191], v[50:53]
	v_mfma_f32_16x16x32_bf16 v[46:49], v[166:169], v[188:191], v[46:49]
	v_mfma_f32_16x16x32_bf16 v[34:37], v[158:161], v[204:207], v[34:37]
	v_mfma_f32_16x16x32_bf16 v[30:33], v[166:169], v[204:207], v[30:33]
	v_mfma_f32_16x16x32_bf16 v[18:21], v[158:161], v[212:215], v[18:21]
	v_mfma_f32_16x16x32_bf16 v[14:17], v[166:169], v[212:215], v[14:17]
	v_mfma_f32_16x16x32_bf16 v[66:69], v[162:165], v[184:187], v[66:69]
	v_mfma_f32_16x16x32_bf16 v[62:65], v[170:173], v[184:187], v[62:65]
	v_mfma_f32_16x16x32_bf16 v[50:53], v[162:165], v[192:195], v[50:53]
	v_mfma_f32_16x16x32_bf16 v[46:49], v[170:173], v[192:195], v[46:49]
	s_add_i32 s82, s82, 2
	s_add_u32 s80, s80, 0x100
	s_addc_u32 s81, s81, 0
	s_cmp_gt_u32 s82, 13
	s_mov_b64 s[2:3], s[8:9]
	v_mfma_f32_16x16x32_bf16 v[34:37], v[162:165], v[208:211], v[34:37]
	v_mfma_f32_16x16x32_bf16 v[30:33], v[170:173], v[208:211], v[30:33]
	v_mfma_f32_16x16x32_bf16 v[18:21], v[162:165], v[216:219], v[18:21]
	v_mfma_f32_16x16x32_bf16 v[14:17], v[170:173], v[216:219], v[14:17]
	s_setprio 0
	s_barrier
	s_cbranch_scc0 .LBB13_358
	s_and_b64 vcc, exec, s[42:43]
	s_cbranch_vccz .LBB13_361
	s_barrier

;     __device__ float mid(int row) const { return rg(row) / ra(row); }
; #define PG8_STAGE(bufoff, gbase, voff) do { const char* gb_ = (const char*)(gbase); asm volatile("" : "+s"(gb_));     \
;         _Pragma("unroll") for (int _i = 0; _i < 2; ++_i) \
;         __builtin_amdgcn_global_load_lds((const unsigned*)(gb_ + (voff)[_i]), (PG8_LAS unsigned*)(lds + (bufoff) + ldsw + _i * 8192), 16, 0, 0); } while (0)
; #define PG8_LDA(dst, b, h) do { _Pragma("unroll") for (int m = 0; m < 4; ++m) _Pragma("unroll") for (int k = 0; k < 2; ++k) dst[m][k] = *(const PG8_LAS bf16x8*)(lds + PG8_SA(b, h) + aoff + m * 2048 + k * 1024); } while (0)
; #define PG8_LDB(dst, b, h) do { _Pragma("unroll") for (int n = 0; n < 2; ++n) _Pragma("unroll") for (int k = 0; k < 2; ++k) dst[n][k] = *(const PG8_LAS bf16x8*)(lds + PG8_SB(b, h) + boff + n * 2048 + k * 1024); } while (0)
; #define PG8_WAIT_V(n) asm volatile("s_waitcnt vmcnt(" #n ")" ::: "memory")
; template <class Epi, class Sched, bool ALIGN_EPI = false, bool SP2 = false>
; __device__ __forceinline__ void gemm_phase(PG8_LAS unsigned char* lds, const Gemm g, const Sched& S, const Epi& E, int wid0) {
;     ...
;         for (int t = 0; t < nt; t += 2) {
;             const bool last = (t == nt - 2);
;             const char* a1 = cA + (size_t)(t + 1) * kstep;
;             const char* a2 = last ? nA : cA + (size_t)(t + 2) * kstep; const char* b2 = last ? nB : cB + (size_t)(t + 2) * kstep;
;             const char* a3 = a2 + kstep; const char* b3 = b2 + kstep;
;             if (last && has_next) S.a_ready(nxt);
;             if constexpr (Epi::HAS_MID) { if (t == Epi::MID_T) E.mid(acc, cur, wr, fr); }
;             unsigned vA_[2] = {voffA[0], voffA[1]}, vB_[2] = {voffB[0], voffB[1]};
;             asm volatile("" : "+v"(vA_[0]), "+v"(vA_[1]), "+v"(vB_[0]), "+v"(vB_[1]));
;             if constexpr (SP2) {
;             PG8_LDB(B0, 0, 0); PG8_LDB(B1, 0, 1); PG8_SCHED; PG8_LDA(At, 0, 0); PG8_STAGE(PG8_SA(1, 1), a1 + hstepA, vA_);
;             PG8_WAIT_V(8); PG8_WAIT_L(0); PG8_BAR; PG8_MMA(0, 0, At, B0); PG8_MMA(0, 1, At, B1); PG8_BAR; PG8_SCHED;
;             PG8_LDA(At, 0, 1); PG8_STAGE(PG8_SB(0, 0), b2, vB_); PG8_STAGE(PG8_SB(0, 1), b2 + hstep, vB_); PG8_STAGE(PG8_SA(0, 0), a2, vA_);
;             PG8_WAIT_V(8); PG8_WAIT_L(0); PG8_BAR; PG8_MMA(1, 0, At, B0); PG8_MMA(1, 1, At, B1); PG8_BAR; PG8_SCHED;
.LBB13_942:
	v_mov_b32_e32 v9, v160
	v_mov_b32_e32 v154, v162
	v_mov_b32_e32 v155, v156
	v_mov_b32_e32 v166, v158
	v_add_u32_e32 v10, s64, v157
	ds_read_b128 v[142:145], v10
	ds_read_b128 v[146:149], v10 offset:1024
	ds_read_b128 v[150:153], v10 offset:2048
	ds_read_b128 v[168:171], v10 offset:3072
	v_add_u32_e32 v10, s65, v157
	s_add_u32 s6, s42, 0x100
	ds_read_b128 v[172:175], v10
	ds_read_b128 v[176:179], v10 offset:1024
	ds_read_b128 v[180:183], v10 offset:2048
	ds_read_b128 v[184:187], v10 offset:3072
	s_addc_u32 s7, s43, 0
	s_cmp_eq_u32 s70, 12
	s_cselect_b32 s50, s35, s6
	s_cselect_b32 s51, s29, s7
	s_cselect_b32 s45, s31, s69
	s_cselect_b32 s44, s67, s68
	s_add_u32 s46, s50, 0x80
	s_addc_u32 s47, s51, 0
	s_add_u32 s48, s44, 0x80
	s_addc_u32 s49, s45, 0
	s_add_u32 s42, s42, 0x80080
	s_addc_u32 s43, s43, 0
	s_add_i32 m0, s13, 0xc000
	ds_read_b128 v[188:191], v167
	ds_read_b128 v[192:195], v167 offset:1024
	ds_read_b128 v[196:199], v167 offset:2048
	ds_read_b128 v[200:203], v167 offset:3072
	ds_read_b128 v[204:207], v167 offset:4096
	ds_read_b128 v[208:211], v167 offset:5120
	ds_read_b128 v[212:215], v167 offset:6144
	ds_read_b128 v[216:219], v167 offset:7168
	s_nop 0
	global_load_lds_dwordx4 v155, s[42:43]
	s_add_i32 m0, s13, 0xe000
	s_nop 0
	global_load_lds_dwordx4 v9, s[42:43]
	s_waitcnt vmcnt(8)
	s_waitcnt lgkmcnt(0)
	s_barrier
	s_setprio 1
	s_waitcnt lgkmcnt(0)
	v_mfma_f32_16x16x32_bf16 v[136:139], v[142:145], v[188:191], v[136:139]
	v_mfma_f32_16x16x32_bf16 v[132:135], v[150:153], v[188:191], v[132:135]
	v_mfma_f32_16x16x32_bf16 v[128:131], v[142:145], v[196:199], v[128:131]
	v_mfma_f32_16x16x32_bf16 v[124:127], v[150:153], v[196:199], v[124:127]
	v_mfma_f32_16x16x32_bf16 v[120:123], v[142:145], v[204:207], v[120:123]
	v_mfma_f32_16x16x32_bf16 v[116:119], v[150:153], v[204:207], v[116:119]
	v_mfma_f32_16x16x32_bf16 v[112:115], v[142:145], v[212:215], v[112:115]
	v_mfma_f32_16x16x32_bf16 v[108:111], v[150:153], v[212:215], v[108:111]
	v_mfma_f32_16x16x32_bf16 v[136:139], v[146:149], v[192:195], v[136:139]
	v_mfma_f32_16x16x32_bf16 v[132:135], v[168:171], v[192:195], v[132:135]
	v_mfma_f32_16x16x32_bf16 v[128:131], v[146:149], v[200:203], v[128:131]
	v_mfma_f32_16x16x32_bf16 v[124:127], v[168:171], v[200:203], v[124:127]
	v_mfma_f32_16x16x32_bf16 v[120:123], v[146:149], v[208:211], v[120:123]
	v_mfma_f32_16x16x32_bf16 v[116:119], v[168:171], v[208:211], v[116:119]
	v_mfma_f32_16x16x32_bf16 v[112:115], v[146:149], v[216:219], v[112:115]
	v_mfma_f32_16x16x32_bf16 v[108:111], v[168:171], v[216:219], v[108:111]
	s_setprio 0
	s_setprio 1
	v_mfma_f32_16x16x32_bf16 v[72:75], v[172:175], v[188:191], v[72:75]
	v_mfma_f32_16x16x32_bf16 v[68:71], v[180:183], v[188:191], v[68:71]
	v_mfma_f32_16x16x32_bf16 v[64:67], v[172:175], v[196:199], v[64:67]
	v_mfma_f32_16x16x32_bf16 v[60:63], v[180:183], v[196:199], v[60:63]
	v_mfma_f32_16x16x32_bf16 v[56:59], v[172:175], v[204:207], v[56:59]
	v_mfma_f32_16x16x32_bf16 v[52:55], v[180:183], v[204:207], v[52:55]
	v_mfma_f32_16x16x32_bf16 v[48:51], v[172:175], v[212:215], v[48:51]
	v_mfma_f32_16x16x32_bf16 v[44:47], v[180:183], v[212:215], v[44:47]
	v_mfma_f32_16x16x32_bf16 v[72:75], v[176:179], v[192:195], v[72:75]
	v_mfma_f32_16x16x32_bf16 v[68:71], v[184:187], v[192:195], v[68:71]
	v_mfma_f32_16x16x32_bf16 v[64:67], v[176:179], v[200:203], v[64:67]
	v_mfma_f32_16x16x32_bf16 v[60:63], v[184:187], v[200:203], v[60:63]
	v_mfma_f32_16x16x32_bf16 v[56:59], v[176:179], v[208:211], v[56:59]
	v_mfma_f32_16x16x32_bf16 v[52:55], v[184:187], v[208:211], v[52:55]
	v_mfma_f32_16x16x32_bf16 v[48:51], v[176:179], v[216:219], v[48:51]
	v_mfma_f32_16x16x32_bf16 v[44:47], v[184:187], v[216:219], v[44:47]
	s_setprio 0
	s_barrier
	s_add_i32 s71, s64, s27
	s_mov_b64 s[42:43], s[44:45]
	s_mov_b32 m0, s71
	ds_read_b128 v[188:191], v167 offset:16384
	ds_read_b128 v[192:195], v167 offset:17408
	ds_read_b128 v[196:199], v167 offset:18432
	ds_read_b128 v[200:203], v167 offset:19456
	ds_read_b128 v[204:207], v167 offset:20480
	ds_read_b128 v[208:211], v167 offset:21504
	ds_read_b128 v[212:215], v167 offset:22528
	ds_read_b128 v[216:219], v167 offset:23552
	s_nop 0
	global_load_lds_dwordx4 v166, s[42:43]
	s_add_i32 m0, s71, 0x2000
	s_nop 0
	global_load_lds_dwordx4 v154, s[42:43]
	s_add_u32 s42, s44, 0x40000
	s_addc_u32 s43, s45, 0
	s_add_i32 s71, s65, s27
	s_mov_b32 m0, s71
	s_nop 0
	global_load_lds_dwordx4 v166, s[42:43]
	s_add_i32 m0, s71, 0x2000
	s_nop 0
	global_load_lds_dwordx4 v154, s[42:43]
	s_mov_b64 s[42:43], s[50:51]
	s_mov_b32 m0, s13
	s_nop 0
	global_load_lds_dwordx4 v155, s[42:43]
	s_mov_b32 m0, s53
	s_nop 0
	global_load_lds_dwordx4 v9, s[42:43]
	s_waitcnt vmcnt(8)
	s_waitcnt lgkmcnt(0)
	s_barrier
; #define PG8_STAGE(bufoff, gbase, voff) do { const char* gb_ = (const char*)(gbase); asm volatile("" : "+s"(gb_));     \
;         _Pragma("unroll") for (int _i = 0; _i < 2; ++_i) \
;         __builtin_amdgcn_global_load_lds((const unsigned*)(gb_ + (voff)[_i]), (PG8_LAS unsigned*)(lds + (bufoff) + ldsw + _i * 8192), 16, 0, 0); } while (0)
; #define PG8_LDA(dst, b, h) do { _Pragma("unroll") for (int m = 0; m < 4; ++m) _Pragma("unroll") for (int k = 0; k < 2; ++k) dst[m][k] = *(const PG8_LAS bf16x8*)(lds + PG8_SA(b, h) + aoff + m * 2048 + k * 1024); } while (0)
; #define PG8_LDB(dst, b, h) do { _Pragma("unroll") for (int n = 0; n < 2; ++n) _Pragma("unroll") for (int k = 0; k < 2; ++k) dst[n][k] = *(const PG8_LAS bf16x8*)(lds + PG8_SB(b, h) + boff + n * 2048 + k * 1024); } while (0)
; #define PG8_MMA(ai, bj, At, Bt) do { __builtin_amdgcn_s_setprio(1); _Pragma("unroll") for (int m = 0; m < 4; ++m) _Pragma("unroll") for (int n = 0; n < 2; ++n) _Pragma("unroll") for (int k = 0; k < 2; ++k) \
;         acc[ai][bj][m][n] = __builtin_amdgcn_mfma_f32_16x16x32_bf16(Bt[n][k], At[m][k], acc[ai][bj][m][n], 0, 0, 0); __builtin_amdgcn_s_setprio(0); } while (0)
; #define PG8_WAIT_V(n) asm volatile("s_waitcnt vmcnt(" #n ")" ::: "memory")
; #define PG8_WAIT_L(n) asm volatile("s_waitcnt lgkmcnt(" #n ")" ::: "memory")
; #define PG8_BAR __builtin_amdgcn_s_barrier()
; #define PG8_SCHED __builtin_amdgcn_sched_barrier(0)
; template <class Epi, class Sched, bool ALIGN_EPI = false, bool SP2 = false>
; __device__ __forceinline__ void gemm_phase(PG8_LAS unsigned char* lds, const Gemm g, const Sched& S, const Epi& E, int wid0) {
;     ...
;             PG8_WAIT_V(8); PG8_WAIT_L(0); PG8_BAR; PG8_MMA(0, 0, At, B0); PG8_MMA(0, 1, At, B1); PG8_BAR; PG8_SCHED;
;             PG8_LDA(At, 0, 1); PG8_STAGE(PG8_SB(0, 0), b2, vB_); PG8_STAGE(PG8_SB(0, 1), b2 + hstep, vB_); PG8_STAGE(PG8_SA(0, 0), a2, vA_);
;             PG8_WAIT_V(8); PG8_WAIT_L(0); PG8_BAR; PG8_MMA(1, 0, At, B0); PG8_MMA(1, 1, At, B1); PG8_BAR; PG8_SCHED;
;             PG8_LDB(B0, 1, 0); PG8_LDB(B1, 1, 1); PG8_SCHED; PG8_LDA(At, 1, 0); PG8_STAGE(PG8_SA(0, 1), a2 + hstepA, vA_);
;             PG8_WAIT_V(8); PG8_WAIT_L(0); PG8_BAR; PG8_MMA(0, 0, At, B0); PG8_MMA(0, 1, At, B1); PG8_BAR; PG8_SCHED;
	s_setprio 1
	s_waitcnt lgkmcnt(0)
	v_mfma_f32_16x16x32_bf16 v[104:107], v[142:145], v[188:191], v[104:107]
	v_mfma_f32_16x16x32_bf16 v[100:103], v[150:153], v[188:191], v[100:103]
	v_mfma_f32_16x16x32_bf16 v[96:99], v[142:145], v[196:199], v[96:99]
	v_mfma_f32_16x16x32_bf16 v[92:95], v[150:153], v[196:199], v[92:95]
	v_mfma_f32_16x16x32_bf16 v[88:91], v[142:145], v[204:207], v[88:91]
	v_mfma_f32_16x16x32_bf16 v[84:87], v[150:153], v[204:207], v[84:87]
	v_mfma_f32_16x16x32_bf16 v[80:83], v[142:145], v[212:215], v[80:83]
	v_mfma_f32_16x16x32_bf16 v[76:79], v[150:153], v[212:215], v[76:79]
	v_mfma_f32_16x16x32_bf16 v[104:107], v[146:149], v[192:195], v[104:107]
	v_mfma_f32_16x16x32_bf16 v[100:103], v[168:171], v[192:195], v[100:103]
	v_mfma_f32_16x16x32_bf16 v[96:99], v[146:149], v[200:203], v[96:99]
	v_mfma_f32_16x16x32_bf16 v[92:95], v[168:171], v[200:203], v[92:95]
	v_mfma_f32_16x16x32_bf16 v[88:91], v[146:149], v[208:211], v[88:91]
	v_mfma_f32_16x16x32_bf16 v[84:87], v[168:171], v[208:211], v[84:87]
	v_mfma_f32_16x16x32_bf16 v[80:83], v[146:149], v[216:219], v[80:83]
	v_mfma_f32_16x16x32_bf16 v[76:79], v[168:171], v[216:219], v[76:79]
	s_setprio 0
	s_setprio 1
	v_mfma_f32_16x16x32_bf16 v[40:43], v[172:175], v[188:191], v[40:43]
	v_mfma_f32_16x16x32_bf16 v[36:39], v[180:183], v[188:191], v[36:39]
	v_mfma_f32_16x16x32_bf16 v[32:35], v[172:175], v[196:199], v[32:35]
	v_mfma_f32_16x16x32_bf16 v[28:31], v[180:183], v[196:199], v[28:31]
	v_mfma_f32_16x16x32_bf16 v[24:27], v[172:175], v[204:207], v[24:27]
	v_mfma_f32_16x16x32_bf16 v[20:23], v[180:183], v[204:207], v[20:23]
	v_mfma_f32_16x16x32_bf16 v[16:19], v[172:175], v[212:215], v[16:19]
	v_mfma_f32_16x16x32_bf16 v[10:13], v[180:183], v[212:215], v[12:15]
	v_mfma_f32_16x16x32_bf16 v[40:43], v[176:179], v[192:195], v[40:43]
	v_mfma_f32_16x16x32_bf16 v[36:39], v[184:187], v[192:195], v[36:39]
	v_mfma_f32_16x16x32_bf16 v[32:35], v[176:179], v[200:203], v[32:35]
	v_mfma_f32_16x16x32_bf16 v[28:31], v[184:187], v[200:203], v[28:31]
	v_mfma_f32_16x16x32_bf16 v[24:27], v[176:179], v[208:211], v[24:27]
	v_mfma_f32_16x16x32_bf16 v[20:23], v[184:187], v[208:211], v[20:23]
	v_mfma_f32_16x16x32_bf16 v[16:19], v[176:179], v[216:219], v[16:19]
	v_mfma_f32_16x16x32_bf16 v[10:13], v[184:187], v[216:219], v[10:13]
	s_setprio 0
	s_barrier
	s_add_i32 s71, 0, 0x18000
	v_add_u32_e32 v14, s71, v157
	s_add_i32 s72, 0, 0x1c000
	ds_read_b128 v[142:145], v14
	ds_read_b128 v[146:149], v14 offset:1024
	ds_read_b128 v[150:153], v14 offset:2048
	ds_read_b128 v[168:171], v14 offset:3072
	v_add_u32_e32 v14, s72, v157
	ds_read_b128 v[172:175], v14
	ds_read_b128 v[176:179], v14 offset:1024
	ds_read_b128 v[180:183], v14 offset:2048
	ds_read_b128 v[184:187], v14 offset:3072
	s_add_u32 s42, s50, 0x80000
	s_addc_u32 s43, s51, 0
	s_mov_b32 m0, s54
	ds_read_b128 v[188:191], v167 offset:32768
	ds_read_b128 v[192:195], v167 offset:33792
	ds_read_b128 v[196:199], v167 offset:34816
	ds_read_b128 v[200:203], v167 offset:35840
	ds_read_b128 v[204:207], v167 offset:36864
	ds_read_b128 v[208:211], v167 offset:37888
	ds_read_b128 v[212:215], v167 offset:38912
	ds_read_b128 v[216:219], v167 offset:39936
	s_nop 0
	global_load_lds_dwordx4 v155, s[42:43]
	s_mov_b32 m0, s55
	s_nop 0
	global_load_lds_dwordx4 v9, s[42:43]
	s_waitcnt vmcnt(8)
	s_waitcnt lgkmcnt(0)
	s_barrier
	s_setprio 1
	s_waitcnt lgkmcnt(0)
	v_mfma_f32_16x16x32_bf16 v[136:139], v[142:145], v[188:191], v[136:139]
	v_mfma_f32_16x16x32_bf16 v[132:135], v[150:153], v[188:191], v[132:135]
	v_mfma_f32_16x16x32_bf16 v[128:131], v[142:145], v[196:199], v[128:131]
	v_mfma_f32_16x16x32_bf16 v[124:127], v[150:153], v[196:199], v[124:127]
	v_mfma_f32_16x16x32_bf16 v[120:123], v[142:145], v[204:207], v[120:123]
	v_mfma_f32_16x16x32_bf16 v[116:119], v[150:153], v[204:207], v[116:119]
	v_mfma_f32_16x16x32_bf16 v[112:115], v[142:145], v[212:215], v[112:115]
	v_mfma_f32_16x16x32_bf16 v[108:111], v[150:153], v[212:215], v[108:111]
	v_mfma_f32_16x16x32_bf16 v[136:139], v[146:149], v[192:195], v[136:139]
	v_mfma_f32_16x16x32_bf16 v[132:135], v[168:171], v[192:195], v[132:135]
	v_mfma_f32_16x16x32_bf16 v[128:131], v[146:149], v[200:203], v[128:131]
	v_mfma_f32_16x16x32_bf16 v[124:127], v[168:171], v[200:203], v[124:127]
	v_mfma_f32_16x16x32_bf16 v[120:123], v[146:149], v[208:211], v[120:123]
	v_mfma_f32_16x16x32_bf16 v[116:119], v[168:171], v[208:211], v[116:119]
	v_mfma_f32_16x16x32_bf16 v[112:115], v[146:149], v[216:219], v[112:115]
	v_mfma_f32_16x16x32_bf16 v[108:111], v[168:171], v[216:219], v[108:111]
	s_setprio 0
	s_setprio 1
	v_mfma_f32_16x16x32_bf16 v[72:75], v[172:175], v[188:191], v[72:75]
	v_mfma_f32_16x16x32_bf16 v[68:71], v[180:183], v[188:191], v[68:71]
	v_mfma_f32_16x16x32_bf16 v[64:67], v[172:175], v[196:199], v[64:67]
	v_mfma_f32_16x16x32_bf16 v[60:63], v[180:183], v[196:199], v[60:63]
	v_mfma_f32_16x16x32_bf16 v[56:59], v[172:175], v[204:207], v[56:59]
	v_mfma_f32_16x16x32_bf16 v[52:55], v[180:183], v[204:207], v[52:55]
	v_mfma_f32_16x16x32_bf16 v[48:51], v[172:175], v[212:215], v[48:51]
	v_mfma_f32_16x16x32_bf16 v[44:47], v[180:183], v[212:215], v[44:47]
	v_mfma_f32_16x16x32_bf16 v[72:75], v[176:179], v[192:195], v[72:75]
	v_mfma_f32_16x16x32_bf16 v[68:71], v[184:187], v[192:195], v[68:71]
	v_mfma_f32_16x16x32_bf16 v[64:67], v[176:179], v[200:203], v[64:67]
	v_mfma_f32_16x16x32_bf16 v[60:63], v[184:187], v[200:203], v[60:63]
	v_mfma_f32_16x16x32_bf16 v[56:59], v[176:179], v[208:211], v[56:59]
	v_mfma_f32_16x16x32_bf16 v[52:55], v[184:187], v[208:211], v[52:55]
	v_mfma_f32_16x16x32_bf16 v[48:51], v[176:179], v[216:219], v[48:51]
	v_mfma_f32_16x16x32_bf16 v[44:47], v[184:187], v[216:219], v[44:47]
	s_setprio 0
	s_barrier
;     __device__ float mid(int row) const { return rg(row) / ra(row); }
; #define PG8_STAGE(bufoff, gbase, voff) do { const char* gb_ = (const char*)(gbase); asm volatile("" : "+s"(gb_));     \
;         _Pragma("unroll") for (int _i = 0; _i < 2; ++_i) \
;         __builtin_amdgcn_global_load_lds((const unsigned*)(gb_ + (voff)[_i]), (PG8_LAS unsigned*)(lds + (bufoff) + ldsw + _i * 8192), 16, 0, 0); } while (0)
; #define PG8_BAR __builtin_amdgcn_s_barrier()
; template <class Epi, class Sched, bool ALIGN_EPI = false, bool SP2 = false>
; __device__ __forceinline__ void gemm_phase(PG8_LAS unsigned char* lds, const Gemm g, const Sched& S, const Epi& E, int wid0) {
;     ...
;         for (int t = 0; t < nt; t += 2) {
;             const bool last = (t == nt - 2);
;             const char* a1 = cA + (size_t)(t + 1) * kstep;
;             const char* a2 = last ? nA : cA + (size_t)(t + 2) * kstep; const char* b2 = last ? nB : cB + (size_t)(t + 2) * kstep;
;             const char* a3 = a2 + kstep; const char* b3 = b2 + kstep;
;             if (last && has_next) S.a_ready(nxt);
;             if constexpr (Epi::HAS_MID) { if (t == Epi::MID_T) E.mid(acc, cur, wr, fr); }
;             unsigned vA_[2] = {voffA[0], voffA[1]}, vB_[2] = {voffB[0], voffB[1]};
;             asm volatile("" : "+v"(vA_[0]), "+v"(vA_[1]), "+v"(vB_[0]), "+v"(vB_[1]));
;             if constexpr (SP2) {
;             PG8_LDB(B0, 0, 0); PG8_LDB(B1, 0, 1); PG8_SCHED; PG8_LDA(At, 0, 0); PG8_STAGE(PG8_SA(1, 1), a1 + hstepA, vA_);
;             PG8_WAIT_V(8); PG8_WAIT_L(0); PG8_BAR; PG8_MMA(0, 0, At, B0); PG8_MMA(0, 1, At, B1); PG8_BAR; PG8_SCHED;
;             PG8_LDA(At, 0, 1); PG8_STAGE(PG8_SB(0, 0), b2, vB_); PG8_STAGE(PG8_SB(0, 1), b2 + hstep, vB_); PG8_STAGE(PG8_SA(0, 0), a2, vA_);
;             PG8_WAIT_V(8); PG8_WAIT_L(0); PG8_BAR; PG8_MMA(1, 0, At, B0); PG8_MMA(1, 1, At, B1); PG8_BAR; PG8_SCHED;
;             PG8_LDB(B0, 1, 0); PG8_LDB(B1, 1, 1); PG8_SCHED; PG8_LDA(At, 1, 0); PG8_STAGE(PG8_SA(0, 1), a2 + hstepA, vA_);
;             PG8_WAIT_V(8); PG8_WAIT_L(0); PG8_BAR; PG8_MMA(0, 0, At, B0); PG8_MMA(0, 1, At, B1); PG8_BAR; PG8_SCHED;
;             PG8_LDA(At, 1, 1); PG8_STAGE(PG8_SB(1, 0), b3, vB_); PG8_STAGE(PG8_SB(1, 1), b3 + hstep, vB_); PG8_STAGE(PG8_SA(1, 0), a3, vA_);
;             PG8_WAIT_V(8); PG8_WAIT_L(0); PG8_BAR; PG8_MMA(1, 0, At, B0); PG8_MMA(1, 1, At, B1); PG8_BAR; PG8_SCHED;
	s_add_i32 s42, s71, s27
	s_mov_b32 m0, s42
	ds_read_b128 v[188:191], v167 offset:49152
	ds_read_b128 v[192:195], v167 offset:50176
	ds_read_b128 v[196:199], v167 offset:51200
	ds_read_b128 v[200:203], v167 offset:52224
	ds_read_b128 v[204:207], v167 offset:53248
	ds_read_b128 v[208:211], v167 offset:54272
	ds_read_b128 v[212:215], v167 offset:55296
	ds_read_b128 v[216:219], v167 offset:56320
	s_nop 0
	global_load_lds_dwordx4 v166, s[48:49]
	s_add_i32 m0, s42, 0x2000
	s_add_u32 s42, s44, 0x40080
	s_addc_u32 s43, s45, 0
	s_add_i32 s44, s72, s27
	global_load_lds_dwordx4 v154, s[48:49]
	s_mov_b32 m0, s44
	s_nop 0
	global_load_lds_dwordx4 v166, s[42:43]
	s_add_i32 m0, s44, 0x2000
	s_nop 0
	global_load_lds_dwordx4 v154, s[42:43]
	s_mov_b32 m0, s59
	s_nop 0
	global_load_lds_dwordx4 v155, s[46:47]
	s_mov_b32 m0, s60
	s_nop 0
	global_load_lds_dwordx4 v9, s[46:47]
	s_waitcnt vmcnt(8)
	s_waitcnt lgkmcnt(0)
	s_barrier
	s_setprio 1
	s_waitcnt lgkmcnt(0)
	v_mfma_f32_16x16x32_bf16 v[104:107], v[142:145], v[188:191], v[104:107]
	v_mfma_f32_16x16x32_bf16 v[100:103], v[150:153], v[188:191], v[100:103]
	v_mfma_f32_16x16x32_bf16 v[96:99], v[142:145], v[196:199], v[96:99]
	v_mfma_f32_16x16x32_bf16 v[92:95], v[150:153], v[196:199], v[92:95]
	v_mfma_f32_16x16x32_bf16 v[88:91], v[142:145], v[204:207], v[88:91]
	v_mfma_f32_16x16x32_bf16 v[84:87], v[150:153], v[204:207], v[84:87]
	v_mfma_f32_16x16x32_bf16 v[80:83], v[142:145], v[212:215], v[80:83]
	v_mfma_f32_16x16x32_bf16 v[76:79], v[150:153], v[212:215], v[76:79]
	v_mfma_f32_16x16x32_bf16 v[104:107], v[146:149], v[192:195], v[104:107]
	v_mfma_f32_16x16x32_bf16 v[100:103], v[168:171], v[192:195], v[100:103]
	v_mfma_f32_16x16x32_bf16 v[96:99], v[146:149], v[200:203], v[96:99]
	v_mfma_f32_16x16x32_bf16 v[92:95], v[168:171], v[200:203], v[92:95]
	v_mfma_f32_16x16x32_bf16 v[88:91], v[146:149], v[208:211], v[88:91]
	v_mfma_f32_16x16x32_bf16 v[84:87], v[168:171], v[208:211], v[84:87]
	v_mfma_f32_16x16x32_bf16 v[80:83], v[146:149], v[216:219], v[80:83]
	v_mfma_f32_16x16x32_bf16 v[76:79], v[168:171], v[216:219], v[76:79]
	s_setprio 0
	s_setprio 1
	v_mfma_f32_16x16x32_bf16 v[40:43], v[172:175], v[188:191], v[40:43]
	v_mfma_f32_16x16x32_bf16 v[36:39], v[180:183], v[188:191], v[36:39]
	v_mfma_f32_16x16x32_bf16 v[32:35], v[172:175], v[196:199], v[32:35]
	v_mfma_f32_16x16x32_bf16 v[28:31], v[180:183], v[196:199], v[28:31]
	v_mfma_f32_16x16x32_bf16 v[24:27], v[172:175], v[204:207], v[24:27]
	v_mfma_f32_16x16x32_bf16 v[20:23], v[180:183], v[204:207], v[20:23]
	v_mfma_f32_16x16x32_bf16 v[14:17], v[172:175], v[212:215], v[16:19]
	v_mfma_f32_16x16x32_bf16 v[10:13], v[180:183], v[212:215], v[10:13]
	v_mfma_f32_16x16x32_bf16 v[40:43], v[176:179], v[192:195], v[40:43]
	v_mfma_f32_16x16x32_bf16 v[36:39], v[184:187], v[192:195], v[36:39]
	v_mfma_f32_16x16x32_bf16 v[32:35], v[176:179], v[200:203], v[32:35]
	v_mfma_f32_16x16x32_bf16 v[28:31], v[184:187], v[200:203], v[28:31]
	s_add_i32 s70, s70, 2
	s_add_u32 s68, s68, 0x100
	s_addc_u32 s69, s69, 0
	s_cmp_gt_u32 s70, 13
	v_mfma_f32_16x16x32_bf16 v[24:27], v[176:179], v[208:211], v[24:27]
	v_mfma_f32_16x16x32_bf16 v[20:23], v[184:187], v[208:211], v[20:23]
	v_mfma_f32_16x16x32_bf16 v[16:19], v[176:179], v[216:219], v[14:17]
	v_mfma_f32_16x16x32_bf16 v[12:15], v[184:187], v[216:219], v[10:13]
	s_setprio 0
	s_barrier
	s_cbranch_scc1 .LBB13_944
	s_mov_b64 s[42:43], s[6:7]
	s_cmp_lg_u32 s70, 6
	s_cbranch_scc0 .LBB13_941
	s_branch .LBB13_942

; #define PG8_STAGE(bufoff, gbase, voff) do { const char* gb_ = (const char*)(gbase); asm volatile("" : "+s"(gb_));     \
;         _Pragma("unroll") for (int _i = 0; _i < 2; ++_i) \
;         __builtin_amdgcn_global_load_lds((const unsigned*)(gb_ + (voff)[_i]), (PG8_LAS unsigned*)(lds + (bufoff) + ldsw + _i * 8192), 16, 0, 0); } while (0)
; #define PG8_LDA(dst, b, h) do { _Pragma("unroll") for (int m = 0; m < 4; ++m) _Pragma("unroll") for (int k = 0; k < 2; ++k) dst[m][k] = *(const PG8_LAS bf16x8*)(lds + PG8_SA(b, h) + aoff + m * 2048 + k * 1024); } while (0)
; #define PG8_LDB(dst, b, h) do { _Pragma("unroll") for (int n = 0; n < 2; ++n) _Pragma("unroll") for (int k = 0; k < 2; ++k) dst[n][k] = *(const PG8_LAS bf16x8*)(lds + PG8_SB(b, h) + boff + n * 2048 + k * 1024); } while (0)
; #define PG8_MMA(ai, bj, At, Bt) do { __builtin_amdgcn_s_setprio(1); _Pragma("unroll") for (int m = 0; m < 4; ++m) _Pragma("unroll") for (int n = 0; n < 2; ++n) _Pragma("unroll") for (int k = 0; k < 2; ++k) \
;         acc[ai][bj][m][n] = __builtin_amdgcn_mfma_f32_16x16x32_bf16(Bt[n][k], At[m][k], acc[ai][bj][m][n], 0, 0, 0); __builtin_amdgcn_s_setprio(0); } while (0)
; #define PG8_WAIT_V(n) asm volatile("s_waitcnt vmcnt(" #n ")" ::: "memory")
; #define PG8_WAIT_L(n) asm volatile("s_waitcnt lgkmcnt(" #n ")" ::: "memory")
; #define PG8_BAR __builtin_amdgcn_s_barrier()
; #define PG8_SCHED __builtin_amdgcn_sched_barrier(0)
; template <class Epi, class Sched, bool ALIGN_EPI = false, bool SP2 = false>
; __device__ __forceinline__ void gemm_phase(PG8_LAS unsigned char* lds, const Gemm g, const Sched& S, const Epi& E, int wid0) {
;     ...
;             PG8_WAIT_V(8); PG8_WAIT_L(0); PG8_BAR; PG8_MMA(0, 0, At, B0); PG8_MMA(0, 1, At, B1); PG8_BAR; PG8_SCHED;
;             PG8_LDA(At, 0, 1); PG8_STAGE(PG8_SB(0, 0), b2, vB_); PG8_STAGE(PG8_SB(0, 1), b2 + hstep, vB_); PG8_STAGE(PG8_SA(0, 0), a2, vA_);
;             PG8_WAIT_V(8); PG8_WAIT_L(0); PG8_BAR; PG8_MMA(1, 0, At, B0); PG8_MMA(1, 1, At, B1); PG8_BAR; PG8_SCHED;
;             PG8_LDB(B0, 1, 0); PG8_LDB(B1, 1, 1); PG8_SCHED; PG8_LDA(At, 1, 0); PG8_STAGE(PG8_SA(0, 1), a2 + hstepA, vA_);
;             PG8_WAIT_V(8); PG8_WAIT_L(0); PG8_BAR; PG8_MMA(0, 0, At, B0); PG8_MMA(0, 1, At, B1); PG8_BAR; PG8_SCHED;
.Lff1a_wd_1:
	s_waitcnt lgkmcnt(0)
	s_barrier
	s_setprio 1
	s_waitcnt lgkmcnt(0)
	v_mfma_f32_16x16x32_bf16 v[74:77], v[142:145], v[186:189], v[74:77]
	v_mfma_f32_16x16x32_bf16 v[70:73], v[150:153], v[186:189], v[70:73]
	v_mfma_f32_16x16x32_bf16 v[58:61], v[142:145], v[194:197], v[58:61]
	v_mfma_f32_16x16x32_bf16 v[54:57], v[150:153], v[194:197], v[54:57]
	v_mfma_f32_16x16x32_bf16 v[42:45], v[142:145], v[202:205], v[42:45]
	v_mfma_f32_16x16x32_bf16 v[38:41], v[150:153], v[202:205], v[38:41]
	v_mfma_f32_16x16x32_bf16 v[26:29], v[142:145], v[210:213], v[26:29]
	v_mfma_f32_16x16x32_bf16 v[22:25], v[150:153], v[210:213], v[22:25]
	v_mfma_f32_16x16x32_bf16 v[74:77], v[146:149], v[190:193], v[74:77]
	v_mfma_f32_16x16x32_bf16 v[70:73], v[154:157], v[190:193], v[70:73]
	v_mfma_f32_16x16x32_bf16 v[58:61], v[146:149], v[198:201], v[58:61]
	v_mfma_f32_16x16x32_bf16 v[54:57], v[154:157], v[198:201], v[54:57]
	v_mfma_f32_16x16x32_bf16 v[42:45], v[146:149], v[206:209], v[42:45]
	v_mfma_f32_16x16x32_bf16 v[38:41], v[154:157], v[206:209], v[38:41]
	v_mfma_f32_16x16x32_bf16 v[26:29], v[146:149], v[214:217], v[26:29]
	v_mfma_f32_16x16x32_bf16 v[22:25], v[154:157], v[214:217], v[22:25]
	s_setprio 0
	s_setprio 1
	v_mfma_f32_16x16x32_bf16 v[66:69], v[164:167], v[186:189], v[66:69]
	v_mfma_f32_16x16x32_bf16 v[62:65], v[178:181], v[186:189], v[62:65]
	v_mfma_f32_16x16x32_bf16 v[50:53], v[164:167], v[194:197], v[50:53]
	v_mfma_f32_16x16x32_bf16 v[46:49], v[178:181], v[194:197], v[46:49]
	v_mfma_f32_16x16x32_bf16 v[34:37], v[164:167], v[202:205], v[34:37]
	v_mfma_f32_16x16x32_bf16 v[30:33], v[178:181], v[202:205], v[30:33]
	v_mfma_f32_16x16x32_bf16 v[18:21], v[164:167], v[210:213], v[18:21]
	v_mfma_f32_16x16x32_bf16 v[14:17], v[178:181], v[210:213], v[14:17]
	v_mfma_f32_16x16x32_bf16 v[66:69], v[174:177], v[190:193], v[66:69]
	v_mfma_f32_16x16x32_bf16 v[62:65], v[182:185], v[190:193], v[62:65]
	v_mfma_f32_16x16x32_bf16 v[50:53], v[174:177], v[198:201], v[50:53]
	v_mfma_f32_16x16x32_bf16 v[46:49], v[182:185], v[198:201], v[46:49]
	v_mfma_f32_16x16x32_bf16 v[34:37], v[174:177], v[206:209], v[34:37]
	v_mfma_f32_16x16x32_bf16 v[30:33], v[182:185], v[206:209], v[30:33]
	v_mfma_f32_16x16x32_bf16 v[18:21], v[174:177], v[214:217], v[18:21]
	v_mfma_f32_16x16x32_bf16 v[14:17], v[182:185], v[214:217], v[14:17]
	s_setprio 0
	s_barrier
	s_add_i32 s62, 0, 0x18000
	s_add_i32 s63, 0, 0x1c000
	v_add_u32_e32 v154, s62, v9
	v_add_u32_e32 v182, s63, v9
	ds_read_b128 v[142:145], v154
	ds_read_b128 v[146:149], v154 offset:1024
	ds_read_b128 v[150:153], v154 offset:2048
	ds_read_b128 v[154:157], v154 offset:3072
	ds_read_b128 v[164:167], v182
	ds_read_b128 v[174:177], v182 offset:1024
	ds_read_b128 v[178:181], v182 offset:2048
	ds_read_b128 v[182:185], v182 offset:3072
	s_add_u32 s8, s40, 0x40000
	s_addc_u32 s9, s41, 0
	s_mov_b32 m0, s46
	ds_read_b128 v[186:189], v173 offset:32768
	ds_read_b128 v[190:193], v173 offset:33792
	ds_read_b128 v[194:197], v173 offset:34816
	ds_read_b128 v[198:201], v173 offset:35840
	ds_read_b128 v[202:205], v173 offset:36864
	ds_read_b128 v[206:209], v173 offset:37888
	ds_read_b128 v[210:213], v173 offset:38912
	ds_read_b128 v[214:217], v173 offset:39936
	s_nop 0
	global_load_lds_dwordx4 v218, s[8:9]
	s_mov_b32 m0, s47
	s_nop 0
	global_load_lds_dwordx4 v220, s[8:9]
	s_waitcnt vmcnt(8)
	s_waitcnt lgkmcnt(0)
	s_barrier
	s_setprio 1
	s_waitcnt lgkmcnt(0)
	v_mfma_f32_16x16x32_bf16 v[138:141], v[142:145], v[186:189], v[138:141]
	v_mfma_f32_16x16x32_bf16 v[134:137], v[150:153], v[186:189], v[134:137]
	v_mfma_f32_16x16x32_bf16 v[122:125], v[142:145], v[194:197], v[122:125]
	v_mfma_f32_16x16x32_bf16 v[118:121], v[150:153], v[194:197], v[118:121]
	v_mfma_f32_16x16x32_bf16 v[106:109], v[142:145], v[202:205], v[106:109]
	v_mfma_f32_16x16x32_bf16 v[102:105], v[150:153], v[202:205], v[102:105]
	v_mfma_f32_16x16x32_bf16 v[90:93], v[142:145], v[210:213], v[90:93]
	v_mfma_f32_16x16x32_bf16 v[86:89], v[150:153], v[210:213], v[86:89]
	v_mfma_f32_16x16x32_bf16 v[138:141], v[146:149], v[190:193], v[138:141]
	v_mfma_f32_16x16x32_bf16 v[134:137], v[154:157], v[190:193], v[134:137]
	v_mfma_f32_16x16x32_bf16 v[122:125], v[146:149], v[198:201], v[122:125]
	v_mfma_f32_16x16x32_bf16 v[118:121], v[154:157], v[198:201], v[118:121]
	v_mfma_f32_16x16x32_bf16 v[106:109], v[146:149], v[206:209], v[106:109]
	v_mfma_f32_16x16x32_bf16 v[102:105], v[154:157], v[206:209], v[102:105]
	v_mfma_f32_16x16x32_bf16 v[90:93], v[146:149], v[214:217], v[90:93]
	v_mfma_f32_16x16x32_bf16 v[86:89], v[154:157], v[214:217], v[86:89]
	s_setprio 0
	s_setprio 1
	v_mfma_f32_16x16x32_bf16 v[130:133], v[164:167], v[186:189], v[130:133]
	v_mfma_f32_16x16x32_bf16 v[126:129], v[178:181], v[186:189], v[126:129]
	v_mfma_f32_16x16x32_bf16 v[114:117], v[164:167], v[194:197], v[114:117]
	v_mfma_f32_16x16x32_bf16 v[110:113], v[178:181], v[194:197], v[110:113]
	v_mfma_f32_16x16x32_bf16 v[98:101], v[164:167], v[202:205], v[98:101]
	v_mfma_f32_16x16x32_bf16 v[94:97], v[178:181], v[202:205], v[94:97]
	v_mfma_f32_16x16x32_bf16 v[82:85], v[164:167], v[210:213], v[82:85]
	v_mfma_f32_16x16x32_bf16 v[78:81], v[178:181], v[210:213], v[78:81]
	v_mfma_f32_16x16x32_bf16 v[130:133], v[174:177], v[190:193], v[130:133]
	v_mfma_f32_16x16x32_bf16 v[126:129], v[182:185], v[190:193], v[126:129]
	v_mfma_f32_16x16x32_bf16 v[114:117], v[174:177], v[198:201], v[114:117]
	v_mfma_f32_16x16x32_bf16 v[110:113], v[182:185], v[198:201], v[110:113]
	v_mfma_f32_16x16x32_bf16 v[98:101], v[174:177], v[206:209], v[98:101]
	v_mfma_f32_16x16x32_bf16 v[94:97], v[182:185], v[206:209], v[94:97]
	v_mfma_f32_16x16x32_bf16 v[82:85], v[174:177], v[214:217], v[82:85]
	v_mfma_f32_16x16x32_bf16 v[78:81], v[182:185], v[214:217], v[78:81]
	s_setprio 0
	s_barrier
;     __device__ float mid(int row) const { return rg(row) / ra(row); }
; #define PG8_STAGE(bufoff, gbase, voff) do { const char* gb_ = (const char*)(gbase); asm volatile("" : "+s"(gb_));     \
;         _Pragma("unroll") for (int _i = 0; _i < 2; ++_i) \
;         __builtin_amdgcn_global_load_lds((const unsigned*)(gb_ + (voff)[_i]), (PG8_LAS unsigned*)(lds + (bufoff) + ldsw + _i * 8192), 16, 0, 0); } while (0)
; #define PG8_BAR __builtin_amdgcn_s_barrier()
; template <class Epi, class Sched, bool ALIGN_EPI = false, bool SP2 = false>
; __device__ __forceinline__ void gemm_phase(PG8_LAS unsigned char* lds, const Gemm g, const Sched& S, const Epi& E, int wid0) {
;     ...
;         for (int t = 0; t < nt; t += 2) {
;             const bool last = (t == nt - 2);
;             const char* a1 = cA + (size_t)(t + 1) * kstep;
;             const char* a2 = last ? nA : cA + (size_t)(t + 2) * kstep; const char* b2 = last ? nB : cB + (size_t)(t + 2) * kstep;
;             const char* a3 = a2 + kstep; const char* b3 = b2 + kstep;
;             if (last && has_next) S.a_ready(nxt);
;             if constexpr (Epi::HAS_MID) { if (t == Epi::MID_T) E.mid(acc, cur, wr, fr); }
;             unsigned vA_[2] = {voffA[0], voffA[1]}, vB_[2] = {voffB[0], voffB[1]};
;             asm volatile("" : "+v"(vA_[0]), "+v"(vA_[1]), "+v"(vB_[0]), "+v"(vB_[1]));
;             if constexpr (SP2) {
;             PG8_LDB(B0, 0, 0); PG8_LDB(B1, 0, 1); PG8_SCHED; PG8_LDA(At, 0, 0); PG8_STAGE(PG8_SA(1, 1), a1 + hstepA, vA_);
;             PG8_WAIT_V(8); PG8_WAIT_L(0); PG8_BAR; PG8_MMA(0, 0, At, B0); PG8_MMA(0, 1, At, B1); PG8_BAR; PG8_SCHED;
;             PG8_LDA(At, 0, 1); PG8_STAGE(PG8_SB(0, 0), b2, vB_); PG8_STAGE(PG8_SB(0, 1), b2 + hstep, vB_); PG8_STAGE(PG8_SA(0, 0), a2, vA_);
;             PG8_WAIT_V(8); PG8_WAIT_L(0); PG8_BAR; PG8_MMA(1, 0, At, B0); PG8_MMA(1, 1, At, B1); PG8_BAR; PG8_SCHED;
;             PG8_LDB(B0, 1, 0); PG8_LDB(B1, 1, 1); PG8_SCHED; PG8_LDA(At, 1, 0); PG8_STAGE(PG8_SA(0, 1), a2 + hstepA, vA_);
;             PG8_WAIT_V(8); PG8_WAIT_L(0); PG8_BAR; PG8_MMA(0, 0, At, B0); PG8_MMA(0, 1, At, B1); PG8_BAR; PG8_SCHED;
;             PG8_LDA(At, 1, 1); PG8_STAGE(PG8_SB(1, 0), b3, vB_); PG8_STAGE(PG8_SB(1, 1), b3 + hstep, vB_); PG8_STAGE(PG8_SA(1, 0), a3, vA_);
;             PG8_WAIT_V(8); PG8_WAIT_L(0); PG8_BAR; PG8_MMA(1, 0, At, B0); PG8_MMA(1, 1, At, B1); PG8_BAR; PG8_SCHED;
	s_add_u32 s8, s38, 0x80
	s_addc_u32 s9, s39, 0
	s_add_i32 s40, s62, s27
	s_mov_b32 m0, s40
	ds_read_b128 v[186:189], v173 offset:49152
	ds_read_b128 v[190:193], v173 offset:50176
	ds_read_b128 v[194:197], v173 offset:51200
	ds_read_b128 v[198:201], v173 offset:52224
	ds_read_b128 v[202:205], v173 offset:53248
	ds_read_b128 v[206:209], v173 offset:54272
	ds_read_b128 v[210:213], v173 offset:55296
	ds_read_b128 v[214:217], v173 offset:56320
	s_nop 0
	global_load_lds_dwordx4 v219, s[8:9]
	s_add_i32 m0, s40, 0x2000
	s_nop 0
	global_load_lds_dwordx4 v221, s[8:9]
	s_add_u32 s8, s38, 0x10080
	s_addc_u32 s9, s39, 0
	s_add_i32 s38, s63, s27
	s_mov_b32 m0, s38
	s_nop 0
	global_load_lds_dwordx4 v219, s[8:9]
	s_add_i32 m0, s38, 0x2000
	s_nop 0
	global_load_lds_dwordx4 v221, s[8:9]
	s_mov_b32 m0, s50
	s_nop 0
	global_load_lds_dwordx4 v218, s[36:37]
	s_mov_b32 m0, s51
	s_nop 0
	global_load_lds_dwordx4 v220, s[36:37]
	s_waitcnt vmcnt(8)
	s_waitcnt lgkmcnt(0)
	s_barrier
	s_setprio 1
	s_waitcnt lgkmcnt(0)
	v_mfma_f32_16x16x32_bf16 v[74:77], v[142:145], v[186:189], v[74:77]
	v_mfma_f32_16x16x32_bf16 v[70:73], v[150:153], v[186:189], v[70:73]
	v_mfma_f32_16x16x32_bf16 v[58:61], v[142:145], v[194:197], v[58:61]
	v_mfma_f32_16x16x32_bf16 v[54:57], v[150:153], v[194:197], v[54:57]
	v_mfma_f32_16x16x32_bf16 v[42:45], v[142:145], v[202:205], v[42:45]
	v_mfma_f32_16x16x32_bf16 v[38:41], v[150:153], v[202:205], v[38:41]
	v_mfma_f32_16x16x32_bf16 v[26:29], v[142:145], v[210:213], v[26:29]
	v_mfma_f32_16x16x32_bf16 v[22:25], v[150:153], v[210:213], v[22:25]
	v_mfma_f32_16x16x32_bf16 v[74:77], v[146:149], v[190:193], v[74:77]
	v_mfma_f32_16x16x32_bf16 v[70:73], v[154:157], v[190:193], v[70:73]
	v_mfma_f32_16x16x32_bf16 v[58:61], v[146:149], v[198:201], v[58:61]
	v_mfma_f32_16x16x32_bf16 v[54:57], v[154:157], v[198:201], v[54:57]
	v_mfma_f32_16x16x32_bf16 v[42:45], v[146:149], v[206:209], v[42:45]
	v_mfma_f32_16x16x32_bf16 v[38:41], v[154:157], v[206:209], v[38:41]
	v_mfma_f32_16x16x32_bf16 v[26:29], v[146:149], v[214:217], v[26:29]
	v_mfma_f32_16x16x32_bf16 v[22:25], v[154:157], v[214:217], v[22:25]
	s_setprio 0
	s_setprio 1
	v_mfma_f32_16x16x32_bf16 v[66:69], v[164:167], v[186:189], v[66:69]
	v_mfma_f32_16x16x32_bf16 v[62:65], v[178:181], v[186:189], v[62:65]
	v_mfma_f32_16x16x32_bf16 v[50:53], v[164:167], v[194:197], v[50:53]
	v_mfma_f32_16x16x32_bf16 v[46:49], v[178:181], v[194:197], v[46:49]
	v_mfma_f32_16x16x32_bf16 v[34:37], v[164:167], v[202:205], v[34:37]
	v_mfma_f32_16x16x32_bf16 v[30:33], v[178:181], v[202:205], v[30:33]
	v_mfma_f32_16x16x32_bf16 v[18:21], v[164:167], v[210:213], v[18:21]
	v_mfma_f32_16x16x32_bf16 v[14:17], v[178:181], v[210:213], v[14:17]
	v_mfma_f32_16x16x32_bf16 v[66:69], v[174:177], v[190:193], v[66:69]
	v_mfma_f32_16x16x32_bf16 v[62:65], v[182:185], v[190:193], v[62:65]
	v_mfma_f32_16x16x32_bf16 v[50:53], v[174:177], v[198:201], v[50:53]
	v_mfma_f32_16x16x32_bf16 v[46:49], v[182:185], v[198:201], v[46:49]
	s_add_i32 s61, s61, 2
	s_add_u32 s59, s59, 0x100
	s_addc_u32 s60, s60, 0
	s_cmp_gt_u32 s61, 13
	s_mov_b64 s[8:9], s[34:35]
	v_mfma_f32_16x16x32_bf16 v[34:37], v[174:177], v[206:209], v[34:37]
	v_mfma_f32_16x16x32_bf16 v[30:33], v[182:185], v[206:209], v[30:33]
	v_mfma_f32_16x16x32_bf16 v[18:21], v[174:177], v[214:217], v[18:21]
	v_mfma_f32_16x16x32_bf16 v[14:17], v[182:185], v[214:217], v[14:17]
	s_setprio 0
	s_barrier
	s_cbranch_scc0 .LBB13_1074
	s_and_b64 vcc, exec, s[16:17]
	s_cbranch_vccz .LBB13_1077
	s_barrier

;     __device__ float mid(int row) const { return rg(row) / ra(row); }
; #define PG8_STAGE(bufoff, gbase, voff) do { const char* gb_ = (const char*)(gbase); asm volatile("" : "+s"(gb_));     \
;         _Pragma("unroll") for (int _i = 0; _i < 2; ++_i) \
;         __builtin_amdgcn_global_load_lds((const unsigned*)(gb_ + (voff)[_i]), (PG8_LAS unsigned*)(lds + (bufoff) + ldsw + _i * 8192), 16, 0, 0); } while (0)
; #define PG8_LDA(dst, b, h) do { _Pragma("unroll") for (int m = 0; m < 4; ++m) _Pragma("unroll") for (int k = 0; k < 2; ++k) dst[m][k] = *(const PG8_LAS bf16x8*)(lds + PG8_SA(b, h) + aoff + m * 2048 + k * 1024); } while (0)
; #define PG8_LDB(dst, b, h) do { _Pragma("unroll") for (int n = 0; n < 2; ++n) _Pragma("unroll") for (int k = 0; k < 2; ++k) dst[n][k] = *(const PG8_LAS bf16x8*)(lds + PG8_SB(b, h) + boff + n * 2048 + k * 1024); } while (0)
; #define PG8_WAIT_V(n) asm volatile("s_waitcnt vmcnt(" #n ")" ::: "memory")
; template <class Epi, class Sched, bool ALIGN_EPI = false, bool SP2 = false>
; __device__ __forceinline__ void gemm_phase(PG8_LAS unsigned char* lds, const Gemm g, const Sched& S, const Epi& E, int wid0) {
;     ...
;         for (int t = 0; t < nt; t += 2) {
;             const bool last = (t == nt - 2);
;             const char* a1 = cA + (size_t)(t + 1) * kstep;
;             const char* a2 = last ? nA : cA + (size_t)(t + 2) * kstep; const char* b2 = last ? nB : cB + (size_t)(t + 2) * kstep;
;             const char* a3 = a2 + kstep; const char* b3 = b2 + kstep;
;             if (last && has_next) S.a_ready(nxt);
;             if constexpr (Epi::HAS_MID) { if (t == Epi::MID_T) E.mid(acc, cur, wr, fr); }
;             unsigned vA_[2] = {voffA[0], voffA[1]}, vB_[2] = {voffB[0], voffB[1]};
;             asm volatile("" : "+v"(vA_[0]), "+v"(vA_[1]), "+v"(vB_[0]), "+v"(vB_[1]));
;             if constexpr (SP2) {
;             PG8_LDB(B0, 0, 0); PG8_LDB(B1, 0, 1); PG8_SCHED; PG8_LDA(At, 0, 0); PG8_STAGE(PG8_SA(1, 1), a1 + hstepA, vA_);
;             PG8_WAIT_V(8); PG8_WAIT_L(0); PG8_BAR; PG8_MMA(0, 0, At, B0); PG8_MMA(0, 1, At, B1); PG8_BAR; PG8_SCHED;
;             PG8_LDA(At, 0, 1); PG8_STAGE(PG8_SB(0, 0), b2, vB_); PG8_STAGE(PG8_SB(0, 1), b2 + hstep, vB_); PG8_STAGE(PG8_SA(0, 0), a2, vA_);
;             PG8_WAIT_V(8); PG8_WAIT_L(0); PG8_BAR; PG8_MMA(1, 0, At, B0); PG8_MMA(1, 1, At, B1); PG8_BAR; PG8_SCHED;
.LBB13_1187:
	v_mov_b32_e32 v181, v162
	v_mov_b32_e32 v202, v156
	v_mov_b32_e32 v203, v158
	v_mov_b32_e32 v204, v160
	ds_read_b128 v[128:131], v161
	ds_read_b128 v[132:135], v161 offset:1024
	ds_read_b128 v[136:139], v161 offset:2048
	ds_read_b128 v[140:143], v161 offset:3072
	ds_read_b128 v[144:147], v163
	ds_read_b128 v[148:151], v163 offset:1024
	ds_read_b128 v[152:155], v163 offset:2048
	ds_read_b128 v[164:167], v163 offset:3072
	s_add_u32 s34, s30, 0x100
	s_addc_u32 s35, s31, 0
	s_cmp_eq_u32 s60, 60
	s_cselect_b32 s40, s27, s34
	s_cselect_b32 s41, s17, s35
	s_cselect_b32 s38, s57, s58
	s_cselect_b32 s39, s19, s59
	s_add_u32 s36, s40, 0x80
	s_addc_u32 s37, s41, 0
	s_add_u32 s30, s30, 0x100080
	s_addc_u32 s31, s31, 0
	s_add_i32 m0, s29, 0xc000
	ds_read_b128 v[168:171], v180
	ds_read_b128 v[172:175], v180 offset:1024
	ds_read_b128 v[176:179], v180 offset:2048
	ds_read_b128 v[182:185], v180 offset:3072
	ds_read_b128 v[186:189], v180 offset:4096
	ds_read_b128 v[190:193], v180 offset:5120
	ds_read_b128 v[194:197], v180 offset:6144
	ds_read_b128 v[198:201], v180 offset:7168
	s_nop 0
	global_load_lds_dwordx4 v202, s[30:31]
	s_add_i32 m0, s29, 0xe000
	s_nop 0
	global_load_lds_dwordx4 v204, s[30:31]
	s_waitcnt vmcnt(8)
	s_waitcnt lgkmcnt(0)
	s_barrier
	s_setprio 1
	s_waitcnt lgkmcnt(0)
	v_mfma_f32_16x16x32_bf16 v[124:127], v[128:131], v[168:171], v[124:127]
	v_mfma_f32_16x16x32_bf16 v[120:123], v[136:139], v[168:171], v[120:123]
	v_mfma_f32_16x16x32_bf16 v[116:119], v[128:131], v[176:179], v[116:119]
	v_mfma_f32_16x16x32_bf16 v[112:115], v[136:139], v[176:179], v[112:115]
	v_mfma_f32_16x16x32_bf16 v[108:111], v[128:131], v[186:189], v[108:111]
	v_mfma_f32_16x16x32_bf16 v[104:107], v[136:139], v[186:189], v[104:107]
	v_mfma_f32_16x16x32_bf16 v[100:103], v[128:131], v[194:197], v[100:103]
	v_mfma_f32_16x16x32_bf16 v[96:99], v[136:139], v[194:197], v[96:99]
	v_mfma_f32_16x16x32_bf16 v[124:127], v[132:135], v[172:175], v[124:127]
	v_mfma_f32_16x16x32_bf16 v[120:123], v[140:143], v[172:175], v[120:123]
	v_mfma_f32_16x16x32_bf16 v[116:119], v[132:135], v[182:185], v[116:119]
	v_mfma_f32_16x16x32_bf16 v[112:115], v[140:143], v[182:185], v[112:115]
	v_mfma_f32_16x16x32_bf16 v[108:111], v[132:135], v[190:193], v[108:111]
	v_mfma_f32_16x16x32_bf16 v[104:107], v[140:143], v[190:193], v[104:107]
	v_mfma_f32_16x16x32_bf16 v[100:103], v[132:135], v[198:201], v[100:103]
	v_mfma_f32_16x16x32_bf16 v[96:99], v[140:143], v[198:201], v[96:99]
	s_setprio 0
	s_setprio 1
	v_mfma_f32_16x16x32_bf16 v[60:63], v[144:147], v[168:171], v[60:63]
	v_mfma_f32_16x16x32_bf16 v[56:59], v[152:155], v[168:171], v[56:59]
	v_mfma_f32_16x16x32_bf16 v[52:55], v[144:147], v[176:179], v[52:55]
	v_mfma_f32_16x16x32_bf16 v[48:51], v[152:155], v[176:179], v[48:51]
	v_mfma_f32_16x16x32_bf16 v[44:47], v[144:147], v[186:189], v[44:47]
	v_mfma_f32_16x16x32_bf16 v[40:43], v[152:155], v[186:189], v[40:43]
	v_mfma_f32_16x16x32_bf16 v[36:39], v[144:147], v[194:197], v[36:39]
	v_mfma_f32_16x16x32_bf16 v[32:35], v[152:155], v[194:197], v[32:35]
	v_mfma_f32_16x16x32_bf16 v[60:63], v[148:151], v[172:175], v[60:63]
	v_mfma_f32_16x16x32_bf16 v[56:59], v[164:167], v[172:175], v[56:59]
	v_mfma_f32_16x16x32_bf16 v[52:55], v[148:151], v[182:185], v[52:55]
	v_mfma_f32_16x16x32_bf16 v[48:51], v[164:167], v[182:185], v[48:51]
	v_mfma_f32_16x16x32_bf16 v[44:47], v[148:151], v[190:193], v[44:47]
	v_mfma_f32_16x16x32_bf16 v[40:43], v[164:167], v[190:193], v[40:43]
	v_mfma_f32_16x16x32_bf16 v[36:39], v[148:151], v[198:201], v[36:39]
	v_mfma_f32_16x16x32_bf16 v[32:35], v[164:167], v[198:201], v[32:35]
	s_setprio 0
	s_barrier
	s_add_i32 s61, s55, s33
	s_mov_b64 s[30:31], s[38:39]
	s_mov_b32 m0, s61
	ds_read_b128 v[168:171], v180 offset:16384
	ds_read_b128 v[172:175], v180 offset:17408
	ds_read_b128 v[176:179], v180 offset:18432
	ds_read_b128 v[182:185], v180 offset:19456
	ds_read_b128 v[186:189], v180 offset:20480
	ds_read_b128 v[190:193], v180 offset:21504
	ds_read_b128 v[194:197], v180 offset:22528
	ds_read_b128 v[198:201], v180 offset:23552
	s_nop 0
	global_load_lds_dwordx4 v203, s[30:31]
	s_add_i32 m0, s61, 0x2000
	s_nop 0
	global_load_lds_dwordx4 v181, s[30:31]
	s_add_u32 s30, s38, 0x100000
	s_addc_u32 s31, s39, 0
	s_add_i32 s61, s56, s33
	s_mov_b32 m0, s61
	s_nop 0
	global_load_lds_dwordx4 v203, s[30:31]
	s_add_i32 m0, s61, 0x2000
	s_nop 0
	global_load_lds_dwordx4 v181, s[30:31]
	s_mov_b64 s[30:31], s[40:41]
	s_mov_b32 m0, s29
	s_nop 0
	global_load_lds_dwordx4 v202, s[30:31]
	s_mov_b32 m0, s46
	s_nop 0
	global_load_lds_dwordx4 v204, s[30:31]
	s_waitcnt vmcnt(8)
	s_waitcnt lgkmcnt(0)
	s_barrier
; #define PG8_STAGE(bufoff, gbase, voff) do { const char* gb_ = (const char*)(gbase); asm volatile("" : "+s"(gb_));     \
;         _Pragma("unroll") for (int _i = 0; _i < 2; ++_i) \
;         __builtin_amdgcn_global_load_lds((const unsigned*)(gb_ + (voff)[_i]), (PG8_LAS unsigned*)(lds + (bufoff) + ldsw + _i * 8192), 16, 0, 0); } while (0)
; #define PG8_LDA(dst, b, h) do { _Pragma("unroll") for (int m = 0; m < 4; ++m) _Pragma("unroll") for (int k = 0; k < 2; ++k) dst[m][k] = *(const PG8_LAS bf16x8*)(lds + PG8_SA(b, h) + aoff + m * 2048 + k * 1024); } while (0)
; #define PG8_LDB(dst, b, h) do { _Pragma("unroll") for (int n = 0; n < 2; ++n) _Pragma("unroll") for (int k = 0; k < 2; ++k) dst[n][k] = *(const PG8_LAS bf16x8*)(lds + PG8_SB(b, h) + boff + n * 2048 + k * 1024); } while (0)
; #define PG8_MMA(ai, bj, At, Bt) do { __builtin_amdgcn_s_setprio(1); _Pragma("unroll") for (int m = 0; m < 4; ++m) _Pragma("unroll") for (int n = 0; n < 2; ++n) _Pragma("unroll") for (int k = 0; k < 2; ++k) \
;         acc[ai][bj][m][n] = __builtin_amdgcn_mfma_f32_16x16x32_bf16(Bt[n][k], At[m][k], acc[ai][bj][m][n], 0, 0, 0); __builtin_amdgcn_s_setprio(0); } while (0)
; template <class Epi, class Sched, bool ALIGN_EPI = false, bool SP2 = false>
; __device__ __forceinline__ void gemm_phase(PG8_LAS unsigned char* lds, const Gemm g, const Sched& S, const Epi& E, int wid0) {
;     ...
;             PG8_LDB(B0, 0, 0); PG8_LDB(B1, 0, 1); PG8_SCHED; PG8_LDA(At, 0, 0); PG8_STAGE(PG8_SA(1, 1), a1 + hstepA, vA_);
;             PG8_WAIT_V(8); PG8_WAIT_L(0); PG8_BAR; PG8_MMA(0, 0, At, B0); PG8_MMA(0, 1, At, B1); PG8_BAR; PG8_SCHED;
;             PG8_LDA(At, 0, 1); PG8_STAGE(PG8_SB(0, 0), b2, vB_); PG8_STAGE(PG8_SB(0, 1), b2 + hstep, vB_); PG8_STAGE(PG8_SA(0, 0), a2, vA_);
;             PG8_WAIT_V(8); PG8_WAIT_L(0); PG8_BAR; PG8_MMA(1, 0, At, B0); PG8_MMA(1, 1, At, B1); PG8_BAR; PG8_SCHED;
;             PG8_LDB(B0, 1, 0); PG8_LDB(B1, 1, 1); PG8_SCHED; PG8_LDA(At, 1, 0); PG8_STAGE(PG8_SA(0, 1), a2 + hstepA, vA_);
;             PG8_WAIT_V(8); PG8_WAIT_L(0); PG8_BAR; PG8_MMA(0, 0, At, B0); PG8_MMA(0, 1, At, B1); PG8_BAR; PG8_SCHED;
;             PG8_LDA(At, 1, 1); PG8_STAGE(PG8_SB(1, 0), b3, vB_); PG8_STAGE(PG8_SB(1, 1), b3 + hstep, vB_); PG8_STAGE(PG8_SA(1, 0), a3, vA_);
;             PG8_WAIT_V(8); PG8_WAIT_L(0); PG8_BAR; PG8_MMA(1, 0, At, B0); PG8_MMA(1, 1, At, B1); PG8_BAR; PG8_SCHED;
	s_setprio 1
	s_waitcnt lgkmcnt(0)
	v_mfma_f32_16x16x32_bf16 v[92:95], v[128:131], v[168:171], v[92:95]
	v_mfma_f32_16x16x32_bf16 v[88:91], v[136:139], v[168:171], v[88:91]
	v_mfma_f32_16x16x32_bf16 v[84:87], v[128:131], v[176:179], v[84:87]
	v_mfma_f32_16x16x32_bf16 v[80:83], v[136:139], v[176:179], v[80:83]
	v_mfma_f32_16x16x32_bf16 v[76:79], v[128:131], v[186:189], v[76:79]
	v_mfma_f32_16x16x32_bf16 v[72:75], v[136:139], v[186:189], v[72:75]
	v_mfma_f32_16x16x32_bf16 v[68:71], v[128:131], v[194:197], v[68:71]
	v_mfma_f32_16x16x32_bf16 v[64:67], v[136:139], v[194:197], v[64:67]
	v_mfma_f32_16x16x32_bf16 v[92:95], v[132:135], v[172:175], v[92:95]
	v_mfma_f32_16x16x32_bf16 v[88:91], v[140:143], v[172:175], v[88:91]
	v_mfma_f32_16x16x32_bf16 v[84:87], v[132:135], v[182:185], v[84:87]
	v_mfma_f32_16x16x32_bf16 v[80:83], v[140:143], v[182:185], v[80:83]
	v_mfma_f32_16x16x32_bf16 v[76:79], v[132:135], v[190:193], v[76:79]
	v_mfma_f32_16x16x32_bf16 v[72:75], v[140:143], v[190:193], v[72:75]
	v_mfma_f32_16x16x32_bf16 v[68:71], v[132:135], v[198:201], v[68:71]
	v_mfma_f32_16x16x32_bf16 v[64:67], v[140:143], v[198:201], v[64:67]
	s_setprio 0
	s_setprio 1
	v_mfma_f32_16x16x32_bf16 v[28:31], v[144:147], v[168:171], v[28:31]
	v_mfma_f32_16x16x32_bf16 v[24:27], v[152:155], v[168:171], v[24:27]
	v_mfma_f32_16x16x32_bf16 v[20:23], v[144:147], v[176:179], v[20:23]
	v_mfma_f32_16x16x32_bf16 v[16:19], v[152:155], v[176:179], v[16:19]
	v_mfma_f32_16x16x32_bf16 v[12:15], v[144:147], v[186:189], v[12:15]
	v_mfma_f32_16x16x32_bf16 v[8:11], v[152:155], v[186:189], v[8:11]
	v_mfma_f32_16x16x32_bf16 v[4:7], v[144:147], v[194:197], v[4:7]
	v_mfma_f32_16x16x32_bf16 v[0:3], v[152:155], v[194:197], v[0:3]
	v_mfma_f32_16x16x32_bf16 v[28:31], v[148:151], v[172:175], v[28:31]
	v_mfma_f32_16x16x32_bf16 v[24:27], v[164:167], v[172:175], v[24:27]
	v_mfma_f32_16x16x32_bf16 v[20:23], v[148:151], v[182:185], v[20:23]
	v_mfma_f32_16x16x32_bf16 v[16:19], v[164:167], v[182:185], v[16:19]
	v_mfma_f32_16x16x32_bf16 v[12:15], v[148:151], v[190:193], v[12:15]
	v_mfma_f32_16x16x32_bf16 v[8:11], v[164:167], v[190:193], v[8:11]
	v_mfma_f32_16x16x32_bf16 v[4:7], v[148:151], v[198:201], v[4:7]
	v_mfma_f32_16x16x32_bf16 v[0:3], v[164:167], v[198:201], v[0:3]
	s_setprio 0
	s_barrier
	s_add_i32 s61, 0, 0x18000
	s_add_i32 s62, 0, 0x1c000
	v_add_u32_e32 v140, s61, v157
	v_add_u32_e32 v164, s62, v157
	ds_read_b128 v[128:131], v140
	ds_read_b128 v[132:135], v140 offset:1024
	ds_read_b128 v[136:139], v140 offset:2048
	ds_read_b128 v[140:143], v140 offset:3072
	ds_read_b128 v[144:147], v164
	ds_read_b128 v[148:151], v164 offset:1024
	ds_read_b128 v[152:155], v164 offset:2048
	ds_read_b128 v[164:167], v164 offset:3072
	s_add_u32 s30, s40, 0x100000
	s_addc_u32 s31, s41, 0
	s_mov_b32 m0, s47
	ds_read_b128 v[168:171], v180 offset:32768
	ds_read_b128 v[172:175], v180 offset:33792
	ds_read_b128 v[176:179], v180 offset:34816
	ds_read_b128 v[182:185], v180 offset:35840
	ds_read_b128 v[186:189], v180 offset:36864
	ds_read_b128 v[190:193], v180 offset:37888
	ds_read_b128 v[194:197], v180 offset:38912
	ds_read_b128 v[198:201], v180 offset:39936
	s_nop 0
	global_load_lds_dwordx4 v202, s[30:31]
	s_mov_b32 m0, s48
	s_nop 0
	global_load_lds_dwordx4 v204, s[30:31]
	s_waitcnt vmcnt(8)
	s_waitcnt lgkmcnt(0)
	s_barrier
	s_setprio 1
	s_waitcnt lgkmcnt(0)
	v_mfma_f32_16x16x32_bf16 v[124:127], v[128:131], v[168:171], v[124:127]
	v_mfma_f32_16x16x32_bf16 v[120:123], v[136:139], v[168:171], v[120:123]
	v_mfma_f32_16x16x32_bf16 v[116:119], v[128:131], v[176:179], v[116:119]
	v_mfma_f32_16x16x32_bf16 v[112:115], v[136:139], v[176:179], v[112:115]
	v_mfma_f32_16x16x32_bf16 v[108:111], v[128:131], v[186:189], v[108:111]
	v_mfma_f32_16x16x32_bf16 v[104:107], v[136:139], v[186:189], v[104:107]
	v_mfma_f32_16x16x32_bf16 v[100:103], v[128:131], v[194:197], v[100:103]
	v_mfma_f32_16x16x32_bf16 v[96:99], v[136:139], v[194:197], v[96:99]
	v_mfma_f32_16x16x32_bf16 v[124:127], v[132:135], v[172:175], v[124:127]
	v_mfma_f32_16x16x32_bf16 v[120:123], v[140:143], v[172:175], v[120:123]
	v_mfma_f32_16x16x32_bf16 v[116:119], v[132:135], v[182:185], v[116:119]
	v_mfma_f32_16x16x32_bf16 v[112:115], v[140:143], v[182:185], v[112:115]
	v_mfma_f32_16x16x32_bf16 v[108:111], v[132:135], v[190:193], v[108:111]
	v_mfma_f32_16x16x32_bf16 v[104:107], v[140:143], v[190:193], v[104:107]
	v_mfma_f32_16x16x32_bf16 v[100:103], v[132:135], v[198:201], v[100:103]
	v_mfma_f32_16x16x32_bf16 v[96:99], v[140:143], v[198:201], v[96:99]
	s_setprio 0
	s_setprio 1
	v_mfma_f32_16x16x32_bf16 v[60:63], v[144:147], v[168:171], v[60:63]
	v_mfma_f32_16x16x32_bf16 v[56:59], v[152:155], v[168:171], v[56:59]
	v_mfma_f32_16x16x32_bf16 v[52:55], v[144:147], v[176:179], v[52:55]
	v_mfma_f32_16x16x32_bf16 v[48:51], v[152:155], v[176:179], v[48:51]
	v_mfma_f32_16x16x32_bf16 v[44:47], v[144:147], v[186:189], v[44:47]
	v_mfma_f32_16x16x32_bf16 v[40:43], v[152:155], v[186:189], v[40:43]
	v_mfma_f32_16x16x32_bf16 v[36:39], v[144:147], v[194:197], v[36:39]
	v_mfma_f32_16x16x32_bf16 v[32:35], v[152:155], v[194:197], v[32:35]
	v_mfma_f32_16x16x32_bf16 v[60:63], v[148:151], v[172:175], v[60:63]
	v_mfma_f32_16x16x32_bf16 v[56:59], v[164:167], v[172:175], v[56:59]
	v_mfma_f32_16x16x32_bf16 v[52:55], v[148:151], v[182:185], v[52:55]
	v_mfma_f32_16x16x32_bf16 v[48:51], v[164:167], v[182:185], v[48:51]
	v_mfma_f32_16x16x32_bf16 v[44:47], v[148:151], v[190:193], v[44:47]
	v_mfma_f32_16x16x32_bf16 v[40:43], v[164:167], v[190:193], v[40:43]
	v_mfma_f32_16x16x32_bf16 v[36:39], v[148:151], v[198:201], v[36:39]
	v_mfma_f32_16x16x32_bf16 v[32:35], v[164:167], v[198:201], v[32:35]
	s_setprio 0
	s_barrier
; #define PG8_STAGE(bufoff, gbase, voff) do { const char* gb_ = (const char*)(gbase); asm volatile("" : "+s"(gb_));     \
;         _Pragma("unroll") for (int _i = 0; _i < 2; ++_i) \
;         __builtin_amdgcn_global_load_lds((const unsigned*)(gb_ + (voff)[_i]), (PG8_LAS unsigned*)(lds + (bufoff) + ldsw + _i * 8192), 16, 0, 0); } while (0)
; #define PG8_LDA(dst, b, h) do { _Pragma("unroll") for (int m = 0; m < 4; ++m) _Pragma("unroll") for (int k = 0; k < 2; ++k) dst[m][k] = *(const PG8_LAS bf16x8*)(lds + PG8_SA(b, h) + aoff + m * 2048 + k * 1024); } while (0)
; #define PG8_LDB(dst, b, h) do { _Pragma("unroll") for (int n = 0; n < 2; ++n) _Pragma("unroll") for (int k = 0; k < 2; ++k) dst[n][k] = *(const PG8_LAS bf16x8*)(lds + PG8_SB(b, h) + boff + n * 2048 + k * 1024); } while (0)
; #define PG8_WAIT_V(n) asm volatile("s_waitcnt vmcnt(" #n ")" ::: "memory")
; #define PG8_WAIT_L(n) asm volatile("s_waitcnt lgkmcnt(" #n ")" ::: "memory")
; #define PG8_BAR __builtin_amdgcn_s_barrier()
; #define PG8_SCHED __builtin_amdgcn_sched_barrier(0)
; template <class Epi, class Sched, bool ALIGN_EPI = false, bool SP2 = false>
; __device__ __forceinline__ void gemm_phase(PG8_LAS unsigned char* lds, const Gemm g, const Sched& S, const Epi& E, int wid0) {
;     ...
;             PG8_LDB(B0, 0, 0); PG8_LDB(B1, 0, 1); PG8_SCHED; PG8_LDA(At, 0, 0); PG8_STAGE(PG8_SA(1, 1), a1 + hstepA, vA_);
;             PG8_WAIT_V(8); PG8_WAIT_L(0); PG8_BAR; PG8_MMA(0, 0, At, B0); PG8_MMA(0, 1, At, B1); PG8_BAR; PG8_SCHED;
;             PG8_LDA(At, 0, 1); PG8_STAGE(PG8_SB(0, 0), b2, vB_); PG8_STAGE(PG8_SB(0, 1), b2 + hstep, vB_); PG8_STAGE(PG8_SA(0, 0), a2, vA_);
;             PG8_WAIT_V(8); PG8_WAIT_L(0); PG8_BAR; PG8_MMA(1, 0, At, B0); PG8_MMA(1, 1, At, B1); PG8_BAR; PG8_SCHED;
;             PG8_LDB(B0, 1, 0); PG8_LDB(B1, 1, 1); PG8_SCHED; PG8_LDA(At, 1, 0); PG8_STAGE(PG8_SA(0, 1), a2 + hstepA, vA_);
;             PG8_WAIT_V(8); PG8_WAIT_L(0); PG8_BAR; PG8_MMA(0, 0, At, B0); PG8_MMA(0, 1, At, B1); PG8_BAR; PG8_SCHED;
;             PG8_LDA(At, 1, 1); PG8_STAGE(PG8_SB(1, 0), b3, vB_); PG8_STAGE(PG8_SB(1, 1), b3 + hstep, vB_); PG8_STAGE(PG8_SA(1, 0), a3, vA_);
;             PG8_WAIT_V(8); PG8_WAIT_L(0); PG8_BAR; PG8_MMA(1, 0, At, B0); PG8_MMA(1, 1, At, B1); PG8_BAR; PG8_SCHED;
;     ...
;         if constexpr (ALIGN_EPI) { if (wr == 0) PG8_BAR; }
	s_add_u32 s30, s38, 0x80
	s_addc_u32 s31, s39, 0
	s_add_i32 s40, s61, s33
	s_mov_b32 m0, s40
	ds_read_b128 v[168:171], v180 offset:49152
	ds_read_b128 v[172:175], v180 offset:50176
	ds_read_b128 v[176:179], v180 offset:51200
	ds_read_b128 v[182:185], v180 offset:52224
	ds_read_b128 v[186:189], v180 offset:53248
	ds_read_b128 v[190:193], v180 offset:54272
	ds_read_b128 v[194:197], v180 offset:55296
	ds_read_b128 v[198:201], v180 offset:56320
	s_nop 0
	global_load_lds_dwordx4 v203, s[30:31]
	s_add_i32 m0, s40, 0x2000
	s_nop 0
	global_load_lds_dwordx4 v181, s[30:31]
	s_add_u32 s30, s38, 0x100080
	s_addc_u32 s31, s39, 0
	s_add_i32 s38, s62, s33
	s_mov_b32 m0, s38
	s_nop 0
	global_load_lds_dwordx4 v203, s[30:31]
	s_add_i32 m0, s38, 0x2000
	s_nop 0
	global_load_lds_dwordx4 v181, s[30:31]
	s_mov_b32 m0, s53
	s_nop 0
	global_load_lds_dwordx4 v202, s[36:37]
	s_mov_b32 m0, s54
	s_nop 0
	global_load_lds_dwordx4 v204, s[36:37]
	s_waitcnt vmcnt(8)
	s_waitcnt lgkmcnt(0)
	s_barrier
	s_setprio 1
	s_waitcnt lgkmcnt(0)
	v_mfma_f32_16x16x32_bf16 v[92:95], v[128:131], v[168:171], v[92:95]
	v_mfma_f32_16x16x32_bf16 v[88:91], v[136:139], v[168:171], v[88:91]
	v_mfma_f32_16x16x32_bf16 v[84:87], v[128:131], v[176:179], v[84:87]
	v_mfma_f32_16x16x32_bf16 v[80:83], v[136:139], v[176:179], v[80:83]
	v_mfma_f32_16x16x32_bf16 v[76:79], v[128:131], v[186:189], v[76:79]
	v_mfma_f32_16x16x32_bf16 v[72:75], v[136:139], v[186:189], v[72:75]
	v_mfma_f32_16x16x32_bf16 v[68:71], v[128:131], v[194:197], v[68:71]
	v_mfma_f32_16x16x32_bf16 v[64:67], v[136:139], v[194:197], v[64:67]
	v_mfma_f32_16x16x32_bf16 v[92:95], v[132:135], v[172:175], v[92:95]
	v_mfma_f32_16x16x32_bf16 v[88:91], v[140:143], v[172:175], v[88:91]
	v_mfma_f32_16x16x32_bf16 v[84:87], v[132:135], v[182:185], v[84:87]
	v_mfma_f32_16x16x32_bf16 v[80:83], v[140:143], v[182:185], v[80:83]
	v_mfma_f32_16x16x32_bf16 v[76:79], v[132:135], v[190:193], v[76:79]
	v_mfma_f32_16x16x32_bf16 v[72:75], v[140:143], v[190:193], v[72:75]
	v_mfma_f32_16x16x32_bf16 v[68:71], v[132:135], v[198:201], v[68:71]
	v_mfma_f32_16x16x32_bf16 v[64:67], v[140:143], v[198:201], v[64:67]
	s_setprio 0
	s_setprio 1
	v_mfma_f32_16x16x32_bf16 v[28:31], v[144:147], v[168:171], v[28:31]
	v_mfma_f32_16x16x32_bf16 v[24:27], v[152:155], v[168:171], v[24:27]
	v_mfma_f32_16x16x32_bf16 v[20:23], v[144:147], v[176:179], v[20:23]
	v_mfma_f32_16x16x32_bf16 v[16:19], v[152:155], v[176:179], v[16:19]
	v_mfma_f32_16x16x32_bf16 v[12:15], v[144:147], v[186:189], v[12:15]
	v_mfma_f32_16x16x32_bf16 v[8:11], v[152:155], v[186:189], v[8:11]
	v_mfma_f32_16x16x32_bf16 v[4:7], v[144:147], v[194:197], v[4:7]
	v_mfma_f32_16x16x32_bf16 v[0:3], v[152:155], v[194:197], v[0:3]
	v_mfma_f32_16x16x32_bf16 v[28:31], v[148:151], v[172:175], v[28:31]
	v_mfma_f32_16x16x32_bf16 v[24:27], v[164:167], v[172:175], v[24:27]
	v_mfma_f32_16x16x32_bf16 v[20:23], v[148:151], v[182:185], v[20:23]
	v_mfma_f32_16x16x32_bf16 v[16:19], v[164:167], v[182:185], v[16:19]
	s_add_i32 s60, s60, 2
	s_add_u32 s58, s58, 0x100
	s_addc_u32 s59, s59, 0
	s_cmp_gt_u32 s60, 61
	s_mov_b64 s[30:31], s[34:35]
	v_mfma_f32_16x16x32_bf16 v[12:15], v[148:151], v[190:193], v[12:15]
	v_mfma_f32_16x16x32_bf16 v[8:11], v[164:167], v[190:193], v[8:11]
	v_mfma_f32_16x16x32_bf16 v[4:7], v[148:151], v[198:201], v[4:7]
	v_mfma_f32_16x16x32_bf16 v[0:3], v[164:167], v[198:201], v[0:3]
	s_setprio 0
	s_barrier
	s_cbranch_scc0 .LBB13_1187
	s_and_b64 vcc, exec, s[14:15]
	s_cbranch_vccz .LBB13_1190
	s_barrier

;     __device__ float mid(int row) const { return rg(row) / ra(row); }
; #define PG8_STAGE(bufoff, gbase, voff) do { const char* gb_ = (const char*)(gbase); asm volatile("" : "+s"(gb_));     \
;         _Pragma("unroll") for (int _i = 0; _i < 2; ++_i) \
;         __builtin_amdgcn_global_load_lds((const unsigned*)(gb_ + (voff)[_i]), (PG8_LAS unsigned*)(lds + (bufoff) + ldsw + _i * 8192), 16, 0, 0); } while (0)
; #define PG8_BAR __builtin_amdgcn_s_barrier()
; template <class Epi, class Sched, bool ALIGN_EPI = false, bool SP2 = false>
; __device__ __forceinline__ void gemm_phase(PG8_LAS unsigned char* lds, const Gemm g, const Sched& S, const Epi& E, int wid0) {
;     ...
;         for (int t = 0; t < nt; t += 2) {
;             const bool last = (t == nt - 2);
;             const char* a1 = cA + (size_t)(t + 1) * kstep;
;             const char* a2 = last ? nA : cA + (size_t)(t + 2) * kstep; const char* b2 = last ? nB : cB + (size_t)(t + 2) * kstep;
;             const char* a3 = a2 + kstep; const char* b3 = b2 + kstep;
;             if (last && has_next) S.a_ready(nxt);
;             if constexpr (Epi::HAS_MID) { if (t == Epi::MID_T) E.mid(acc, cur, wr, fr); }
;             unsigned vA_[2] = {voffA[0], voffA[1]}, vB_[2] = {voffB[0], voffB[1]};
;             asm volatile("" : "+v"(vA_[0]), "+v"(vA_[1]), "+v"(vB_[0]), "+v"(vB_[1]));
;             if constexpr (SP2) {
;             PG8_LDB(B0, 0, 0); PG8_LDB(B1, 0, 1); PG8_SCHED; PG8_LDA(At, 0, 0); PG8_STAGE(PG8_SA(1, 1), a1 + hstepA, vA_);
;             PG8_WAIT_V(8); PG8_WAIT_L(0); PG8_BAR; PG8_MMA(0, 0, At, B0); PG8_MMA(0, 1, At, B1); PG8_BAR; PG8_SCHED;
;             PG8_LDA(At, 0, 1); PG8_STAGE(PG8_SB(0, 0), b2, vB_); PG8_STAGE(PG8_SB(0, 1), b2 + hstep, vB_); PG8_STAGE(PG8_SA(0, 0), a2, vA_);
;             PG8_WAIT_V(8); PG8_WAIT_L(0); PG8_BAR; PG8_MMA(1, 0, At, B0); PG8_MMA(1, 1, At, B1); PG8_BAR; PG8_SCHED;
;             PG8_LDB(B0, 1, 0); PG8_LDB(B1, 1, 1); PG8_SCHED; PG8_LDA(At, 1, 0); PG8_STAGE(PG8_SA(0, 1), a2 + hstepA, vA_);
;             PG8_WAIT_V(8); PG8_WAIT_L(0); PG8_BAR; PG8_MMA(0, 0, At, B0); PG8_MMA(0, 1, At, B1); PG8_BAR; PG8_SCHED;
;             PG8_LDA(At, 1, 1); PG8_STAGE(PG8_SB(1, 0), b3, vB_); PG8_STAGE(PG8_SB(1, 1), b3 + hstep, vB_); PG8_STAGE(PG8_SA(1, 0), a3, vA_);
;             PG8_WAIT_V(8); PG8_WAIT_L(0); PG8_BAR; PG8_MMA(1, 0, At, B0); PG8_MMA(1, 1, At, B1); PG8_BAR; PG8_SCHED;
.LBB13_1336:
	v_mov_b32_e32 v8, v178
	v_mov_b32_e32 v220, v174
	v_mov_b32_e32 v221, v200
	v_mov_b32_e32 v222, v176
	ds_read_b128 v[82:85], v201
	ds_read_b128 v[90:93], v201 offset:1024
	ds_read_b128 v[94:97], v201 offset:2048
	ds_read_b128 v[102:105], v201 offset:3072
	ds_read_b128 v[158:161], v202
	ds_read_b128 v[162:165], v202 offset:1024
	ds_read_b128 v[166:169], v202 offset:2048
	ds_read_b128 v[170:173], v202 offset:3072
	s_add_u32 s8, s2, 0x100
	s_addc_u32 s9, s3, 0
	s_cmp_eq_u32 s82, 12
	s_cselect_b32 s58, s78, s8
	s_cselect_b32 s59, s47, s9
	s_cselect_b32 s12, s79, s80
	s_cselect_b32 s13, s49, s81
	s_add_u32 s10, s58, 0x80
	s_addc_u32 s11, s59, 0
	s_add_u32 s2, s2, 0x40080
	s_addc_u32 s3, s3, 0
	s_add_i32 m0, s57, 0xc000
	ds_read_b128 v[180:183], v203
	ds_read_b128 v[184:187], v203 offset:1024
	ds_read_b128 v[188:191], v203 offset:2048
	ds_read_b128 v[192:195], v203 offset:3072
	ds_read_b128 v[204:207], v203 offset:4096
	ds_read_b128 v[208:211], v203 offset:5120
	ds_read_b128 v[212:215], v203 offset:6144
	ds_read_b128 v[216:219], v203 offset:7168
	s_nop 0
	global_load_lds_dwordx4 v220, s[2:3]
	s_add_i32 m0, s57, 0xe000
	s_nop 0
	global_load_lds_dwordx4 v222, s[2:3]
	s_waitcnt vmcnt(8)
	s_waitcnt lgkmcnt(0)
	s_barrier
	s_setprio 1
	s_waitcnt lgkmcnt(0)
	v_mfma_f32_16x16x32_bf16 v[154:157], v[82:85], v[180:183], v[154:157]
	v_mfma_f32_16x16x32_bf16 v[150:153], v[94:97], v[180:183], v[150:153]
	v_mfma_f32_16x16x32_bf16 v[138:141], v[82:85], v[188:191], v[138:141]
	v_mfma_f32_16x16x32_bf16 v[134:137], v[94:97], v[188:191], v[134:137]
	v_mfma_f32_16x16x32_bf16 v[122:125], v[82:85], v[204:207], v[122:125]
	v_mfma_f32_16x16x32_bf16 v[118:121], v[94:97], v[204:207], v[118:121]
	v_mfma_f32_16x16x32_bf16 v[106:109], v[82:85], v[212:215], v[106:109]
	v_mfma_f32_16x16x32_bf16 v[98:101], v[94:97], v[212:215], v[98:101]
	v_mfma_f32_16x16x32_bf16 v[154:157], v[90:93], v[184:187], v[154:157]
	v_mfma_f32_16x16x32_bf16 v[150:153], v[102:105], v[184:187], v[150:153]
	v_mfma_f32_16x16x32_bf16 v[138:141], v[90:93], v[192:195], v[138:141]
	v_mfma_f32_16x16x32_bf16 v[134:137], v[102:105], v[192:195], v[134:137]
	v_mfma_f32_16x16x32_bf16 v[122:125], v[90:93], v[208:211], v[122:125]
	v_mfma_f32_16x16x32_bf16 v[118:121], v[102:105], v[208:211], v[118:121]
	v_mfma_f32_16x16x32_bf16 v[106:109], v[90:93], v[216:219], v[106:109]
	v_mfma_f32_16x16x32_bf16 v[98:101], v[102:105], v[216:219], v[98:101]
	s_setprio 0
	s_setprio 1
	v_mfma_f32_16x16x32_bf16 v[146:149], v[158:161], v[180:183], v[146:149]
	v_mfma_f32_16x16x32_bf16 v[142:145], v[166:169], v[180:183], v[142:145]
	v_mfma_f32_16x16x32_bf16 v[130:133], v[158:161], v[188:191], v[130:133]
	v_mfma_f32_16x16x32_bf16 v[126:129], v[166:169], v[188:191], v[126:129]
	v_mfma_f32_16x16x32_bf16 v[114:117], v[158:161], v[204:207], v[114:117]
	v_mfma_f32_16x16x32_bf16 v[110:113], v[166:169], v[204:207], v[110:113]
	v_mfma_f32_16x16x32_bf16 v[86:89], v[158:161], v[212:215], v[86:89]
	v_mfma_f32_16x16x32_bf16 v[78:81], v[166:169], v[212:215], v[78:81]
	v_mfma_f32_16x16x32_bf16 v[146:149], v[162:165], v[184:187], v[146:149]
	v_mfma_f32_16x16x32_bf16 v[142:145], v[170:173], v[184:187], v[142:145]
	v_mfma_f32_16x16x32_bf16 v[130:133], v[162:165], v[192:195], v[130:133]
	v_mfma_f32_16x16x32_bf16 v[126:129], v[170:173], v[192:195], v[126:129]
	v_mfma_f32_16x16x32_bf16 v[114:117], v[162:165], v[208:211], v[114:117]
	v_mfma_f32_16x16x32_bf16 v[110:113], v[170:173], v[208:211], v[110:113]
	v_mfma_f32_16x16x32_bf16 v[86:89], v[162:165], v[216:219], v[86:89]
	v_mfma_f32_16x16x32_bf16 v[78:81], v[170:173], v[216:219], v[78:81]
	s_setprio 0
	s_barrier
	s_add_i32 s83, s75, s55
	s_mov_b64 s[2:3], s[12:13]
	s_mov_b32 m0, s83
	ds_read_b128 v[180:183], v203 offset:16384
	ds_read_b128 v[184:187], v203 offset:17408
	ds_read_b128 v[188:191], v203 offset:18432
	ds_read_b128 v[192:195], v203 offset:19456
	ds_read_b128 v[204:207], v203 offset:20480
	ds_read_b128 v[208:211], v203 offset:21504
	ds_read_b128 v[212:215], v203 offset:22528
	ds_read_b128 v[216:219], v203 offset:23552
	s_nop 0
	global_load_lds_dwordx4 v221, s[2:3]
	s_add_i32 m0, s83, 0x2000
	s_nop 0
	global_load_lds_dwordx4 v8, s[2:3]
	s_add_u32 s2, s12, 0x40000
	s_addc_u32 s3, s13, 0
	s_add_i32 s83, s76, s55
	s_mov_b32 m0, s83
	s_nop 0
	global_load_lds_dwordx4 v221, s[2:3]
	s_add_i32 m0, s83, 0x2000
	s_nop 0
	global_load_lds_dwordx4 v8, s[2:3]
	s_mov_b64 s[2:3], s[58:59]
	s_mov_b32 m0, s57
	s_nop 0
	global_load_lds_dwordx4 v220, s[2:3]
	s_mov_b32 m0, s64
	s_nop 0
	global_load_lds_dwordx4 v222, s[2:3]
	s_waitcnt vmcnt(8)
	s_waitcnt lgkmcnt(0)
	s_barrier
; #define PG8_STAGE(bufoff, gbase, voff) do { const char* gb_ = (const char*)(gbase); asm volatile("" : "+s"(gb_));     \
;         _Pragma("unroll") for (int _i = 0; _i < 2; ++_i) \
;         __builtin_amdgcn_global_load_lds((const unsigned*)(gb_ + (voff)[_i]), (PG8_LAS unsigned*)(lds + (bufoff) + ldsw + _i * 8192), 16, 0, 0); } while (0)
; #define PG8_LDA(dst, b, h) do { _Pragma("unroll") for (int m = 0; m < 4; ++m) _Pragma("unroll") for (int k = 0; k < 2; ++k) dst[m][k] = *(const PG8_LAS bf16x8*)(lds + PG8_SA(b, h) + aoff + m * 2048 + k * 1024); } while (0)
; #define PG8_LDB(dst, b, h) do { _Pragma("unroll") for (int n = 0; n < 2; ++n) _Pragma("unroll") for (int k = 0; k < 2; ++k) dst[n][k] = *(const PG8_LAS bf16x8*)(lds + PG8_SB(b, h) + boff + n * 2048 + k * 1024); } while (0)
; #define PG8_MMA(ai, bj, At, Bt) do { __builtin_amdgcn_s_setprio(1); _Pragma("unroll") for (int m = 0; m < 4; ++m) _Pragma("unroll") for (int n = 0; n < 2; ++n) _Pragma("unroll") for (int k = 0; k < 2; ++k) \
;         acc[ai][bj][m][n] = __builtin_amdgcn_mfma_f32_16x16x32_bf16(Bt[n][k], At[m][k], acc[ai][bj][m][n], 0, 0, 0); __builtin_amdgcn_s_setprio(0); } while (0)
; template <class Epi, class Sched, bool ALIGN_EPI = false, bool SP2 = false>
; __device__ __forceinline__ void gemm_phase(PG8_LAS unsigned char* lds, const Gemm g, const Sched& S, const Epi& E, int wid0) {
;     ...
;             PG8_LDB(B0, 0, 0); PG8_LDB(B1, 0, 1); PG8_SCHED; PG8_LDA(At, 0, 0); PG8_STAGE(PG8_SA(1, 1), a1 + hstepA, vA_);
;             PG8_WAIT_V(8); PG8_WAIT_L(0); PG8_BAR; PG8_MMA(0, 0, At, B0); PG8_MMA(0, 1, At, B1); PG8_BAR; PG8_SCHED;
;             PG8_LDA(At, 0, 1); PG8_STAGE(PG8_SB(0, 0), b2, vB_); PG8_STAGE(PG8_SB(0, 1), b2 + hstep, vB_); PG8_STAGE(PG8_SA(0, 0), a2, vA_);
;             PG8_WAIT_V(8); PG8_WAIT_L(0); PG8_BAR; PG8_MMA(1, 0, At, B0); PG8_MMA(1, 1, At, B1); PG8_BAR; PG8_SCHED;
;             PG8_LDB(B0, 1, 0); PG8_LDB(B1, 1, 1); PG8_SCHED; PG8_LDA(At, 1, 0); PG8_STAGE(PG8_SA(0, 1), a2 + hstepA, vA_);
;             PG8_WAIT_V(8); PG8_WAIT_L(0); PG8_BAR; PG8_MMA(0, 0, At, B0); PG8_MMA(0, 1, At, B1); PG8_BAR; PG8_SCHED;
;             PG8_LDA(At, 1, 1); PG8_STAGE(PG8_SB(1, 0), b3, vB_); PG8_STAGE(PG8_SB(1, 1), b3 + hstep, vB_); PG8_STAGE(PG8_SA(1, 0), a3, vA_);
;             PG8_WAIT_V(8); PG8_WAIT_L(0); PG8_BAR; PG8_MMA(1, 0, At, B0); PG8_MMA(1, 1, At, B1); PG8_BAR; PG8_SCHED;
	s_setprio 1
	s_waitcnt lgkmcnt(0)
	v_mfma_f32_16x16x32_bf16 v[74:77], v[82:85], v[180:183], v[74:77]
	v_mfma_f32_16x16x32_bf16 v[70:73], v[94:97], v[180:183], v[70:73]
	v_mfma_f32_16x16x32_bf16 v[58:61], v[82:85], v[188:191], v[58:61]
	v_mfma_f32_16x16x32_bf16 v[54:57], v[94:97], v[188:191], v[54:57]
	v_mfma_f32_16x16x32_bf16 v[42:45], v[82:85], v[204:207], v[42:45]
	v_mfma_f32_16x16x32_bf16 v[38:41], v[94:97], v[204:207], v[38:41]
	v_mfma_f32_16x16x32_bf16 v[26:29], v[82:85], v[212:215], v[26:29]
	v_mfma_f32_16x16x32_bf16 v[22:25], v[94:97], v[212:215], v[22:25]
	v_mfma_f32_16x16x32_bf16 v[74:77], v[90:93], v[184:187], v[74:77]
	v_mfma_f32_16x16x32_bf16 v[70:73], v[102:105], v[184:187], v[70:73]
	v_mfma_f32_16x16x32_bf16 v[58:61], v[90:93], v[192:195], v[58:61]
	v_mfma_f32_16x16x32_bf16 v[54:57], v[102:105], v[192:195], v[54:57]
	v_mfma_f32_16x16x32_bf16 v[42:45], v[90:93], v[208:211], v[42:45]
	v_mfma_f32_16x16x32_bf16 v[38:41], v[102:105], v[208:211], v[38:41]
	v_mfma_f32_16x16x32_bf16 v[26:29], v[90:93], v[216:219], v[26:29]
	v_mfma_f32_16x16x32_bf16 v[22:25], v[102:105], v[216:219], v[22:25]
	s_setprio 0
	s_setprio 1
	v_mfma_f32_16x16x32_bf16 v[66:69], v[158:161], v[180:183], v[66:69]
	v_mfma_f32_16x16x32_bf16 v[62:65], v[166:169], v[180:183], v[62:65]
	v_mfma_f32_16x16x32_bf16 v[50:53], v[158:161], v[188:191], v[50:53]
	v_mfma_f32_16x16x32_bf16 v[46:49], v[166:169], v[188:191], v[46:49]
	v_mfma_f32_16x16x32_bf16 v[34:37], v[158:161], v[204:207], v[34:37]
	v_mfma_f32_16x16x32_bf16 v[30:33], v[166:169], v[204:207], v[30:33]
	v_mfma_f32_16x16x32_bf16 v[18:21], v[158:161], v[212:215], v[18:21]
	v_mfma_f32_16x16x32_bf16 v[14:17], v[166:169], v[212:215], v[14:17]
	v_mfma_f32_16x16x32_bf16 v[66:69], v[162:165], v[184:187], v[66:69]
	v_mfma_f32_16x16x32_bf16 v[62:65], v[170:173], v[184:187], v[62:65]
	v_mfma_f32_16x16x32_bf16 v[50:53], v[162:165], v[192:195], v[50:53]
	v_mfma_f32_16x16x32_bf16 v[46:49], v[170:173], v[192:195], v[46:49]
	v_mfma_f32_16x16x32_bf16 v[34:37], v[162:165], v[208:211], v[34:37]
	v_mfma_f32_16x16x32_bf16 v[30:33], v[170:173], v[208:211], v[30:33]
	v_mfma_f32_16x16x32_bf16 v[18:21], v[162:165], v[216:219], v[18:21]
	v_mfma_f32_16x16x32_bf16 v[14:17], v[170:173], v[216:219], v[14:17]
	s_setprio 0
	s_barrier
	s_add_i32 s83, 0, 0x18000
	s_add_i32 s84, 0, 0x1c000
	v_add_u32_e32 v102, s83, v175
	v_add_u32_e32 v170, s84, v175
	ds_read_b128 v[82:85], v102
	ds_read_b128 v[90:93], v102 offset:1024
	ds_read_b128 v[94:97], v102 offset:2048
	ds_read_b128 v[102:105], v102 offset:3072
	ds_read_b128 v[158:161], v170
	ds_read_b128 v[162:165], v170 offset:1024
	ds_read_b128 v[166:169], v170 offset:2048
	ds_read_b128 v[170:173], v170 offset:3072
	s_add_u32 s2, s58, 0x40000
	s_addc_u32 s3, s59, 0
	s_mov_b32 m0, s65
	ds_read_b128 v[180:183], v203 offset:32768
	ds_read_b128 v[184:187], v203 offset:33792
	ds_read_b128 v[188:191], v203 offset:34816
	ds_read_b128 v[192:195], v203 offset:35840
	ds_read_b128 v[204:207], v203 offset:36864
	ds_read_b128 v[208:211], v203 offset:37888
	ds_read_b128 v[212:215], v203 offset:38912
	ds_read_b128 v[216:219], v203 offset:39936
	s_nop 0
	global_load_lds_dwordx4 v220, s[2:3]
	s_mov_b32 m0, s66
	s_nop 0
	global_load_lds_dwordx4 v222, s[2:3]
	s_waitcnt vmcnt(8)
	s_waitcnt lgkmcnt(0)
	s_barrier
	s_setprio 1
	s_waitcnt lgkmcnt(0)
	v_mfma_f32_16x16x32_bf16 v[154:157], v[82:85], v[180:183], v[154:157]
	v_mfma_f32_16x16x32_bf16 v[150:153], v[94:97], v[180:183], v[150:153]
	v_mfma_f32_16x16x32_bf16 v[138:141], v[82:85], v[188:191], v[138:141]
	v_mfma_f32_16x16x32_bf16 v[134:137], v[94:97], v[188:191], v[134:137]
	v_mfma_f32_16x16x32_bf16 v[122:125], v[82:85], v[204:207], v[122:125]
	v_mfma_f32_16x16x32_bf16 v[118:121], v[94:97], v[204:207], v[118:121]
	v_mfma_f32_16x16x32_bf16 v[106:109], v[82:85], v[212:215], v[106:109]
	v_mfma_f32_16x16x32_bf16 v[98:101], v[94:97], v[212:215], v[98:101]
	v_mfma_f32_16x16x32_bf16 v[154:157], v[90:93], v[184:187], v[154:157]
	v_mfma_f32_16x16x32_bf16 v[150:153], v[102:105], v[184:187], v[150:153]
	v_mfma_f32_16x16x32_bf16 v[138:141], v[90:93], v[192:195], v[138:141]
	v_mfma_f32_16x16x32_bf16 v[134:137], v[102:105], v[192:195], v[134:137]
	v_mfma_f32_16x16x32_bf16 v[122:125], v[90:93], v[208:211], v[122:125]
	v_mfma_f32_16x16x32_bf16 v[118:121], v[102:105], v[208:211], v[118:121]
	v_mfma_f32_16x16x32_bf16 v[106:109], v[90:93], v[216:219], v[106:109]
	v_mfma_f32_16x16x32_bf16 v[98:101], v[102:105], v[216:219], v[98:101]
	s_setprio 0
	s_setprio 1
	v_mfma_f32_16x16x32_bf16 v[146:149], v[158:161], v[180:183], v[146:149]
	v_mfma_f32_16x16x32_bf16 v[142:145], v[166:169], v[180:183], v[142:145]
	v_mfma_f32_16x16x32_bf16 v[130:133], v[158:161], v[188:191], v[130:133]
	v_mfma_f32_16x16x32_bf16 v[126:129], v[166:169], v[188:191], v[126:129]
	v_mfma_f32_16x16x32_bf16 v[114:117], v[158:161], v[204:207], v[114:117]
	v_mfma_f32_16x16x32_bf16 v[110:113], v[166:169], v[204:207], v[110:113]
	v_mfma_f32_16x16x32_bf16 v[86:89], v[158:161], v[212:215], v[86:89]
	v_mfma_f32_16x16x32_bf16 v[78:81], v[166:169], v[212:215], v[78:81]
	v_mfma_f32_16x16x32_bf16 v[146:149], v[162:165], v[184:187], v[146:149]
	v_mfma_f32_16x16x32_bf16 v[142:145], v[170:173], v[184:187], v[142:145]
	v_mfma_f32_16x16x32_bf16 v[130:133], v[162:165], v[192:195], v[130:133]
	v_mfma_f32_16x16x32_bf16 v[126:129], v[170:173], v[192:195], v[126:129]
	v_mfma_f32_16x16x32_bf16 v[114:117], v[162:165], v[208:211], v[114:117]
	v_mfma_f32_16x16x32_bf16 v[110:113], v[170:173], v[208:211], v[110:113]
	v_mfma_f32_16x16x32_bf16 v[86:89], v[162:165], v[216:219], v[86:89]
	v_mfma_f32_16x16x32_bf16 v[78:81], v[170:173], v[216:219], v[78:81]
	s_setprio 0
	s_barrier
; #define PG8_STAGE(bufoff, gbase, voff) do { const char* gb_ = (const char*)(gbase); asm volatile("" : "+s"(gb_));     \
;         _Pragma("unroll") for (int _i = 0; _i < 2; ++_i) \
;         __builtin_amdgcn_global_load_lds((const unsigned*)(gb_ + (voff)[_i]), (PG8_LAS unsigned*)(lds + (bufoff) + ldsw + _i * 8192), 16, 0, 0); } while (0)
; #define PG8_LDA(dst, b, h) do { _Pragma("unroll") for (int m = 0; m < 4; ++m) _Pragma("unroll") for (int k = 0; k < 2; ++k) dst[m][k] = *(const PG8_LAS bf16x8*)(lds + PG8_SA(b, h) + aoff + m * 2048 + k * 1024); } while (0)
; #define PG8_LDB(dst, b, h) do { _Pragma("unroll") for (int n = 0; n < 2; ++n) _Pragma("unroll") for (int k = 0; k < 2; ++k) dst[n][k] = *(const PG8_LAS bf16x8*)(lds + PG8_SB(b, h) + boff + n * 2048 + k * 1024); } while (0)
; #define PG8_WAIT_V(n) asm volatile("s_waitcnt vmcnt(" #n ")" ::: "memory")
; #define PG8_WAIT_L(n) asm volatile("s_waitcnt lgkmcnt(" #n ")" ::: "memory")
; #define PG8_BAR __builtin_amdgcn_s_barrier()
; #define PG8_SCHED __builtin_amdgcn_sched_barrier(0)
; template <class Epi, class Sched, bool ALIGN_EPI = false, bool SP2 = false>
; __device__ __forceinline__ void gemm_phase(PG8_LAS unsigned char* lds, const Gemm g, const Sched& S, const Epi& E, int wid0) {
;     ...
;             PG8_LDB(B0, 0, 0); PG8_LDB(B1, 0, 1); PG8_SCHED; PG8_LDA(At, 0, 0); PG8_STAGE(PG8_SA(1, 1), a1 + hstepA, vA_);
;             PG8_WAIT_V(8); PG8_WAIT_L(0); PG8_BAR; PG8_MMA(0, 0, At, B0); PG8_MMA(0, 1, At, B1); PG8_BAR; PG8_SCHED;
;             PG8_LDA(At, 0, 1); PG8_STAGE(PG8_SB(0, 0), b2, vB_); PG8_STAGE(PG8_SB(0, 1), b2 + hstep, vB_); PG8_STAGE(PG8_SA(0, 0), a2, vA_);
;             PG8_WAIT_V(8); PG8_WAIT_L(0); PG8_BAR; PG8_MMA(1, 0, At, B0); PG8_MMA(1, 1, At, B1); PG8_BAR; PG8_SCHED;
;             PG8_LDB(B0, 1, 0); PG8_LDB(B1, 1, 1); PG8_SCHED; PG8_LDA(At, 1, 0); PG8_STAGE(PG8_SA(0, 1), a2 + hstepA, vA_);
;             PG8_WAIT_V(8); PG8_WAIT_L(0); PG8_BAR; PG8_MMA(0, 0, At, B0); PG8_MMA(0, 1, At, B1); PG8_BAR; PG8_SCHED;
;             PG8_LDA(At, 1, 1); PG8_STAGE(PG8_SB(1, 0), b3, vB_); PG8_STAGE(PG8_SB(1, 1), b3 + hstep, vB_); PG8_STAGE(PG8_SA(1, 0), a3, vA_);
;             PG8_WAIT_V(8); PG8_WAIT_L(0); PG8_BAR; PG8_MMA(1, 0, At, B0); PG8_MMA(1, 1, At, B1); PG8_BAR; PG8_SCHED;
;     ...
;         if constexpr (ALIGN_EPI) { if (wr == 0) PG8_BAR; }
	s_add_u32 s2, s12, 0x80
	s_addc_u32 s3, s13, 0
	s_add_i32 s58, s83, s55
	s_mov_b32 m0, s58
	ds_read_b128 v[180:183], v203 offset:49152
	ds_read_b128 v[184:187], v203 offset:50176
	ds_read_b128 v[188:191], v203 offset:51200
	ds_read_b128 v[192:195], v203 offset:52224
	ds_read_b128 v[204:207], v203 offset:53248
	ds_read_b128 v[208:211], v203 offset:54272
	ds_read_b128 v[212:215], v203 offset:55296
	ds_read_b128 v[216:219], v203 offset:56320
	s_nop 0
	global_load_lds_dwordx4 v221, s[2:3]
	s_add_i32 m0, s58, 0x2000
	s_nop 0
	global_load_lds_dwordx4 v8, s[2:3]
	s_add_u32 s2, s12, 0x40080
	s_addc_u32 s3, s13, 0
	s_add_i32 s12, s84, s55
	s_mov_b32 m0, s12
	s_nop 0
	global_load_lds_dwordx4 v221, s[2:3]
	s_add_i32 m0, s12, 0x2000
	s_nop 0
	global_load_lds_dwordx4 v8, s[2:3]
	s_mov_b32 m0, s69
	s_nop 0
	global_load_lds_dwordx4 v220, s[10:11]
	s_mov_b32 m0, s70
	s_nop 0
	global_load_lds_dwordx4 v222, s[10:11]
	s_waitcnt vmcnt(8)
	s_waitcnt lgkmcnt(0)
	s_barrier
	s_setprio 1
	s_waitcnt lgkmcnt(0)
	v_mfma_f32_16x16x32_bf16 v[74:77], v[82:85], v[180:183], v[74:77]
	v_mfma_f32_16x16x32_bf16 v[70:73], v[94:97], v[180:183], v[70:73]
	v_mfma_f32_16x16x32_bf16 v[58:61], v[82:85], v[188:191], v[58:61]
	v_mfma_f32_16x16x32_bf16 v[54:57], v[94:97], v[188:191], v[54:57]
	v_mfma_f32_16x16x32_bf16 v[42:45], v[82:85], v[204:207], v[42:45]
	v_mfma_f32_16x16x32_bf16 v[38:41], v[94:97], v[204:207], v[38:41]
	v_mfma_f32_16x16x32_bf16 v[26:29], v[82:85], v[212:215], v[26:29]
	v_mfma_f32_16x16x32_bf16 v[22:25], v[94:97], v[212:215], v[22:25]
	v_mfma_f32_16x16x32_bf16 v[74:77], v[90:93], v[184:187], v[74:77]
	v_mfma_f32_16x16x32_bf16 v[70:73], v[102:105], v[184:187], v[70:73]
	v_mfma_f32_16x16x32_bf16 v[58:61], v[90:93], v[192:195], v[58:61]
	v_mfma_f32_16x16x32_bf16 v[54:57], v[102:105], v[192:195], v[54:57]
	v_mfma_f32_16x16x32_bf16 v[42:45], v[90:93], v[208:211], v[42:45]
	v_mfma_f32_16x16x32_bf16 v[38:41], v[102:105], v[208:211], v[38:41]
	v_mfma_f32_16x16x32_bf16 v[26:29], v[90:93], v[216:219], v[26:29]
	v_mfma_f32_16x16x32_bf16 v[22:25], v[102:105], v[216:219], v[22:25]
	s_setprio 0
	s_setprio 1
	v_mfma_f32_16x16x32_bf16 v[66:69], v[158:161], v[180:183], v[66:69]
	v_mfma_f32_16x16x32_bf16 v[62:65], v[166:169], v[180:183], v[62:65]
	v_mfma_f32_16x16x32_bf16 v[50:53], v[158:161], v[188:191], v[50:53]
	v_mfma_f32_16x16x32_bf16 v[46:49], v[166:169], v[188:191], v[46:49]
	v_mfma_f32_16x16x32_bf16 v[34:37], v[158:161], v[204:207], v[34:37]
	v_mfma_f32_16x16x32_bf16 v[30:33], v[166:169], v[204:207], v[30:33]
	v_mfma_f32_16x16x32_bf16 v[18:21], v[158:161], v[212:215], v[18:21]
	v_mfma_f32_16x16x32_bf16 v[14:17], v[166:169], v[212:215], v[14:17]
	v_mfma_f32_16x16x32_bf16 v[66:69], v[162:165], v[184:187], v[66:69]
	v_mfma_f32_16x16x32_bf16 v[62:65], v[170:173], v[184:187], v[62:65]
	v_mfma_f32_16x16x32_bf16 v[50:53], v[162:165], v[192:195], v[50:53]
	v_mfma_f32_16x16x32_bf16 v[46:49], v[170:173], v[192:195], v[46:49]
	s_add_i32 s82, s82, 2
	s_add_u32 s80, s80, 0x100
	s_addc_u32 s81, s81, 0
	s_cmp_gt_u32 s82, 13
	s_mov_b64 s[2:3], s[8:9]
	v_mfma_f32_16x16x32_bf16 v[34:37], v[162:165], v[208:211], v[34:37]
	v_mfma_f32_16x16x32_bf16 v[30:33], v[170:173], v[208:211], v[30:33]
	v_mfma_f32_16x16x32_bf16 v[18:21], v[162:165], v[216:219], v[18:21]
	v_mfma_f32_16x16x32_bf16 v[14:17], v[170:173], v[216:219], v[14:17]
	s_setprio 0
	s_barrier
	s_cbranch_scc0 .LBB13_1336
	s_and_b64 vcc, exec, s[42:43]
	s_cbranch_vccz .LBB13_1339
	s_barrier

;     __device__ float mid(int row) const { return rg(row) / ra(row); }
; #define PG8_STAGE(bufoff, gbase, voff) do { const char* gb_ = (const char*)(gbase); asm volatile("" : "+s"(gb_));     \
;         _Pragma("unroll") for (int _i = 0; _i < 2; ++_i) \
;         __builtin_amdgcn_global_load_lds((const unsigned*)(gb_ + (voff)[_i]), (PG8_LAS unsigned*)(lds + (bufoff) + ldsw + _i * 8192), 16, 0, 0); } while (0)
; #define PG8_BAR __builtin_amdgcn_s_barrier()
; template <class Epi, class Sched, bool ALIGN_EPI = false, bool SP2 = false>
; __device__ __forceinline__ void gemm_phase(PG8_LAS unsigned char* lds, const Gemm g, const Sched& S, const Epi& E, int wid0) {
;     ...
;         for (int t = 0; t < nt; t += 2) {
;             const bool last = (t == nt - 2);
;             const char* a1 = cA + (size_t)(t + 1) * kstep;
;             const char* a2 = last ? nA : cA + (size_t)(t + 2) * kstep; const char* b2 = last ? nB : cB + (size_t)(t + 2) * kstep;
;             const char* a3 = a2 + kstep; const char* b3 = b2 + kstep;
;             if (last && has_next) S.a_ready(nxt);
;             if constexpr (Epi::HAS_MID) { if (t == Epi::MID_T) E.mid(acc, cur, wr, fr); }
;             unsigned vA_[2] = {voffA[0], voffA[1]}, vB_[2] = {voffB[0], voffB[1]};
;             asm volatile("" : "+v"(vA_[0]), "+v"(vA_[1]), "+v"(vB_[0]), "+v"(vB_[1]));
;             if constexpr (SP2) {
;             PG8_LDB(B0, 0, 0); PG8_LDB(B1, 0, 1); PG8_SCHED; PG8_LDA(At, 0, 0); PG8_STAGE(PG8_SA(1, 1), a1 + hstepA, vA_);
;             PG8_WAIT_V(8); PG8_WAIT_L(0); PG8_BAR; PG8_MMA(0, 0, At, B0); PG8_MMA(0, 1, At, B1); PG8_BAR; PG8_SCHED;
;             PG8_LDA(At, 0, 1); PG8_STAGE(PG8_SB(0, 0), b2, vB_); PG8_STAGE(PG8_SB(0, 1), b2 + hstep, vB_); PG8_STAGE(PG8_SA(0, 0), a2, vA_);
;             PG8_WAIT_V(8); PG8_WAIT_L(0); PG8_BAR; PG8_MMA(1, 0, At, B0); PG8_MMA(1, 1, At, B1); PG8_BAR; PG8_SCHED;
;             PG8_LDB(B0, 1, 0); PG8_LDB(B1, 1, 1); PG8_SCHED; PG8_LDA(At, 1, 0); PG8_STAGE(PG8_SA(0, 1), a2 + hstepA, vA_);
;             PG8_WAIT_V(8); PG8_WAIT_L(0); PG8_BAR; PG8_MMA(0, 0, At, B0); PG8_MMA(0, 1, At, B1); PG8_BAR; PG8_SCHED;
;             PG8_LDA(At, 1, 1); PG8_STAGE(PG8_SB(1, 0), b3, vB_); PG8_STAGE(PG8_SB(1, 1), b3 + hstep, vB_); PG8_STAGE(PG8_SA(1, 0), a3, vA_);
;             PG8_WAIT_V(8); PG8_WAIT_L(0); PG8_BAR; PG8_MMA(1, 0, At, B0); PG8_MMA(1, 1, At, B1); PG8_BAR; PG8_SCHED;
.LBB13_1920:
	v_mov_b32_e32 v9, v172
	v_mov_b32_e32 v170, v174
	v_mov_b32_e32 v171, v176
	v_mov_b32_e32 v182, v178
	v_add_u32_e32 v10, s62, v173
	ds_read_b128 v[142:145], v10
	ds_read_b128 v[146:149], v10 offset:1024
	ds_read_b128 v[150:153], v10 offset:2048
	ds_read_b128 v[154:157], v10 offset:3072
	v_add_u32_e32 v10, s63, v173
	s_add_u32 s6, s40, 0x100
	ds_read_b128 v[158:161], v10
	ds_read_b128 v[162:165], v10 offset:1024
	ds_read_b128 v[166:169], v10 offset:2048
	ds_read_b128 v[184:187], v10 offset:3072
	s_addc_u32 s7, s41, 0
	s_cmp_eq_u32 s68, 12
	s_cselect_b32 s48, s31, s6
	s_cselect_b32 s49, s27, s7
	s_cselect_b32 s43, s29, s67
	s_cselect_b32 s42, s65, s66
	s_add_u32 s44, s48, 0x80
	s_addc_u32 s45, s49, 0
	s_add_u32 s46, s42, 0x80
	s_addc_u32 s47, s43, 0
	s_add_u32 s40, s40, 0x80080
	s_addc_u32 s41, s41, 0
	s_add_i32 m0, s13, 0xc000
	ds_read_b128 v[188:191], v183
	ds_read_b128 v[192:195], v183 offset:1024
	ds_read_b128 v[196:199], v183 offset:2048
	ds_read_b128 v[200:203], v183 offset:3072
	ds_read_b128 v[204:207], v183 offset:4096
	ds_read_b128 v[208:211], v183 offset:5120
	ds_read_b128 v[212:215], v183 offset:6144
	ds_read_b128 v[216:219], v183 offset:7168
	s_nop 0
	global_load_lds_dwordx4 v9, s[40:41]
	s_add_i32 m0, s13, 0xe000
	s_nop 0
	global_load_lds_dwordx4 v171, s[40:41]
	s_waitcnt vmcnt(8)
	s_waitcnt lgkmcnt(0)
	s_barrier
	s_setprio 1
	s_waitcnt lgkmcnt(0)
	v_mfma_f32_16x16x32_bf16 v[136:139], v[142:145], v[188:191], v[136:139]
	v_mfma_f32_16x16x32_bf16 v[132:135], v[150:153], v[188:191], v[132:135]
	v_mfma_f32_16x16x32_bf16 v[128:131], v[142:145], v[196:199], v[128:131]
	v_mfma_f32_16x16x32_bf16 v[124:127], v[150:153], v[196:199], v[124:127]
	v_mfma_f32_16x16x32_bf16 v[120:123], v[142:145], v[204:207], v[120:123]
	v_mfma_f32_16x16x32_bf16 v[116:119], v[150:153], v[204:207], v[116:119]
	v_mfma_f32_16x16x32_bf16 v[112:115], v[142:145], v[212:215], v[112:115]
	v_mfma_f32_16x16x32_bf16 v[108:111], v[150:153], v[212:215], v[108:111]
	v_mfma_f32_16x16x32_bf16 v[136:139], v[146:149], v[192:195], v[136:139]
	v_mfma_f32_16x16x32_bf16 v[132:135], v[154:157], v[192:195], v[132:135]
	v_mfma_f32_16x16x32_bf16 v[128:131], v[146:149], v[200:203], v[128:131]
	v_mfma_f32_16x16x32_bf16 v[124:127], v[154:157], v[200:203], v[124:127]
	v_mfma_f32_16x16x32_bf16 v[120:123], v[146:149], v[208:211], v[120:123]
	v_mfma_f32_16x16x32_bf16 v[116:119], v[154:157], v[208:211], v[116:119]
	v_mfma_f32_16x16x32_bf16 v[112:115], v[146:149], v[216:219], v[112:115]
	v_mfma_f32_16x16x32_bf16 v[108:111], v[154:157], v[216:219], v[108:111]
	s_setprio 0
	s_setprio 1
	v_mfma_f32_16x16x32_bf16 v[72:75], v[158:161], v[188:191], v[72:75]
	v_mfma_f32_16x16x32_bf16 v[68:71], v[166:169], v[188:191], v[68:71]
	v_mfma_f32_16x16x32_bf16 v[64:67], v[158:161], v[196:199], v[64:67]
	v_mfma_f32_16x16x32_bf16 v[60:63], v[166:169], v[196:199], v[60:63]
	v_mfma_f32_16x16x32_bf16 v[56:59], v[158:161], v[204:207], v[56:59]
	v_mfma_f32_16x16x32_bf16 v[52:55], v[166:169], v[204:207], v[52:55]
	v_mfma_f32_16x16x32_bf16 v[48:51], v[158:161], v[212:215], v[48:51]
	v_mfma_f32_16x16x32_bf16 v[44:47], v[166:169], v[212:215], v[44:47]
	v_mfma_f32_16x16x32_bf16 v[72:75], v[162:165], v[192:195], v[72:75]
	v_mfma_f32_16x16x32_bf16 v[68:71], v[184:187], v[192:195], v[68:71]
	v_mfma_f32_16x16x32_bf16 v[64:67], v[162:165], v[200:203], v[64:67]
	v_mfma_f32_16x16x32_bf16 v[60:63], v[184:187], v[200:203], v[60:63]
	v_mfma_f32_16x16x32_bf16 v[56:59], v[162:165], v[208:211], v[56:59]
	v_mfma_f32_16x16x32_bf16 v[52:55], v[184:187], v[208:211], v[52:55]
	v_mfma_f32_16x16x32_bf16 v[48:51], v[162:165], v[216:219], v[48:51]
	v_mfma_f32_16x16x32_bf16 v[44:47], v[184:187], v[216:219], v[44:47]
	s_setprio 0
	s_barrier
	s_add_i32 s69, s62, s25
	s_mov_b64 s[40:41], s[42:43]
	s_mov_b32 m0, s69
	ds_read_b128 v[188:191], v183 offset:16384
	ds_read_b128 v[192:195], v183 offset:17408
	ds_read_b128 v[196:199], v183 offset:18432
	ds_read_b128 v[200:203], v183 offset:19456
	ds_read_b128 v[204:207], v183 offset:20480
	ds_read_b128 v[208:211], v183 offset:21504
	ds_read_b128 v[212:215], v183 offset:22528
	ds_read_b128 v[216:219], v183 offset:23552
	s_nop 0
	global_load_lds_dwordx4 v170, s[40:41]
	s_add_i32 m0, s69, 0x2000
	s_nop 0
	global_load_lds_dwordx4 v182, s[40:41]
	s_add_u32 s40, s42, 0x40000
	s_addc_u32 s41, s43, 0
	s_add_i32 s69, s63, s25
	s_mov_b32 m0, s69
	s_nop 0
	global_load_lds_dwordx4 v170, s[40:41]
	s_add_i32 m0, s69, 0x2000
	s_nop 0
	global_load_lds_dwordx4 v182, s[40:41]
	s_mov_b64 s[40:41], s[48:49]
	s_mov_b32 m0, s13
	s_nop 0
	global_load_lds_dwordx4 v9, s[40:41]
	s_mov_b32 m0, s51
	s_nop 0
	global_load_lds_dwordx4 v171, s[40:41]
	s_waitcnt vmcnt(8)
	s_waitcnt lgkmcnt(0)
	s_barrier
; #define PG8_STAGE(bufoff, gbase, voff) do { const char* gb_ = (const char*)(gbase); asm volatile("" : "+s"(gb_));     \
;         _Pragma("unroll") for (int _i = 0; _i < 2; ++_i) \
;         __builtin_amdgcn_global_load_lds((const unsigned*)(gb_ + (voff)[_i]), (PG8_LAS unsigned*)(lds + (bufoff) + ldsw + _i * 8192), 16, 0, 0); } while (0)
; #define PG8_LDA(dst, b, h) do { _Pragma("unroll") for (int m = 0; m < 4; ++m) _Pragma("unroll") for (int k = 0; k < 2; ++k) dst[m][k] = *(const PG8_LAS bf16x8*)(lds + PG8_SA(b, h) + aoff + m * 2048 + k * 1024); } while (0)
; #define PG8_LDB(dst, b, h) do { _Pragma("unroll") for (int n = 0; n < 2; ++n) _Pragma("unroll") for (int k = 0; k < 2; ++k) dst[n][k] = *(const PG8_LAS bf16x8*)(lds + PG8_SB(b, h) + boff + n * 2048 + k * 1024); } while (0)
; #define PG8_MMA(ai, bj, At, Bt) do { __builtin_amdgcn_s_setprio(1); _Pragma("unroll") for (int m = 0; m < 4; ++m) _Pragma("unroll") for (int n = 0; n < 2; ++n) _Pragma("unroll") for (int k = 0; k < 2; ++k) \
;         acc[ai][bj][m][n] = __builtin_amdgcn_mfma_f32_16x16x32_bf16(Bt[n][k], At[m][k], acc[ai][bj][m][n], 0, 0, 0); __builtin_amdgcn_s_setprio(0); } while (0)
; template <class Epi, class Sched, bool ALIGN_EPI = false, bool SP2 = false>
; __device__ __forceinline__ void gemm_phase(PG8_LAS unsigned char* lds, const Gemm g, const Sched& S, const Epi& E, int wid0) {
;     ...
;             PG8_LDB(B0, 0, 0); PG8_LDB(B1, 0, 1); PG8_SCHED; PG8_LDA(At, 0, 0); PG8_STAGE(PG8_SA(1, 1), a1 + hstepA, vA_);
;             PG8_WAIT_V(8); PG8_WAIT_L(0); PG8_BAR; PG8_MMA(0, 0, At, B0); PG8_MMA(0, 1, At, B1); PG8_BAR; PG8_SCHED;
;             PG8_LDA(At, 0, 1); PG8_STAGE(PG8_SB(0, 0), b2, vB_); PG8_STAGE(PG8_SB(0, 1), b2 + hstep, vB_); PG8_STAGE(PG8_SA(0, 0), a2, vA_);
;             PG8_WAIT_V(8); PG8_WAIT_L(0); PG8_BAR; PG8_MMA(1, 0, At, B0); PG8_MMA(1, 1, At, B1); PG8_BAR; PG8_SCHED;
;             PG8_LDB(B0, 1, 0); PG8_LDB(B1, 1, 1); PG8_SCHED; PG8_LDA(At, 1, 0); PG8_STAGE(PG8_SA(0, 1), a2 + hstepA, vA_);
;             PG8_WAIT_V(8); PG8_WAIT_L(0); PG8_BAR; PG8_MMA(0, 0, At, B0); PG8_MMA(0, 1, At, B1); PG8_BAR; PG8_SCHED;
;             PG8_LDA(At, 1, 1); PG8_STAGE(PG8_SB(1, 0), b3, vB_); PG8_STAGE(PG8_SB(1, 1), b3 + hstep, vB_); PG8_STAGE(PG8_SA(1, 0), a3, vA_);
;             PG8_WAIT_V(8); PG8_WAIT_L(0); PG8_BAR; PG8_MMA(1, 0, At, B0); PG8_MMA(1, 1, At, B1); PG8_BAR; PG8_SCHED;
	s_setprio 1
	s_waitcnt lgkmcnt(0)
	v_mfma_f32_16x16x32_bf16 v[104:107], v[142:145], v[188:191], v[104:107]
	v_mfma_f32_16x16x32_bf16 v[100:103], v[150:153], v[188:191], v[100:103]
	v_mfma_f32_16x16x32_bf16 v[96:99], v[142:145], v[196:199], v[96:99]
	v_mfma_f32_16x16x32_bf16 v[92:95], v[150:153], v[196:199], v[92:95]
	v_mfma_f32_16x16x32_bf16 v[88:91], v[142:145], v[204:207], v[88:91]
	v_mfma_f32_16x16x32_bf16 v[84:87], v[150:153], v[204:207], v[84:87]
	v_mfma_f32_16x16x32_bf16 v[80:83], v[142:145], v[212:215], v[80:83]
	v_mfma_f32_16x16x32_bf16 v[76:79], v[150:153], v[212:215], v[76:79]
	v_mfma_f32_16x16x32_bf16 v[104:107], v[146:149], v[192:195], v[104:107]
	v_mfma_f32_16x16x32_bf16 v[100:103], v[154:157], v[192:195], v[100:103]
	v_mfma_f32_16x16x32_bf16 v[96:99], v[146:149], v[200:203], v[96:99]
	v_mfma_f32_16x16x32_bf16 v[92:95], v[154:157], v[200:203], v[92:95]
	v_mfma_f32_16x16x32_bf16 v[88:91], v[146:149], v[208:211], v[88:91]
	v_mfma_f32_16x16x32_bf16 v[84:87], v[154:157], v[208:211], v[84:87]
	v_mfma_f32_16x16x32_bf16 v[80:83], v[146:149], v[216:219], v[80:83]
	v_mfma_f32_16x16x32_bf16 v[76:79], v[154:157], v[216:219], v[76:79]
	s_setprio 0
	s_setprio 1
	v_mfma_f32_16x16x32_bf16 v[40:43], v[158:161], v[188:191], v[40:43]
	v_mfma_f32_16x16x32_bf16 v[36:39], v[166:169], v[188:191], v[36:39]
	v_mfma_f32_16x16x32_bf16 v[32:35], v[158:161], v[196:199], v[32:35]
	v_mfma_f32_16x16x32_bf16 v[28:31], v[166:169], v[196:199], v[28:31]
	v_mfma_f32_16x16x32_bf16 v[24:27], v[158:161], v[204:207], v[24:27]
	v_mfma_f32_16x16x32_bf16 v[20:23], v[166:169], v[204:207], v[20:23]
	v_mfma_f32_16x16x32_bf16 v[16:19], v[158:161], v[212:215], v[16:19]
	v_mfma_f32_16x16x32_bf16 v[10:13], v[166:169], v[212:215], v[12:15]
	v_mfma_f32_16x16x32_bf16 v[40:43], v[162:165], v[192:195], v[40:43]
	v_mfma_f32_16x16x32_bf16 v[36:39], v[184:187], v[192:195], v[36:39]
	v_mfma_f32_16x16x32_bf16 v[32:35], v[162:165], v[200:203], v[32:35]
	v_mfma_f32_16x16x32_bf16 v[28:31], v[184:187], v[200:203], v[28:31]
	v_mfma_f32_16x16x32_bf16 v[24:27], v[162:165], v[208:211], v[24:27]
	v_mfma_f32_16x16x32_bf16 v[20:23], v[184:187], v[208:211], v[20:23]
	v_mfma_f32_16x16x32_bf16 v[16:19], v[162:165], v[216:219], v[16:19]
	v_mfma_f32_16x16x32_bf16 v[10:13], v[184:187], v[216:219], v[10:13]
	s_setprio 0
	s_barrier
	s_add_i32 s69, 0, 0x18000
	v_add_u32_e32 v14, s69, v173
	s_add_i32 s70, 0, 0x1c000
	ds_read_b128 v[142:145], v14
	ds_read_b128 v[146:149], v14 offset:1024
	ds_read_b128 v[150:153], v14 offset:2048
	ds_read_b128 v[154:157], v14 offset:3072
	v_add_u32_e32 v14, s70, v173
	ds_read_b128 v[158:161], v14
	ds_read_b128 v[162:165], v14 offset:1024
	ds_read_b128 v[166:169], v14 offset:2048
	ds_read_b128 v[184:187], v14 offset:3072
	s_add_u32 s40, s48, 0x80000
	s_addc_u32 s41, s49, 0
	s_mov_b32 m0, s52
	ds_read_b128 v[188:191], v183 offset:32768
	ds_read_b128 v[192:195], v183 offset:33792
	ds_read_b128 v[196:199], v183 offset:34816
	ds_read_b128 v[200:203], v183 offset:35840
	ds_read_b128 v[204:207], v183 offset:36864
	ds_read_b128 v[208:211], v183 offset:37888
	ds_read_b128 v[212:215], v183 offset:38912
	ds_read_b128 v[216:219], v183 offset:39936
	s_nop 0
	global_load_lds_dwordx4 v9, s[40:41]
	s_mov_b32 m0, s53
	s_nop 0
	global_load_lds_dwordx4 v171, s[40:41]
	s_waitcnt vmcnt(8)
	s_waitcnt lgkmcnt(0)
	s_barrier
	s_setprio 1
	s_waitcnt lgkmcnt(0)
	v_mfma_f32_16x16x32_bf16 v[136:139], v[142:145], v[188:191], v[136:139]
	v_mfma_f32_16x16x32_bf16 v[132:135], v[150:153], v[188:191], v[132:135]
	v_mfma_f32_16x16x32_bf16 v[128:131], v[142:145], v[196:199], v[128:131]
	v_mfma_f32_16x16x32_bf16 v[124:127], v[150:153], v[196:199], v[124:127]
	v_mfma_f32_16x16x32_bf16 v[120:123], v[142:145], v[204:207], v[120:123]
	v_mfma_f32_16x16x32_bf16 v[116:119], v[150:153], v[204:207], v[116:119]
	v_mfma_f32_16x16x32_bf16 v[112:115], v[142:145], v[212:215], v[112:115]
	v_mfma_f32_16x16x32_bf16 v[108:111], v[150:153], v[212:215], v[108:111]
	v_mfma_f32_16x16x32_bf16 v[136:139], v[146:149], v[192:195], v[136:139]
	v_mfma_f32_16x16x32_bf16 v[132:135], v[154:157], v[192:195], v[132:135]
	v_mfma_f32_16x16x32_bf16 v[128:131], v[146:149], v[200:203], v[128:131]
	v_mfma_f32_16x16x32_bf16 v[124:127], v[154:157], v[200:203], v[124:127]
	v_mfma_f32_16x16x32_bf16 v[120:123], v[146:149], v[208:211], v[120:123]
	v_mfma_f32_16x16x32_bf16 v[116:119], v[154:157], v[208:211], v[116:119]
	v_mfma_f32_16x16x32_bf16 v[112:115], v[146:149], v[216:219], v[112:115]
	v_mfma_f32_16x16x32_bf16 v[108:111], v[154:157], v[216:219], v[108:111]
	s_setprio 0
	s_setprio 1
	v_mfma_f32_16x16x32_bf16 v[72:75], v[158:161], v[188:191], v[72:75]
	v_mfma_f32_16x16x32_bf16 v[68:71], v[166:169], v[188:191], v[68:71]
	v_mfma_f32_16x16x32_bf16 v[64:67], v[158:161], v[196:199], v[64:67]
	v_mfma_f32_16x16x32_bf16 v[60:63], v[166:169], v[196:199], v[60:63]
	v_mfma_f32_16x16x32_bf16 v[56:59], v[158:161], v[204:207], v[56:59]
	v_mfma_f32_16x16x32_bf16 v[52:55], v[166:169], v[204:207], v[52:55]
	v_mfma_f32_16x16x32_bf16 v[48:51], v[158:161], v[212:215], v[48:51]
	v_mfma_f32_16x16x32_bf16 v[44:47], v[166:169], v[212:215], v[44:47]
	v_mfma_f32_16x16x32_bf16 v[72:75], v[162:165], v[192:195], v[72:75]
	v_mfma_f32_16x16x32_bf16 v[68:71], v[184:187], v[192:195], v[68:71]
	v_mfma_f32_16x16x32_bf16 v[64:67], v[162:165], v[200:203], v[64:67]
	v_mfma_f32_16x16x32_bf16 v[60:63], v[184:187], v[200:203], v[60:63]
	v_mfma_f32_16x16x32_bf16 v[56:59], v[162:165], v[208:211], v[56:59]
	v_mfma_f32_16x16x32_bf16 v[52:55], v[184:187], v[208:211], v[52:55]
	v_mfma_f32_16x16x32_bf16 v[48:51], v[162:165], v[216:219], v[48:51]
	v_mfma_f32_16x16x32_bf16 v[44:47], v[184:187], v[216:219], v[44:47]
	s_setprio 0
	s_barrier
;     __device__ float mid(int row) const { return rg(row) / ra(row); }
; #define PG8_STAGE(bufoff, gbase, voff) do { const char* gb_ = (const char*)(gbase); asm volatile("" : "+s"(gb_));     \
;         _Pragma("unroll") for (int _i = 0; _i < 2; ++_i) \
;         __builtin_amdgcn_global_load_lds((const unsigned*)(gb_ + (voff)[_i]), (PG8_LAS unsigned*)(lds + (bufoff) + ldsw + _i * 8192), 16, 0, 0); } while (0)
; #define PG8_LDA(dst, b, h) do { _Pragma("unroll") for (int m = 0; m < 4; ++m) _Pragma("unroll") for (int k = 0; k < 2; ++k) dst[m][k] = *(const PG8_LAS bf16x8*)(lds + PG8_SA(b, h) + aoff + m * 2048 + k * 1024); } while (0)
; #define PG8_WAIT_V(n) asm volatile("s_waitcnt vmcnt(" #n ")" ::: "memory")
; #define PG8_WAIT_L(n) asm volatile("s_waitcnt lgkmcnt(" #n ")" ::: "memory")
; template <class Epi, class Sched, bool ALIGN_EPI = false, bool SP2 = false>
; __device__ __forceinline__ void gemm_phase(PG8_LAS unsigned char* lds, const Gemm g, const Sched& S, const Epi& E, int wid0) {
;     ...
;             if constexpr (Epi::HAS_MID) { if (t == Epi::MID_T) E.mid(acc, cur, wr, fr); }
;             unsigned vA_[2] = {voffA[0], voffA[1]}, vB_[2] = {voffB[0], voffB[1]};
;             asm volatile("" : "+v"(vA_[0]), "+v"(vA_[1]), "+v"(vB_[0]), "+v"(vB_[1]));
;             if constexpr (SP2) {
;             PG8_LDB(B0, 0, 0); PG8_LDB(B1, 0, 1); PG8_SCHED; PG8_LDA(At, 0, 0); PG8_STAGE(PG8_SA(1, 1), a1 + hstepA, vA_);
;             PG8_WAIT_V(8); PG8_WAIT_L(0); PG8_BAR; PG8_MMA(0, 0, At, B0); PG8_MMA(0, 1, At, B1); PG8_BAR; PG8_SCHED;
;             PG8_LDA(At, 0, 1); PG8_STAGE(PG8_SB(0, 0), b2, vB_); PG8_STAGE(PG8_SB(0, 1), b2 + hstep, vB_); PG8_STAGE(PG8_SA(0, 0), a2, vA_);
;             PG8_WAIT_V(8); PG8_WAIT_L(0); PG8_BAR; PG8_MMA(1, 0, At, B0); PG8_MMA(1, 1, At, B1); PG8_BAR; PG8_SCHED;
;             PG8_LDB(B0, 1, 0); PG8_LDB(B1, 1, 1); PG8_SCHED; PG8_LDA(At, 1, 0); PG8_STAGE(PG8_SA(0, 1), a2 + hstepA, vA_);
;             PG8_WAIT_V(8); PG8_WAIT_L(0); PG8_BAR; PG8_MMA(0, 0, At, B0); PG8_MMA(0, 1, At, B1); PG8_BAR; PG8_SCHED;
;             PG8_LDA(At, 1, 1); PG8_STAGE(PG8_SB(1, 0), b3, vB_); PG8_STAGE(PG8_SB(1, 1), b3 + hstep, vB_); PG8_STAGE(PG8_SA(1, 0), a3, vA_);
;             PG8_WAIT_V(8); PG8_WAIT_L(0); PG8_BAR; PG8_MMA(1, 0, At, B0); PG8_MMA(1, 1, At, B1); PG8_BAR; PG8_SCHED;
;     ...
;         if constexpr (ALIGN_EPI) { if (wr == 0) PG8_BAR; }
	s_add_i32 s40, s69, s25
	s_mov_b32 m0, s40
	ds_read_b128 v[188:191], v183 offset:49152
	ds_read_b128 v[192:195], v183 offset:50176
	ds_read_b128 v[196:199], v183 offset:51200
	ds_read_b128 v[200:203], v183 offset:52224
	ds_read_b128 v[204:207], v183 offset:53248
	ds_read_b128 v[208:211], v183 offset:54272
	ds_read_b128 v[212:215], v183 offset:55296
	ds_read_b128 v[216:219], v183 offset:56320
	s_nop 0
	global_load_lds_dwordx4 v170, s[46:47]
	s_add_i32 m0, s40, 0x2000
	s_add_u32 s40, s42, 0x40080
	s_addc_u32 s41, s43, 0
	s_add_i32 s42, s70, s25
	global_load_lds_dwordx4 v182, s[46:47]
	s_mov_b32 m0, s42
	s_nop 0
	global_load_lds_dwordx4 v170, s[40:41]
	s_add_i32 m0, s42, 0x2000
	s_nop 0
	global_load_lds_dwordx4 v182, s[40:41]
	s_mov_b32 m0, s57
	s_nop 0
	global_load_lds_dwordx4 v9, s[44:45]
	s_mov_b32 m0, s58
	s_nop 0
	global_load_lds_dwordx4 v171, s[44:45]
	s_waitcnt vmcnt(8)
	s_waitcnt lgkmcnt(0)
	s_barrier
	s_setprio 1
	s_waitcnt lgkmcnt(0)
	v_mfma_f32_16x16x32_bf16 v[104:107], v[142:145], v[188:191], v[104:107]
	v_mfma_f32_16x16x32_bf16 v[100:103], v[150:153], v[188:191], v[100:103]
	v_mfma_f32_16x16x32_bf16 v[96:99], v[142:145], v[196:199], v[96:99]
	v_mfma_f32_16x16x32_bf16 v[92:95], v[150:153], v[196:199], v[92:95]
	v_mfma_f32_16x16x32_bf16 v[88:91], v[142:145], v[204:207], v[88:91]
	v_mfma_f32_16x16x32_bf16 v[84:87], v[150:153], v[204:207], v[84:87]
	v_mfma_f32_16x16x32_bf16 v[80:83], v[142:145], v[212:215], v[80:83]
	v_mfma_f32_16x16x32_bf16 v[76:79], v[150:153], v[212:215], v[76:79]
	v_mfma_f32_16x16x32_bf16 v[104:107], v[146:149], v[192:195], v[104:107]
	v_mfma_f32_16x16x32_bf16 v[100:103], v[154:157], v[192:195], v[100:103]
	v_mfma_f32_16x16x32_bf16 v[96:99], v[146:149], v[200:203], v[96:99]
	v_mfma_f32_16x16x32_bf16 v[92:95], v[154:157], v[200:203], v[92:95]
	v_mfma_f32_16x16x32_bf16 v[88:91], v[146:149], v[208:211], v[88:91]
	v_mfma_f32_16x16x32_bf16 v[84:87], v[154:157], v[208:211], v[84:87]
	v_mfma_f32_16x16x32_bf16 v[80:83], v[146:149], v[216:219], v[80:83]
	v_mfma_f32_16x16x32_bf16 v[76:79], v[154:157], v[216:219], v[76:79]
	s_setprio 0
	s_setprio 1
	v_mfma_f32_16x16x32_bf16 v[40:43], v[158:161], v[188:191], v[40:43]
	v_mfma_f32_16x16x32_bf16 v[36:39], v[166:169], v[188:191], v[36:39]
	v_mfma_f32_16x16x32_bf16 v[32:35], v[158:161], v[196:199], v[32:35]
	v_mfma_f32_16x16x32_bf16 v[28:31], v[166:169], v[196:199], v[28:31]
	v_mfma_f32_16x16x32_bf16 v[24:27], v[158:161], v[204:207], v[24:27]
	v_mfma_f32_16x16x32_bf16 v[20:23], v[166:169], v[204:207], v[20:23]
	v_mfma_f32_16x16x32_bf16 v[14:17], v[158:161], v[212:215], v[16:19]
	v_mfma_f32_16x16x32_bf16 v[10:13], v[166:169], v[212:215], v[10:13]
	v_mfma_f32_16x16x32_bf16 v[40:43], v[162:165], v[192:195], v[40:43]
	v_mfma_f32_16x16x32_bf16 v[36:39], v[184:187], v[192:195], v[36:39]
	v_mfma_f32_16x16x32_bf16 v[32:35], v[162:165], v[200:203], v[32:35]
	v_mfma_f32_16x16x32_bf16 v[28:31], v[184:187], v[200:203], v[28:31]
	s_add_i32 s68, s68, 2
	s_add_u32 s66, s66, 0x100
	s_addc_u32 s67, s67, 0
	s_cmp_gt_u32 s68, 13
	v_mfma_f32_16x16x32_bf16 v[24:27], v[162:165], v[208:211], v[24:27]
	v_mfma_f32_16x16x32_bf16 v[20:23], v[184:187], v[208:211], v[20:23]
	v_mfma_f32_16x16x32_bf16 v[16:19], v[162:165], v[216:219], v[14:17]
	v_mfma_f32_16x16x32_bf16 v[12:15], v[184:187], v[216:219], v[10:13]
	s_setprio 0
	s_barrier
	s_cbranch_scc1 .LBB13_1922
	s_mov_b64 s[40:41], s[6:7]
	s_cmp_lg_u32 s68, 6
	s_cbranch_scc0 .LBB13_1919
	s_branch .LBB13_1920

;     __device__ float mid(int row) const { return rg(row) / ra(row); }
; #define PG8_STAGE(bufoff, gbase, voff) do { const char* gb_ = (const char*)(gbase); asm volatile("" : "+s"(gb_));     \
;         _Pragma("unroll") for (int _i = 0; _i < 2; ++_i) \
;         __builtin_amdgcn_global_load_lds((const unsigned*)(gb_ + (voff)[_i]), (PG8_LAS unsigned*)(lds + (bufoff) + ldsw + _i * 8192), 16, 0, 0); } while (0)
; #define PG8_BAR __builtin_amdgcn_s_barrier()
; template <class Epi, class Sched, bool ALIGN_EPI = false, bool SP2 = false>
; __device__ __forceinline__ void gemm_phase(PG8_LAS unsigned char* lds, const Gemm g, const Sched& S, const Epi& E, int wid0) {
;     ...
;         for (int t = 0; t < nt; t += 2) {
;             const bool last = (t == nt - 2);
;             const char* a1 = cA + (size_t)(t + 1) * kstep;
;             const char* a2 = last ? nA : cA + (size_t)(t + 2) * kstep; const char* b2 = last ? nB : cB + (size_t)(t + 2) * kstep;
;             const char* a3 = a2 + kstep; const char* b3 = b2 + kstep;
;             if (last && has_next) S.a_ready(nxt);
;             if constexpr (Epi::HAS_MID) { if (t == Epi::MID_T) E.mid(acc, cur, wr, fr); }
;             unsigned vA_[2] = {voffA[0], voffA[1]}, vB_[2] = {voffB[0], voffB[1]};
;             asm volatile("" : "+v"(vA_[0]), "+v"(vA_[1]), "+v"(vB_[0]), "+v"(vB_[1]));
;             if constexpr (SP2) {
;             PG8_LDB(B0, 0, 0); PG8_LDB(B1, 0, 1); PG8_SCHED; PG8_LDA(At, 0, 0); PG8_STAGE(PG8_SA(1, 1), a1 + hstepA, vA_);
;             PG8_WAIT_V(8); PG8_WAIT_L(0); PG8_BAR; PG8_MMA(0, 0, At, B0); PG8_MMA(0, 1, At, B1); PG8_BAR; PG8_SCHED;
;             PG8_LDA(At, 0, 1); PG8_STAGE(PG8_SB(0, 0), b2, vB_); PG8_STAGE(PG8_SB(0, 1), b2 + hstep, vB_); PG8_STAGE(PG8_SA(0, 0), a2, vA_);
;             PG8_WAIT_V(8); PG8_WAIT_L(0); PG8_BAR; PG8_MMA(1, 0, At, B0); PG8_MMA(1, 1, At, B1); PG8_BAR; PG8_SCHED;
;             PG8_LDB(B0, 1, 0); PG8_LDB(B1, 1, 1); PG8_SCHED; PG8_LDA(At, 1, 0); PG8_STAGE(PG8_SA(0, 1), a2 + hstepA, vA_);
;             PG8_WAIT_V(8); PG8_WAIT_L(0); PG8_BAR; PG8_MMA(0, 0, At, B0); PG8_MMA(0, 1, At, B1); PG8_BAR; PG8_SCHED;
;             PG8_LDA(At, 1, 1); PG8_STAGE(PG8_SB(1, 0), b3, vB_); PG8_STAGE(PG8_SB(1, 1), b3 + hstep, vB_); PG8_STAGE(PG8_SA(1, 0), a3, vA_);
;             PG8_WAIT_V(8); PG8_WAIT_L(0); PG8_BAR; PG8_MMA(1, 0, At, B0); PG8_MMA(1, 1, At, B1); PG8_BAR; PG8_SCHED;
.LBB13_2163:
	v_mov_b32_e32 v202, v150
	v_mov_b32_e32 v203, v152
	v_mov_b32_e32 v204, v154
	v_mov_b32_e32 v205, v148
	ds_read_b128 v[128:131], v153
	ds_read_b128 v[132:135], v153 offset:1024
	ds_read_b128 v[136:139], v153 offset:2048
	ds_read_b128 v[140:143], v153 offset:3072
	ds_read_b128 v[144:147], v155
	ds_read_b128 v[158:161], v155 offset:1024
	ds_read_b128 v[162:165], v155 offset:2048
	ds_read_b128 v[166:169], v155 offset:3072
	s_add_u32 s26, s24, 0x100
	s_addc_u32 s27, s25, 0
	s_cmp_eq_u32 s53, 60
	s_cselect_b32 s34, s49, s26
	s_cselect_b32 s35, s11, s27
	s_cselect_b32 s30, s50, s51
	s_cselect_b32 s31, s13, s52
	s_add_u32 s28, s34, 0x80
	s_addc_u32 s29, s35, 0
	s_add_u32 s24, s24, 0x100080
	s_addc_u32 s25, s25, 0
	s_add_i32 m0, s21, 0xc000
	ds_read_b128 v[170:173], v156
	ds_read_b128 v[174:177], v156 offset:1024
	ds_read_b128 v[178:181], v156 offset:2048
	ds_read_b128 v[182:185], v156 offset:3072
	ds_read_b128 v[186:189], v156 offset:4096
	ds_read_b128 v[190:193], v156 offset:5120
	ds_read_b128 v[194:197], v156 offset:6144
	ds_read_b128 v[198:201], v156 offset:7168
	s_nop 0
	global_load_lds_dwordx4 v205, s[24:25]
	s_add_i32 m0, s21, 0xe000
	s_nop 0
	global_load_lds_dwordx4 v203, s[24:25]
	s_waitcnt vmcnt(8)
	s_waitcnt lgkmcnt(0)
	s_barrier
	s_setprio 1
	s_waitcnt lgkmcnt(0)
	v_mfma_f32_16x16x32_bf16 v[124:127], v[128:131], v[170:173], v[124:127]
	v_mfma_f32_16x16x32_bf16 v[120:123], v[136:139], v[170:173], v[120:123]
	v_mfma_f32_16x16x32_bf16 v[116:119], v[128:131], v[178:181], v[116:119]
	v_mfma_f32_16x16x32_bf16 v[112:115], v[136:139], v[178:181], v[112:115]
	v_mfma_f32_16x16x32_bf16 v[108:111], v[128:131], v[186:189], v[108:111]
	v_mfma_f32_16x16x32_bf16 v[104:107], v[136:139], v[186:189], v[104:107]
	v_mfma_f32_16x16x32_bf16 v[100:103], v[128:131], v[194:197], v[100:103]
	v_mfma_f32_16x16x32_bf16 v[96:99], v[136:139], v[194:197], v[96:99]
	v_mfma_f32_16x16x32_bf16 v[124:127], v[132:135], v[174:177], v[124:127]
	v_mfma_f32_16x16x32_bf16 v[120:123], v[140:143], v[174:177], v[120:123]
	v_mfma_f32_16x16x32_bf16 v[116:119], v[132:135], v[182:185], v[116:119]
	v_mfma_f32_16x16x32_bf16 v[112:115], v[140:143], v[182:185], v[112:115]
	v_mfma_f32_16x16x32_bf16 v[108:111], v[132:135], v[190:193], v[108:111]
	v_mfma_f32_16x16x32_bf16 v[104:107], v[140:143], v[190:193], v[104:107]
	v_mfma_f32_16x16x32_bf16 v[100:103], v[132:135], v[198:201], v[100:103]
	v_mfma_f32_16x16x32_bf16 v[96:99], v[140:143], v[198:201], v[96:99]
	s_setprio 0
	s_setprio 1
	v_mfma_f32_16x16x32_bf16 v[60:63], v[144:147], v[170:173], v[60:63]
	v_mfma_f32_16x16x32_bf16 v[56:59], v[162:165], v[170:173], v[56:59]
	v_mfma_f32_16x16x32_bf16 v[52:55], v[144:147], v[178:181], v[52:55]
	v_mfma_f32_16x16x32_bf16 v[48:51], v[162:165], v[178:181], v[48:51]
	v_mfma_f32_16x16x32_bf16 v[44:47], v[144:147], v[186:189], v[44:47]
	v_mfma_f32_16x16x32_bf16 v[40:43], v[162:165], v[186:189], v[40:43]
	v_mfma_f32_16x16x32_bf16 v[36:39], v[144:147], v[194:197], v[36:39]
	v_mfma_f32_16x16x32_bf16 v[32:35], v[162:165], v[194:197], v[32:35]
	v_mfma_f32_16x16x32_bf16 v[60:63], v[158:161], v[174:177], v[60:63]
	v_mfma_f32_16x16x32_bf16 v[56:59], v[166:169], v[174:177], v[56:59]
	v_mfma_f32_16x16x32_bf16 v[52:55], v[158:161], v[182:185], v[52:55]
	v_mfma_f32_16x16x32_bf16 v[48:51], v[166:169], v[182:185], v[48:51]
	v_mfma_f32_16x16x32_bf16 v[44:47], v[158:161], v[190:193], v[44:47]
	v_mfma_f32_16x16x32_bf16 v[40:43], v[166:169], v[190:193], v[40:43]
	v_mfma_f32_16x16x32_bf16 v[36:39], v[158:161], v[198:201], v[36:39]
	v_mfma_f32_16x16x32_bf16 v[32:35], v[166:169], v[198:201], v[32:35]
	s_setprio 0
	s_barrier
	s_add_i32 s54, s47, s33
	s_mov_b64 s[24:25], s[30:31]
	s_mov_b32 m0, s54
	ds_read_b128 v[170:173], v156 offset:16384
	ds_read_b128 v[174:177], v156 offset:17408
	ds_read_b128 v[178:181], v156 offset:18432
	ds_read_b128 v[182:185], v156 offset:19456
	ds_read_b128 v[186:189], v156 offset:20480
	ds_read_b128 v[190:193], v156 offset:21504
	ds_read_b128 v[194:197], v156 offset:22528
	ds_read_b128 v[198:201], v156 offset:23552
	s_nop 0
	global_load_lds_dwordx4 v202, s[24:25]
	s_add_i32 m0, s54, 0x2000
	s_nop 0
	global_load_lds_dwordx4 v204, s[24:25]
	s_add_u32 s24, s30, 0x100000
	s_addc_u32 s25, s31, 0
	s_add_i32 s54, s48, s33
	s_mov_b32 m0, s54
	s_nop 0
	global_load_lds_dwordx4 v202, s[24:25]
	s_add_i32 m0, s54, 0x2000
	s_nop 0
	global_load_lds_dwordx4 v204, s[24:25]
	s_mov_b64 s[24:25], s[34:35]
	s_mov_b32 m0, s21
	s_nop 0
	global_load_lds_dwordx4 v205, s[24:25]
	s_mov_b32 m0, s23
	s_nop 0
	global_load_lds_dwordx4 v203, s[24:25]
	s_waitcnt vmcnt(8)
	s_waitcnt lgkmcnt(0)
	s_barrier
; #define PG8_STAGE(bufoff, gbase, voff) do { const char* gb_ = (const char*)(gbase); asm volatile("" : "+s"(gb_));     \
;         _Pragma("unroll") for (int _i = 0; _i < 2; ++_i) \
;         __builtin_amdgcn_global_load_lds((const unsigned*)(gb_ + (voff)[_i]), (PG8_LAS unsigned*)(lds + (bufoff) + ldsw + _i * 8192), 16, 0, 0); } while (0)
; #define PG8_LDA(dst, b, h) do { _Pragma("unroll") for (int m = 0; m < 4; ++m) _Pragma("unroll") for (int k = 0; k < 2; ++k) dst[m][k] = *(const PG8_LAS bf16x8*)(lds + PG8_SA(b, h) + aoff + m * 2048 + k * 1024); } while (0)
; #define PG8_LDB(dst, b, h) do { _Pragma("unroll") for (int n = 0; n < 2; ++n) _Pragma("unroll") for (int k = 0; k < 2; ++k) dst[n][k] = *(const PG8_LAS bf16x8*)(lds + PG8_SB(b, h) + boff + n * 2048 + k * 1024); } while (0)
; #define PG8_MMA(ai, bj, At, Bt) do { __builtin_amdgcn_s_setprio(1); _Pragma("unroll") for (int m = 0; m < 4; ++m) _Pragma("unroll") for (int n = 0; n < 2; ++n) _Pragma("unroll") for (int k = 0; k < 2; ++k) \
;         acc[ai][bj][m][n] = __builtin_amdgcn_mfma_f32_16x16x32_bf16(Bt[n][k], At[m][k], acc[ai][bj][m][n], 0, 0, 0); __builtin_amdgcn_s_setprio(0); } while (0)
; template <class Epi, class Sched, bool ALIGN_EPI = false, bool SP2 = false>
; __device__ __forceinline__ void gemm_phase(PG8_LAS unsigned char* lds, const Gemm g, const Sched& S, const Epi& E, int wid0) {
;     ...
;             PG8_LDB(B0, 0, 0); PG8_LDB(B1, 0, 1); PG8_SCHED; PG8_LDA(At, 0, 0); PG8_STAGE(PG8_SA(1, 1), a1 + hstepA, vA_);
;             PG8_WAIT_V(8); PG8_WAIT_L(0); PG8_BAR; PG8_MMA(0, 0, At, B0); PG8_MMA(0, 1, At, B1); PG8_BAR; PG8_SCHED;
;             PG8_LDA(At, 0, 1); PG8_STAGE(PG8_SB(0, 0), b2, vB_); PG8_STAGE(PG8_SB(0, 1), b2 + hstep, vB_); PG8_STAGE(PG8_SA(0, 0), a2, vA_);
;             PG8_WAIT_V(8); PG8_WAIT_L(0); PG8_BAR; PG8_MMA(1, 0, At, B0); PG8_MMA(1, 1, At, B1); PG8_BAR; PG8_SCHED;
;             PG8_LDB(B0, 1, 0); PG8_LDB(B1, 1, 1); PG8_SCHED; PG8_LDA(At, 1, 0); PG8_STAGE(PG8_SA(0, 1), a2 + hstepA, vA_);
;             PG8_WAIT_V(8); PG8_WAIT_L(0); PG8_BAR; PG8_MMA(0, 0, At, B0); PG8_MMA(0, 1, At, B1); PG8_BAR; PG8_SCHED;
;             PG8_LDA(At, 1, 1); PG8_STAGE(PG8_SB(1, 0), b3, vB_); PG8_STAGE(PG8_SB(1, 1), b3 + hstep, vB_); PG8_STAGE(PG8_SA(1, 0), a3, vA_);
;             PG8_WAIT_V(8); PG8_WAIT_L(0); PG8_BAR; PG8_MMA(1, 0, At, B0); PG8_MMA(1, 1, At, B1); PG8_BAR; PG8_SCHED;
	s_setprio 1
	s_waitcnt lgkmcnt(0)
	v_mfma_f32_16x16x32_bf16 v[92:95], v[128:131], v[170:173], v[92:95]
	v_mfma_f32_16x16x32_bf16 v[88:91], v[136:139], v[170:173], v[88:91]
	v_mfma_f32_16x16x32_bf16 v[84:87], v[128:131], v[178:181], v[84:87]
	v_mfma_f32_16x16x32_bf16 v[80:83], v[136:139], v[178:181], v[80:83]
	v_mfma_f32_16x16x32_bf16 v[76:79], v[128:131], v[186:189], v[76:79]
	v_mfma_f32_16x16x32_bf16 v[72:75], v[136:139], v[186:189], v[72:75]
	v_mfma_f32_16x16x32_bf16 v[68:71], v[128:131], v[194:197], v[68:71]
	v_mfma_f32_16x16x32_bf16 v[64:67], v[136:139], v[194:197], v[64:67]
	v_mfma_f32_16x16x32_bf16 v[92:95], v[132:135], v[174:177], v[92:95]
	v_mfma_f32_16x16x32_bf16 v[88:91], v[140:143], v[174:177], v[88:91]
	v_mfma_f32_16x16x32_bf16 v[84:87], v[132:135], v[182:185], v[84:87]
	v_mfma_f32_16x16x32_bf16 v[80:83], v[140:143], v[182:185], v[80:83]
	v_mfma_f32_16x16x32_bf16 v[76:79], v[132:135], v[190:193], v[76:79]
	v_mfma_f32_16x16x32_bf16 v[72:75], v[140:143], v[190:193], v[72:75]
	v_mfma_f32_16x16x32_bf16 v[68:71], v[132:135], v[198:201], v[68:71]
	v_mfma_f32_16x16x32_bf16 v[64:67], v[140:143], v[198:201], v[64:67]
	s_setprio 0
	s_setprio 1
	v_mfma_f32_16x16x32_bf16 v[28:31], v[144:147], v[170:173], v[28:31]
	v_mfma_f32_16x16x32_bf16 v[24:27], v[162:165], v[170:173], v[24:27]
	v_mfma_f32_16x16x32_bf16 v[20:23], v[144:147], v[178:181], v[20:23]
	v_mfma_f32_16x16x32_bf16 v[16:19], v[162:165], v[178:181], v[16:19]
	v_mfma_f32_16x16x32_bf16 v[12:15], v[144:147], v[186:189], v[12:15]
	v_mfma_f32_16x16x32_bf16 v[8:11], v[162:165], v[186:189], v[8:11]
	v_mfma_f32_16x16x32_bf16 v[4:7], v[144:147], v[194:197], v[4:7]
	v_mfma_f32_16x16x32_bf16 v[0:3], v[162:165], v[194:197], v[0:3]
	v_mfma_f32_16x16x32_bf16 v[28:31], v[158:161], v[174:177], v[28:31]
	v_mfma_f32_16x16x32_bf16 v[24:27], v[166:169], v[174:177], v[24:27]
	v_mfma_f32_16x16x32_bf16 v[20:23], v[158:161], v[182:185], v[20:23]
	v_mfma_f32_16x16x32_bf16 v[16:19], v[166:169], v[182:185], v[16:19]
	v_mfma_f32_16x16x32_bf16 v[12:15], v[158:161], v[190:193], v[12:15]
	v_mfma_f32_16x16x32_bf16 v[8:11], v[166:169], v[190:193], v[8:11]
	v_mfma_f32_16x16x32_bf16 v[4:7], v[158:161], v[198:201], v[4:7]
	v_mfma_f32_16x16x32_bf16 v[0:3], v[166:169], v[198:201], v[0:3]
	s_setprio 0
	s_barrier
	s_add_i32 s54, 0, 0x18000
	s_add_i32 s55, 0, 0x1c000
	v_add_u32_e32 v140, s54, v149
	v_add_u32_e32 v166, s55, v149
	ds_read_b128 v[128:131], v140
	ds_read_b128 v[132:135], v140 offset:1024
	ds_read_b128 v[136:139], v140 offset:2048
	ds_read_b128 v[140:143], v140 offset:3072
	ds_read_b128 v[144:147], v166
	ds_read_b128 v[158:161], v166 offset:1024
	ds_read_b128 v[162:165], v166 offset:2048
	ds_read_b128 v[166:169], v166 offset:3072
	s_add_u32 s24, s34, 0x100000
	s_addc_u32 s25, s35, 0
	s_mov_b32 m0, s40
	ds_read_b128 v[170:173], v156 offset:32768
	ds_read_b128 v[174:177], v156 offset:33792
	ds_read_b128 v[178:181], v156 offset:34816
	ds_read_b128 v[182:185], v156 offset:35840
	ds_read_b128 v[186:189], v156 offset:36864
	ds_read_b128 v[190:193], v156 offset:37888
	ds_read_b128 v[194:197], v156 offset:38912
	ds_read_b128 v[198:201], v156 offset:39936
	s_nop 0
	global_load_lds_dwordx4 v205, s[24:25]
	s_mov_b32 m0, s41
	s_nop 0
	global_load_lds_dwordx4 v203, s[24:25]
	s_waitcnt vmcnt(8)
	s_waitcnt lgkmcnt(0)
	s_barrier
	s_setprio 1
	s_waitcnt lgkmcnt(0)
	v_mfma_f32_16x16x32_bf16 v[124:127], v[128:131], v[170:173], v[124:127]
	v_mfma_f32_16x16x32_bf16 v[120:123], v[136:139], v[170:173], v[120:123]
	v_mfma_f32_16x16x32_bf16 v[116:119], v[128:131], v[178:181], v[116:119]
	v_mfma_f32_16x16x32_bf16 v[112:115], v[136:139], v[178:181], v[112:115]
	v_mfma_f32_16x16x32_bf16 v[108:111], v[128:131], v[186:189], v[108:111]
	v_mfma_f32_16x16x32_bf16 v[104:107], v[136:139], v[186:189], v[104:107]
	v_mfma_f32_16x16x32_bf16 v[100:103], v[128:131], v[194:197], v[100:103]
	v_mfma_f32_16x16x32_bf16 v[96:99], v[136:139], v[194:197], v[96:99]
	v_mfma_f32_16x16x32_bf16 v[124:127], v[132:135], v[174:177], v[124:127]
	v_mfma_f32_16x16x32_bf16 v[120:123], v[140:143], v[174:177], v[120:123]
	v_mfma_f32_16x16x32_bf16 v[116:119], v[132:135], v[182:185], v[116:119]
	v_mfma_f32_16x16x32_bf16 v[112:115], v[140:143], v[182:185], v[112:115]
	v_mfma_f32_16x16x32_bf16 v[108:111], v[132:135], v[190:193], v[108:111]
	v_mfma_f32_16x16x32_bf16 v[104:107], v[140:143], v[190:193], v[104:107]
	v_mfma_f32_16x16x32_bf16 v[100:103], v[132:135], v[198:201], v[100:103]
	v_mfma_f32_16x16x32_bf16 v[96:99], v[140:143], v[198:201], v[96:99]
	s_setprio 0
	s_setprio 1
	v_mfma_f32_16x16x32_bf16 v[60:63], v[144:147], v[170:173], v[60:63]
	v_mfma_f32_16x16x32_bf16 v[56:59], v[162:165], v[170:173], v[56:59]
	v_mfma_f32_16x16x32_bf16 v[52:55], v[144:147], v[178:181], v[52:55]
	v_mfma_f32_16x16x32_bf16 v[48:51], v[162:165], v[178:181], v[48:51]
	v_mfma_f32_16x16x32_bf16 v[44:47], v[144:147], v[186:189], v[44:47]
	v_mfma_f32_16x16x32_bf16 v[40:43], v[162:165], v[186:189], v[40:43]
	v_mfma_f32_16x16x32_bf16 v[36:39], v[144:147], v[194:197], v[36:39]
	v_mfma_f32_16x16x32_bf16 v[32:35], v[162:165], v[194:197], v[32:35]
	v_mfma_f32_16x16x32_bf16 v[60:63], v[158:161], v[174:177], v[60:63]
	v_mfma_f32_16x16x32_bf16 v[56:59], v[166:169], v[174:177], v[56:59]
	v_mfma_f32_16x16x32_bf16 v[52:55], v[158:161], v[182:185], v[52:55]
	v_mfma_f32_16x16x32_bf16 v[48:51], v[166:169], v[182:185], v[48:51]
	v_mfma_f32_16x16x32_bf16 v[44:47], v[158:161], v[190:193], v[44:47]
	v_mfma_f32_16x16x32_bf16 v[40:43], v[166:169], v[190:193], v[40:43]
	v_mfma_f32_16x16x32_bf16 v[36:39], v[158:161], v[198:201], v[36:39]
	v_mfma_f32_16x16x32_bf16 v[32:35], v[166:169], v[198:201], v[32:35]
	s_setprio 0
	s_barrier
; #define PG8_STAGE(bufoff, gbase, voff) do { const char* gb_ = (const char*)(gbase); asm volatile("" : "+s"(gb_));     \
;         _Pragma("unroll") for (int _i = 0; _i < 2; ++_i) \
;         __builtin_amdgcn_global_load_lds((const unsigned*)(gb_ + (voff)[_i]), (PG8_LAS unsigned*)(lds + (bufoff) + ldsw + _i * 8192), 16, 0, 0); } while (0)
; #define PG8_LDA(dst, b, h) do { _Pragma("unroll") for (int m = 0; m < 4; ++m) _Pragma("unroll") for (int k = 0; k < 2; ++k) dst[m][k] = *(const PG8_LAS bf16x8*)(lds + PG8_SA(b, h) + aoff + m * 2048 + k * 1024); } while (0)
; #define PG8_LDB(dst, b, h) do { _Pragma("unroll") for (int n = 0; n < 2; ++n) _Pragma("unroll") for (int k = 0; k < 2; ++k) dst[n][k] = *(const PG8_LAS bf16x8*)(lds + PG8_SB(b, h) + boff + n * 2048 + k * 1024); } while (0)
; #define PG8_WAIT_V(n) asm volatile("s_waitcnt vmcnt(" #n ")" ::: "memory")
; #define PG8_WAIT_L(n) asm volatile("s_waitcnt lgkmcnt(" #n ")" ::: "memory")
; #define PG8_BAR __builtin_amdgcn_s_barrier()
; #define PG8_SCHED __builtin_amdgcn_sched_barrier(0)
; template <class Epi, class Sched, bool ALIGN_EPI = false, bool SP2 = false>
; __device__ __forceinline__ void gemm_phase(PG8_LAS unsigned char* lds, const Gemm g, const Sched& S, const Epi& E, int wid0) {
;     ...
;             PG8_LDB(B0, 0, 0); PG8_LDB(B1, 0, 1); PG8_SCHED; PG8_LDA(At, 0, 0); PG8_STAGE(PG8_SA(1, 1), a1 + hstepA, vA_);
;             PG8_WAIT_V(8); PG8_WAIT_L(0); PG8_BAR; PG8_MMA(0, 0, At, B0); PG8_MMA(0, 1, At, B1); PG8_BAR; PG8_SCHED;
;             PG8_LDA(At, 0, 1); PG8_STAGE(PG8_SB(0, 0), b2, vB_); PG8_STAGE(PG8_SB(0, 1), b2 + hstep, vB_); PG8_STAGE(PG8_SA(0, 0), a2, vA_);
;             PG8_WAIT_V(8); PG8_WAIT_L(0); PG8_BAR; PG8_MMA(1, 0, At, B0); PG8_MMA(1, 1, At, B1); PG8_BAR; PG8_SCHED;
;             PG8_LDB(B0, 1, 0); PG8_LDB(B1, 1, 1); PG8_SCHED; PG8_LDA(At, 1, 0); PG8_STAGE(PG8_SA(0, 1), a2 + hstepA, vA_);
;             PG8_WAIT_V(8); PG8_WAIT_L(0); PG8_BAR; PG8_MMA(0, 0, At, B0); PG8_MMA(0, 1, At, B1); PG8_BAR; PG8_SCHED;
;             PG8_LDA(At, 1, 1); PG8_STAGE(PG8_SB(1, 0), b3, vB_); PG8_STAGE(PG8_SB(1, 1), b3 + hstep, vB_); PG8_STAGE(PG8_SA(1, 0), a3, vA_);
;             PG8_WAIT_V(8); PG8_WAIT_L(0); PG8_BAR; PG8_MMA(1, 0, At, B0); PG8_MMA(1, 1, At, B1); PG8_BAR; PG8_SCHED;
;     ...
;         if constexpr (ALIGN_EPI) { if (wr == 0) PG8_BAR; }
	s_add_u32 s24, s30, 0x80
	s_addc_u32 s25, s31, 0
	s_add_i32 s34, s54, s33
	s_mov_b32 m0, s34
	ds_read_b128 v[170:173], v156 offset:49152
	ds_read_b128 v[174:177], v156 offset:50176
	ds_read_b128 v[178:181], v156 offset:51200
	ds_read_b128 v[182:185], v156 offset:52224
	ds_read_b128 v[186:189], v156 offset:53248
	ds_read_b128 v[190:193], v156 offset:54272
	ds_read_b128 v[194:197], v156 offset:55296
	ds_read_b128 v[198:201], v156 offset:56320
	s_nop 0
	global_load_lds_dwordx4 v202, s[24:25]
	s_add_i32 m0, s34, 0x2000
	s_nop 0
	global_load_lds_dwordx4 v204, s[24:25]
	s_add_u32 s24, s30, 0x100080
	s_addc_u32 s25, s31, 0
	s_add_i32 s30, s55, s33
	s_mov_b32 m0, s30
	s_nop 0
	global_load_lds_dwordx4 v202, s[24:25]
	s_add_i32 m0, s30, 0x2000
	s_nop 0
	global_load_lds_dwordx4 v204, s[24:25]
	s_mov_b32 m0, s45
	s_nop 0
	global_load_lds_dwordx4 v205, s[28:29]
	s_mov_b32 m0, s46
	s_nop 0
	global_load_lds_dwordx4 v203, s[28:29]
	s_waitcnt vmcnt(8)
	s_waitcnt lgkmcnt(0)
	s_barrier
	s_setprio 1
	s_waitcnt lgkmcnt(0)
	v_mfma_f32_16x16x32_bf16 v[92:95], v[128:131], v[170:173], v[92:95]
	v_mfma_f32_16x16x32_bf16 v[88:91], v[136:139], v[170:173], v[88:91]
	v_mfma_f32_16x16x32_bf16 v[84:87], v[128:131], v[178:181], v[84:87]
	v_mfma_f32_16x16x32_bf16 v[80:83], v[136:139], v[178:181], v[80:83]
	v_mfma_f32_16x16x32_bf16 v[76:79], v[128:131], v[186:189], v[76:79]
	v_mfma_f32_16x16x32_bf16 v[72:75], v[136:139], v[186:189], v[72:75]
	v_mfma_f32_16x16x32_bf16 v[68:71], v[128:131], v[194:197], v[68:71]
	v_mfma_f32_16x16x32_bf16 v[64:67], v[136:139], v[194:197], v[64:67]
	v_mfma_f32_16x16x32_bf16 v[92:95], v[132:135], v[174:177], v[92:95]
	v_mfma_f32_16x16x32_bf16 v[88:91], v[140:143], v[174:177], v[88:91]
	v_mfma_f32_16x16x32_bf16 v[84:87], v[132:135], v[182:185], v[84:87]
	v_mfma_f32_16x16x32_bf16 v[80:83], v[140:143], v[182:185], v[80:83]
	v_mfma_f32_16x16x32_bf16 v[76:79], v[132:135], v[190:193], v[76:79]
	v_mfma_f32_16x16x32_bf16 v[72:75], v[140:143], v[190:193], v[72:75]
	v_mfma_f32_16x16x32_bf16 v[68:71], v[132:135], v[198:201], v[68:71]
	v_mfma_f32_16x16x32_bf16 v[64:67], v[140:143], v[198:201], v[64:67]
	s_setprio 0
	s_setprio 1
	v_mfma_f32_16x16x32_bf16 v[28:31], v[144:147], v[170:173], v[28:31]
	v_mfma_f32_16x16x32_bf16 v[24:27], v[162:165], v[170:173], v[24:27]
	v_mfma_f32_16x16x32_bf16 v[20:23], v[144:147], v[178:181], v[20:23]
	v_mfma_f32_16x16x32_bf16 v[16:19], v[162:165], v[178:181], v[16:19]
	v_mfma_f32_16x16x32_bf16 v[12:15], v[144:147], v[186:189], v[12:15]
	v_mfma_f32_16x16x32_bf16 v[8:11], v[162:165], v[186:189], v[8:11]
	v_mfma_f32_16x16x32_bf16 v[4:7], v[144:147], v[194:197], v[4:7]
	v_mfma_f32_16x16x32_bf16 v[0:3], v[162:165], v[194:197], v[0:3]
	v_mfma_f32_16x16x32_bf16 v[28:31], v[158:161], v[174:177], v[28:31]
	v_mfma_f32_16x16x32_bf16 v[24:27], v[166:169], v[174:177], v[24:27]
	v_mfma_f32_16x16x32_bf16 v[20:23], v[158:161], v[182:185], v[20:23]
	v_mfma_f32_16x16x32_bf16 v[16:19], v[166:169], v[182:185], v[16:19]
	s_add_i32 s53, s53, 2
	s_add_u32 s51, s51, 0x100
	s_addc_u32 s52, s52, 0
	s_cmp_gt_u32 s53, 61
	s_mov_b64 s[24:25], s[26:27]
	v_mfma_f32_16x16x32_bf16 v[12:15], v[158:161], v[190:193], v[12:15]
	v_mfma_f32_16x16x32_bf16 v[8:11], v[166:169], v[190:193], v[8:11]
	v_mfma_f32_16x16x32_bf16 v[4:7], v[158:161], v[198:201], v[4:7]
	v_mfma_f32_16x16x32_bf16 v[0:3], v[166:169], v[198:201], v[0:3]
	s_setprio 0
	s_barrier
	s_cbranch_scc0 .LBB13_2163
	s_and_b64 vcc, exec, s[8:9]
	s_cbranch_vccz .LBB13_2166
	s_barrier
